# nt (non-temporal) hint on the read-once streaming loads of P2 (K/V rows, conv rows), P3 scan and P4 (states, q/k/v rows, gates); on top of v8
# speedup vs baseline: 1.0098x; 1.0098x over previous
; #define LAS __attribute__((address_space(3)))
; __device__ __forceinline__ unsigned pk2(float lo, float hi) { return pg8::cvt_pk_bf16(lo, hi); }
; __device__ __forceinline__ float bfe(const u32x4& w, int e) { const unsigned x = w[e >> 1]; return (e & 1) ? bfhi(x) : bflo(x); }
; __device__ __forceinline__ float fexp2(float x) { return __builtin_amdgcn_exp2f(x); }
; __device__ __forceinline__ float log_sigmoid(float x) { return -log1pf(expf(-x)); }
; __device__ __forceinline__ void kv_unit(LAS unsigned char* lds, int u, const bf16* PROJ, const int* pos, const float* dec_f, const float* dec_b, bf16* KVc, int tid, UnitRaw& raw, int next_u) {
;     const int lane = tid & 63, wave = tid >> 6, fr = lane & 15, fq = lane >> 4;
;     const int bh = u >> 6, c = u & 63, h = bh & 3;
;     LAS bf16* KTf = (LAS bf16*)lds; LAS bf16* KTb = (LAS bf16*)(lds + TILE_B); LAS bf16* VT = (LAS bf16*)(lds + 2 * TILE_B);
;     const float lgf2 = log_sigmoid(dec_f[h]) * LOG2E, lgb2 = log_sigmoid(dec_b[h]) * LOG2E;
; #pragma unroll
;     for (int ii = 0; ii < 2; ++ii) { const int it = tid + 512 * ii, dc = it & 7, j = it >> 3;
;         const u32x4 w1 = raw.k1[ii], w2 = raw.k2[ii];
;         const float p = raw.p[ii];
;         const float zf = fexp2(lgf2 * (float)(127 - j)) * 0.08838834764831845f, zb = fexp2(lgb2 * (float)j) * 0.08838834764831845f;
;         const int jsw = (((j >> 3) ^ (dc & 7)) << 3) | (j & 7);
; #pragma unroll
;         for (int e = 0; e < 8; ++e) { const int i = dc * 8 + e; const float inv = fexp2(-(float)i * 0.20762050593046015f);
;             float sn, cs; fast_sincos(p * inv, sn, cs);
;             const float k1 = bfe(w1, e), k2 = bfe(w2, e), r1 = k1 * cs - k2 * sn, r2 = k2 * cs + k1 * sn;
;             const unsigned pf = pk2(r1 * zf, r2 * zf), pb = pk2(r1 * zb, r2 * zb);
;             KTf[i * LDT + jsw] = (bf16)(pf & 0xffffu); KTf[(i + 64) * LDT + jsw] = (bf16)(pf >> 16);
;             KTb[i * LDT + jsw] = (bf16)(pb & 0xffffu); KTb[(i + 64) * LDT + jsw] = (bf16)(pb >> 16); }
; __global__ void __launch_bounds__(512, 2) fwd_mega(Args a) {
;     ...
;         { UnitRaw raw; int u = bid; if (u < 512) raw_load<false>(raw, u, PROJ, pos, tid);
;           for (; u < 512; u += G) kv_unit(lds, u, PROJ, pos, a.in[5], a.in[6], KVC, tid, raw, (u + G < 512) ? u + G : -1); }
.LBB0_213:
	s_cmp_lt_i32 s86, 3
	s_cselect_b64 s[4:5], -1, 0
	s_add_u32 s70, s84, 0x4800000
	s_addc_u32 s71, s85, 0
	s_add_u32 s8, s84, 0x6800000
	s_addc_u32 s9, s85, 0
	v_writelane_b32 v255, s8, 26
	s_and_b64 s[0:1], s[4:5], s[0:1]
	s_andn2_b64 vcc, exec, s[0:1]
	v_writelane_b32 v255, s9, 27
	s_cbranch_vccnz .LBB0_225
	s_cmpk_gt_i32 s2, 0x1ff
	s_cbranch_scc1 .LBB0_225
	v_and_b32_e32 v0, 7, v128
	v_lshlrev_b32_e32 v1, 3, v0
	v_cvt_f32_ubyte0_e32 v2, v1
	v_lshrrev_b32_e32 v34, 3, v128
	v_lshrrev_b32_e32 v75, 6, v128
	v_mul_f32_e32 v2, 0xbe549a78, v2
	v_xor_b32_e32 v3, 0x7f, v34
	v_exp_f32_e32 v35, v2
	v_bfe_u32 v2, v128, 3, 3
	v_cvt_f32_ubyte0_e32 v41, v3
	v_bitop3_b32 v3, v75, v128, 7 bitop3:0x78
	v_lshl_or_b32 v3, v3, 3, v2
	s_movk_i32 s4, 0x440
	v_mad_u32_u24 v4, v0, s4, v3
	v_lshl_add_u32 v55, v4, 1, 0
	v_or_b32_e32 v4, 1, v1
	v_cvt_f32_ubyte0_e32 v5, v4
	v_mul_f32_e32 v5, 0xbe549a78, v5
	s_movk_i32 s8, 0x88
	v_exp_f32_e32 v56, v5
	v_mad_u32_u24 v5, v4, s8, v3
	v_lshl_add_u32 v57, v5, 1, 0
	v_or_b32_e32 v5, 2, v1
	v_cvt_f32_ubyte0_e32 v5, v5
	v_mul_f32_e32 v5, 0xbe549a78, v5
	v_exp_f32_e32 v58, v5
	v_mad_u32_u24 v5, v4, s8, s8
	v_add_u32_e32 v6, v5, v3
	v_lshl_add_u32 v59, v6, 1, 0
	v_or_b32_e32 v6, 3, v1
	v_cvt_f32_ubyte0_e32 v6, v6
	v_mul_f32_e32 v6, 0xbe549a78, v6
	v_exp_f32_e32 v60, v6
	v_mov_b32_e32 v6, 0x110
	v_mad_u32_u24 v6, v4, s8, v6
	v_add_u32_e32 v7, v6, v3
	v_lshl_add_u32 v61, v7, 1, 0
	v_or_b32_e32 v7, 4, v1
	v_cvt_f32_ubyte0_e32 v7, v7
	v_mul_f32_e32 v7, 0xbe549a78, v7
	v_exp_f32_e32 v62, v7
	v_mov_b32_e32 v7, 0x198
	v_mad_u32_u24 v7, v4, s8, v7
	v_add_u32_e32 v8, v7, v3
	v_lshl_add_u32 v63, v8, 1, 0
	v_or_b32_e32 v8, 5, v1
	v_cvt_f32_ubyte0_e32 v8, v8
	v_mul_f32_e32 v8, 0xbe549a78, v8
	v_exp_f32_e32 v64, v8
	v_mov_b32_e32 v8, 0x220
	v_mad_u32_u24 v8, v4, s8, v8
	v_add_u32_e32 v9, v8, v3
	v_lshl_add_u32 v65, v9, 1, 0
	v_or_b32_e32 v9, 6, v1
	v_or_b32_e32 v1, 7, v1
	v_cvt_f32_ubyte0_e32 v9, v9
	v_cvt_f32_ubyte0_e32 v1, v1
	v_mul_f32_e32 v9, 0xbe549a78, v9
	v_mul_f32_e32 v1, 0xbe549a78, v1
	v_exp_f32_e32 v66, v9
	v_mov_b32_e32 v9, 0x2a8
	v_exp_f32_e32 v68, v1
	v_mov_b32_e32 v1, 0x330
	v_mad_u32_u24 v9, v4, s8, v9
	v_mad_u32_u24 v1, v4, s8, v1
	v_add_u32_e32 v10, v9, v3
	v_add_u32_e32 v3, v1, v3
	v_lshl_add_u32 v69, v3, 1, 0
	v_add_u32_e32 v3, 0x200, v128
	v_lshrrev_b32_e32 v36, 3, v3
	v_lshl_add_u32 v67, v10, 1, 0
	v_sub_u32_e32 v10, 0x7f, v36
	v_cvt_f32_i32_e32 v70, v10
	v_lshrrev_b32_e32 v10, 6, v3
	v_bitop3_b32 v10, v10, v128, 7 bitop3:0x78
	v_lshl_or_b32 v2, v10, 3, v2
	v_mad_u32_u24 v4, v4, s8, v2
	v_lshl_add_u32 v73, v4, 1, 0
	v_add_u32_e32 v4, v2, v5
	v_lshl_add_u32 v74, v4, 1, 0
	v_add_u32_e32 v4, v2, v6
	v_lshl_add_u32 v77, v4, 1, 0
	v_add_u32_e32 v4, v2, v7
	v_add_u32_e32 v1, v2, v1
	v_mad_u32_u24 v10, v0, s4, v2
	v_lshl_add_u32 v78, v4, 1, 0
	v_add_u32_e32 v4, v2, v8
	v_lshl_add_u32 v81, v1, 1, 0
	v_lshlrev_b32_e32 v76, 3, v128
	v_lshrrev_b32_e32 v1, 7, v128
	s_add_i32 s4, 0, 0x11000
	s_movk_i32 s3, 0x110
	v_lshl_add_u32 v79, v4, 1, 0
	v_add_u32_e32 v4, v2, v9
	v_and_b32_e32 v48, 0x78, v76
	v_mov_b32_e32 v33, s4
	v_and_b32_e32 v5, 14, v34
	v_bitop3_b32 v0, v1, v0, 8 bitop3:0x36
	v_lshl_add_u32 v80, v4, 1, 0
	v_mad_u32_u24 v4, v48, s3, v33
	v_lshl_or_b32 v0, v0, 4, v5
	v_bitop3_b32 v2, v1, v128, 7 bitop3:0x78
	v_add_u32_e32 v84, v4, v0
	v_add_u32_e32 v0, 0x600, v128
	v_lshl_or_b32 v2, v2, 4, v5
	v_lshrrev_b32_e32 v1, 7, v0
	s_ashr_i32 s8, s2, 8
	v_add_u32_e32 v82, v4, v2
	v_lshrrev_b32_e32 v2, 7, v3
	v_bitop3_b32 v1, v1, v128, 7 bitop3:0x78
	s_ashr_i32 s9, s8, 31
	s_lshl_b32 s4, s2, 7
	v_bitop3_b32 v2, v2, v128, 7 bitop3:0x78
	v_lshl_or_b32 v1, v1, 4, v5
	v_mov_b32_e32 v39, 0
	s_lshl_b64 s[8:9], s[8:9], 13
	s_and_b32 s4, s4, 0x1f80
	v_lshl_or_b32 v2, v2, 4, v5
	v_add_u32_e32 v85, v4, v1
	v_lshlrev_b32_e32 v1, 4, v128
	v_lshrrev_b32_e32 v44, 4, v0
	v_mov_b32_e32 v45, v39
	s_or_b32 s8, s8, s4
	v_add_u32_e32 v83, v4, v2
	v_and_b32_e32 v38, 0x70, v1
	v_lshrrev_b32_e32 v40, 4, v3
	v_lshl_add_u64 v[0:1], s[8:9], 0, v[44:45]
	s_movk_i32 s14, 0x1800
	v_mov_b64_e32 v[2:3], s[6:7]
	v_mad_u64_u32 v[4:5], s[10:11], v0, s14, v[2:3]
	s_lshl_b32 s4, s2, 2
	v_lshrrev_b32_e32 v32, 4, v128
	s_mov_b32 s5, 0
	v_mad_i32_i24 v5, v1, s14, v5
	s_and_b32 s4, s4, 0x300
	v_or_b32_e32 v42, 64, v32
	v_lshl_add_u64 v[0:1], v[4:5], 0, s[4:5]
	v_lshlrev_b32_e32 v4, 1, v48
	v_mov_b32_e32 v5, v39
	v_lshl_add_u64 v[28:29], v[0:1], 0, v[4:5]
	v_or_b32_e32 v0, s8, v42
	v_mad_u64_u32 v[0:1], s[10:11], v0, s14, v[2:3]
; template <bool WITHQ> __device__ __forceinline__ void raw_load(UnitRaw& r, int u, const bf16* PROJ, const int* pos, int tid) {
;     const int bh = u >> 6, c = u & 63, b = bh >> 2, h = bh & 3; const size_t row0 = (size_t)b * SEQ + (size_t)c * 128;
; #pragma unroll
;     for (int i = 0; i < 2; ++i) { const int it = tid + 512 * i, dc = it & 7, j = it >> 3; const bf16* qr = PROJ + (row0 + j) * INC + h * 128 + dc * 8; const bf16* kr = qr + 512;
;         if (WITHQ) { r.a1[i] = *(const u32x4*)qr; r.a2[i] = *(const u32x4*)(qr + 64); }
;         r.k1[i] = *(const u32x4*)kr; r.k2[i] = *(const u32x4*)(kr + 64); r.p[i] = (float)pos[row0 + j]; }
; #pragma unroll
;     for (int i = 0; i < 4; ++i) { const int it = tid + 512 * i, ec = it & 15, j = it >> 4; r.v[i] = *(const u32x4*)(PROJ + (row0 + j) * INC + 1024 + h * 128 + ec * 8); }
; __global__ void __launch_bounds__(512, 2) fwd_mega(Args a) {
;     ...
;         { UnitRaw raw; int u = bid; if (u < 512) raw_load<false>(raw, u, PROJ, pos, tid);
	v_mov_b32_e32 v87, 0x1800
	v_mad_i32_i24 v1, s9, v87, v1
	v_lshl_add_u64 v[0:1], v[0:1], 0, s[4:5]
	v_lshl_add_u64 v[24:25], v[0:1], 0, v[4:5]
	v_or_b32_e32 v0, s8, v40
	v_mad_u64_u32 v[0:1], s[10:11], v0, s14, v[2:3]
	v_mad_i32_i24 v1, s9, v87, v1
	v_mov_b32_e32 v37, v39
	v_lshl_add_u64 v[0:1], v[0:1], 0, s[4:5]
	v_lshl_add_u64 v[20:21], v[0:1], 0, v[4:5]
	v_lshl_add_u64 v[0:1], s[8:9], 0, v[36:37]
	v_or_b32_e32 v8, s8, v34
	v_mov_b32_e32 v9, s9
	v_lshl_add_u32 v72, v10, 1, 0
	v_lshl_add_u64 v[6:7], v[0:1], 2, s[12:13]
	v_lshl_add_u64 v[10:11], v[8:9], 2, s[12:13]
	global_load_dword v49, v[10:11], off
	global_load_dword v51, v[6:7], off
	v_or_b32_e32 v6, s8, v32
	v_mad_u64_u32 v[2:3], s[10:11], v6, s14, v[2:3]
	v_mad_i32_i24 v3, s9, v87, v3
	s_add_u32 s10, s6, s4
	v_lshl_add_u64 v[2:3], v[2:3], 0, s[4:5]
	s_addc_u32 s11, s7, 0
	v_lshl_add_u64 v[16:17], v[2:3], 0, v[4:5]
	v_lshl_add_u64 v[2:3], s[10:11], 0, v[38:39]
	v_mad_u64_u32 v[12:13], s[10:11], v0, s14, v[2:3]
	v_mad_u64_u32 v[4:5], s[10:11], v8, s14, v[2:3]
	v_mad_i32_i24 v13, v1, s14, v13
	v_mad_i32_i24 v5, s9, v87, v5
	global_load_dwordx4 v[0:3], v[4:5], off offset:1024 nt
	s_nop 0
	global_load_dwordx4 v[4:7], v[4:5], off offset:1152 nt
	s_nop 0
	global_load_dwordx4 v[8:11], v[12:13], off offset:1024 nt
	s_nop 0
	global_load_dwordx4 v[12:15], v[12:13], off offset:1152 nt
	s_nop 0
	global_load_dwordx4 v[16:19], v[16:17], off offset:2048 nt
	s_nop 0
	global_load_dwordx4 v[20:23], v[20:21], off offset:2048 nt
	s_nop 0
	global_load_dwordx4 v[24:27], v[24:25], off offset:2048 nt
	s_nop 0
	global_load_dwordx4 v[28:31], v[28:29], off offset:2048 nt
	v_lshl_add_u64 v[46:47], s[6:7], 0, v[38:39]
	v_and_b32_e32 v38, 15, v128
	v_lshl_or_b32 v52, v75, 4, v38
	v_mad_u32_u24 v52, v52, s3, v33
	v_lshrrev_b32_e32 v33, 5, v128
	v_bfe_u32 v50, v128, 4, 2
	v_bfe_u32 v53, v128, 3, 1
	v_and_b32_e32 v33, 6, v33
	v_bitop3_b32 v54, v33, v50, v53 bitop3:0x36
	v_mul_u32_u24_e32 v86, 0x88, v38
	v_lshlrev_b32_e32 v105, 4, v54
	v_bitop3_b32 v54, v53, v32, 3 bitop3:0x78
	v_lshl_add_u32 v86, v86, 1, 0
	v_lshl_add_u32 v88, v54, 4, v86
	v_bitop3_b32 v54, v53, v50, 2 bitop3:0x36
	v_lshl_add_u32 v89, v54, 4, v86
	v_bitop3_b32 v54, v53, v50, 4 bitop3:0x36
	v_lshl_add_u32 v90, v54, 4, v86
	v_bitop3_b32 v54, v53, v50, 6 bitop3:0x36
	v_lshl_add_u32 v91, v54, 4, v86
	v_or_b32_e32 v54, 4, v50
	v_bitop3_b32 v92, v33, v54, v53 bitop3:0x36
	v_bitop3_b32 v93, v53, v54, 2 bitop3:0x36
	v_bitop3_b32 v54, v53, v54, 6 bitop3:0x36
	v_lshl_add_u32 v95, v54, 4, v86
	v_or_b32_e32 v54, 8, v50
	v_bitop3_b32 v96, v33, v54, v53 bitop3:0x36
	v_bitop3_b32 v97, v53, v54, 2 bitop3:0x36
	v_bitop3_b32 v98, v53, v54, 4 bitop3:0x36
	v_bitop3_b32 v54, v53, v54, 6 bitop3:0x36
	v_lshl_add_u32 v99, v54, 4, v86
	v_or_b32_e32 v54, 12, v50
	v_bitop3_b32 v33, v33, v54, v53 bitop3:0x36
	v_lshlrev_b32_e32 v108, 4, v33
	v_bitop3_b32 v33, v50, v53, 12 bitop3:0x36
	v_lshl_add_u32 v100, v33, 4, v86
	v_bitop3_b32 v33, v53, v54, 2 bitop3:0x36
	v_lshl_add_u32 v101, v33, 4, v86
	v_bitop3_b32 v33, v53, v54, 4 bitop3:0x36
	v_lshl_add_u32 v102, v33, 4, v86
	v_bitop3_b32 v33, v53, v54, 6 bitop3:0x36
	v_lshlrev_b32_e32 v106, 4, v92
	v_bitop3_b32 v92, v50, v53, 4 bitop3:0x36
	v_bitop3_b32 v94, v53, v50, 4 bitop3:0x14
	v_lshlrev_b32_e32 v107, 4, v96
	v_bitop3_b32 v96, v50, v53, 8 bitop3:0x36
	v_lshl_add_u32 v103, v33, 4, v86
	v_lshl_add_u32 v92, v92, 4, v86
	v_lshl_add_u32 v93, v93, 4, v86
	v_lshl_add_u32 v94, v94, 4, v86
	v_lshl_add_u32 v96, v96, 4, v86
	v_lshl_add_u32 v97, v97, 4, v86
	v_lshl_add_u32 v98, v98, 4, v86
	v_lshlrev_b32_e32 v86, 11, v75
	v_lshl_or_b32 v38, v38, 7, v86
	v_lshlrev_b32_e32 v50, 2, v50
	v_readlane_b32 s8, v255, 8
	v_cvt_f32_ubyte0_e32 v43, v34
	v_cvt_f32_ubyte0_e32 v71, v36
	s_lshl_b32 s15, s2, 14
	s_lshl_b32 s24, s8, 14
	s_mov_b32 s25, 0xbfb8aa3b
	s_waitcnt vmcnt(0)
	v_cvt_f32_i32_e32 v54, v49
	v_cvt_f32_i32_e32 v33, v51
	s_mov_b32 s26, 0x42ce8ed0
	s_mov_b32 s27, 0xc2b17218
	s_mov_b32 s28, 0x7f800000
	s_mov_b32 s29, 0x3f2aaaab
	v_mov_b32_e32 v104, 0x3ecc95a3
	s_mov_b32 s30, 0x3f317218
	s_mov_b32 s31, 0x33800000
	v_lshlrev_b32_e32 v48, 1, v48
	v_add_u32_e32 v105, v52, v105
	v_add_u32_e32 v106, v52, v106
	v_add_u32_e32 v107, v52, v107
	v_add_u32_e32 v108, v52, v108
	v_lshlrev_b32_e32 v38, 1, v38
	v_lshlrev_b32_e32 v50, 1, v50
	s_mov_b32 s33, 0x1000000
	v_mov_b32_e32 v109, 0x7f800000
	v_mov_b32_e32 v52, 0x3f317218
	s_mov_b32 s34, s2
	v_readlane_b32 s9, v255, 9
	s_branch .LBB0_217

; #define LAS __attribute__((address_space(3)))
; __device__ __forceinline__ float log_sigmoid(float x) { return -log1pf(expf(-x)); }
; __device__ __forceinline__ void kv_unit(LAS unsigned char* lds, int u, const bf16* PROJ, const int* pos, const float* dec_f, const float* dec_b, bf16* KVc, int tid, UnitRaw& raw, int next_u) {
;     const int lane = tid & 63, wave = tid >> 6, fr = lane & 15, fq = lane >> 4;
;     const int bh = u >> 6, c = u & 63, h = bh & 3;
;     LAS bf16* KTf = (LAS bf16*)lds; LAS bf16* KTb = (LAS bf16*)(lds + TILE_B); LAS bf16* VT = (LAS bf16*)(lds + 2 * TILE_B);
;     const float lgf2 = log_sigmoid(dec_f[h]) * LOG2E, lgb2 = log_sigmoid(dec_b[h]) * LOG2E;
.LBB0_217:
	v_readlane_b32 s8, v255, 8
	s_mov_b32 s4, s34
	s_add_i32 s34, s34, s8
	v_readlane_b32 s9, v255, 9
	s_cmpk_gt_i32 s34, 0x1ff
	s_cselect_b64 s[8:9], -1, 0
	s_cmpk_lt_i32 s34, 0x200
	s_cselect_b32 s3, s34, -1
	s_ashr_i32 s10, s4, 6
	s_lshl_b32 s4, s10, 2
	s_and_b32 s4, s4, 12
	v_mov_b32_e32 v49, s4
	global_load_dword v51, v49, s[18:19]
	s_nop 0
	global_load_dword v49, v49, s[20:21]
	s_waitcnt vmcnt(1)
	v_mul_f32_e32 v53, 0xbfb8aa3b, v51
	s_waitcnt vmcnt(0)
	v_mul_f32_e32 v110, 0xbfb8aa3b, v49
	v_fma_f32 v111, v51, s25, -v53
	v_rndne_f32_e32 v112, v53
	v_fma_f32 v113, v49, s25, -v110
	v_rndne_f32_e32 v114, v110
	v_fmac_f32_e32 v111, 0xb2a5705f, v51
	v_sub_f32_e32 v53, v53, v112
	v_fmac_f32_e32 v113, 0xb2a5705f, v49
	v_sub_f32_e32 v110, v110, v114
	v_add_f32_e32 v53, v53, v111
	v_cvt_i32_f32_e32 v112, v112
	v_add_f32_e32 v110, v110, v113
	v_exp_f32_e32 v53, v53
	v_cvt_i32_f32_e32 v114, v114
	v_exp_f32_e32 v110, v110
	v_cmp_nlt_f32_e32 vcc, s26, v51
	v_ldexp_f32 v53, v53, v112
	v_ldexp_f32 v110, v110, v114
	v_cndmask_b32_e32 v53, 0, v53, vcc
	v_cmp_nlt_f32_e32 vcc, s26, v49
	s_nop 1
	v_cndmask_b32_e32 v110, 0, v110, vcc
	v_cmp_ngt_f32_e32 vcc, s27, v51
	s_nop 1
	v_cndmask_b32_e32 v51, v109, v53, vcc
	v_cmp_ngt_f32_e32 vcc, s27, v49
	v_add_f32_e32 v53, 1.0, v51
	v_frexp_mant_f32_e32 v116, v53
	v_cndmask_b32_e32 v49, v109, v110, vcc
	v_cvt_f64_f32_e32 v[110:111], v53
	v_add_f32_e32 v114, 1.0, v49
	v_add_f32_e32 v115, -1.0, v53
	v_frexp_exp_i32_f64_e32 v110, v[110:111]
	v_cmp_gt_f32_e32 vcc, s29, v116
	v_add_f32_e32 v117, -1.0, v114
	v_frexp_mant_f32_e32 v118, v114
	v_cvt_f64_f32_e32 v[112:113], v114
	v_sub_f32_e32 v119, v115, v53
	v_subbrev_co_u32_e32 v110, vcc, 0, v110, vcc
	v_sub_f32_e32 v115, v51, v115
	v_sub_f32_e32 v111, v117, v114
	v_frexp_exp_i32_f64_e32 v112, v[112:113]
	v_add_f32_e32 v113, 1.0, v119
	v_cmp_gt_f32_e32 vcc, s29, v118
	v_sub_f32_e32 v117, v49, v117
	v_add_f32_e32 v111, 1.0, v111
	v_subbrev_co_u32_e32 v126, vcc, 0, v112, vcc
	v_add_f32_e32 v112, v115, v113
	v_sub_u32_e32 v113, 0, v110
	v_add_f32_e32 v111, v117, v111
	v_sub_u32_e32 v115, 0, v126
	v_ldexp_f32 v53, v53, v113
	v_ldexp_f32 v127, v114, v115
	v_ldexp_f32 v129, v111, v115
	v_add_f32_e32 v111, -1.0, v53
	v_add_f32_e32 v114, 1.0, v53
	v_ldexp_f32 v112, v112, v113
	v_add_f32_e32 v113, 1.0, v111
	v_add_f32_e32 v115, -1.0, v114
	v_sub_f32_e32 v113, v53, v113
	v_sub_f32_e32 v53, v53, v115
	v_add_f32_e32 v53, v112, v53
	v_add_f32_e32 v118, v114, v53
	v_rcp_f32_e32 v119, v118
	v_add_f32_e32 v115, v112, v113
	v_add_f32_e32 v113, v111, v115
	v_sub_f32_e32 v112, v114, v118
	v_mul_f32_e32 v120, v113, v119
	v_mul_f32_e32 v114, v118, v120
	v_add_f32_e32 v53, v53, v112
	v_fma_f32 v116, v120, v118, -v114
	v_fmac_f32_e32 v116, v120, v53
	v_sub_f32_e32 v111, v111, v113
	v_add_f32_e32 v112, v114, v116
	v_add_f32_e32 v111, v115, v111
	v_sub_f32_e32 v115, v113, v112
	v_mov_b32_e32 v117, v112
	v_pk_add_f32 v[112:113], v[112:113], v[114:115] neg_lo:[0,1] neg_hi:[0,1]
	v_cvt_f32_i32_e32 v110, v110
	v_pk_add_f32 v[112:113], v[112:113], v[116:117] neg_lo:[0,1] neg_hi:[0,1]
	v_add_f32_e32 v130, -1.0, v127
	v_add_f32_e32 v111, v111, v113
	v_add_f32_e32 v111, v112, v111
	v_add_f32_e32 v113, v115, v111
	v_mul_f32_e32 v112, v119, v113
	v_mul_f32_e32 v114, v118, v112
	v_sub_f32_e32 v115, v115, v113
	v_add_f32_e32 v121, v120, v112
	v_fma_f32 v116, v112, v118, -v114
	v_add_f32_e32 v111, v111, v115
	v_sub_f32_e32 v115, v121, v120
	v_fmac_f32_e32 v116, v112, v53
	v_sub_f32_e32 v53, v112, v115
	v_add_f32_e32 v112, v114, v116
	v_sub_f32_e32 v115, v113, v112
	v_mov_b32_e32 v117, v112
	v_pk_add_f32 v[112:113], v[112:113], v[114:115] neg_lo:[0,1] neg_hi:[0,1]
	v_cmp_neq_f32_e32 vcc, s28, v51
	v_pk_add_f32 v[112:113], v[112:113], v[116:117] neg_lo:[0,1] neg_hi:[0,1]
	v_add_f32_e32 v131, 1.0, v130
	v_add_f32_e32 v111, v111, v113
	v_add_f32_e32 v111, v112, v111
	v_add_f32_e32 v111, v115, v111
	v_mul_f32_e32 v111, v119, v111
	v_add_f32_e32 v53, v53, v111
	v_add_f32_e32 v111, v121, v53
	v_mul_f32_e32 v112, v111, v111
	v_sub_f32_e32 v114, v111, v121
	v_fmamk_f32 v115, v112, 0x3e9b6dac, v104
	v_ldexp_f32 v113, v111, 1
	v_sub_f32_e32 v114, v53, v114
	v_mul_f32_e32 v111, v111, v112
	v_fmaak_f32 v53, v112, v115, 0x3f2aaada
	v_ldexp_f32 v117, v114, 1
	v_pk_mul_f32 v[114:115], v[110:111], v[52:53]
	s_nop 0
	v_fma_f32 v112, v110, s30, -v114
	v_fmac_f32_e32 v112, 0xb102e308, v110
	v_pk_add_f32 v[110:111], v[114:115], v[112:113]
	v_mov_b32_e32 v116, v114
	v_sub_f32_e32 v53, v111, v113
	v_sub_f32_e32 v53, v115, v53
	v_add_f32_e32 v117, v117, v53
	v_pk_add_f32 v[118:119], v[110:111], v[114:115] neg_lo:[0,1] neg_hi:[0,1]
	v_pk_add_f32 v[122:123], v[110:111], v[116:117]
	v_mov_b32_e32 v113, v110
	v_mov_b32_e32 v119, v123
	v_pk_add_f32 v[124:125], v[112:113], v[118:119] neg_lo:[0,1] neg_hi:[0,1]
	v_pk_add_f32 v[112:113], v[112:113], v[118:119]
	v_mov_b32_e32 v114, v111
	v_mov_b32_e32 v121, v110
	v_pk_add_f32 v[110:111], v[112:113], v[110:111] op_sel:[1,0] op_sel_hi:[0,1] neg_lo:[0,1] neg_hi:[0,1]
	v_mov_b32_e32 v120, v117
	v_mov_b32_e32 v116, v123
	v_mov_b32_e32 v117, v113
	v_mov_b32_e32 v115, v110
	v_pk_add_f32 v[118:119], v[122:123], v[110:111] op_sel_hi:[1,0] neg_lo:[0,1] neg_hi:[0,1]
	v_pk_add_f32 v[110:111], v[116:117], v[114:115] neg_lo:[0,1] neg_hi:[0,1]
	v_mov_b32_e32 v118, v124
	v_pk_add_f32 v[110:111], v[120:121], v[110:111] neg_lo:[0,1] neg_hi:[0,1]
	v_mov_b32_e32 v125, v113
	v_pk_add_f32 v[114:115], v[118:119], v[110:111]
	s_nop 0
	v_pk_add_f32 v[116:117], v[114:115], v[114:115] op_sel:[0,1] op_sel_hi:[1,0]
	s_nop 0
	v_pk_add_f32 v[112:113], v[112:113], v[116:117] op_sel:[1,0] op_sel_hi:[0,1]
; __device__ __forceinline__ unsigned pk2(float lo, float hi) { return pg8::cvt_pk_bf16(lo, hi); }
; __device__ __forceinline__ float bfe(const u32x4& w, int e) { const unsigned x = w[e >> 1]; return (e & 1) ? bfhi(x) : bflo(x); }
; __device__ __forceinline__ float fexp2(float x) { return __builtin_amdgcn_exp2f(x); }
; __device__ __forceinline__ float log_sigmoid(float x) { return -log1pf(expf(-x)); }
; __device__ __forceinline__ void kv_unit(LAS unsigned char* lds, int u, const bf16* PROJ, const int* pos, const float* dec_f, const float* dec_b, bf16* KVc, int tid, UnitRaw& raw, int next_u) {
;     ...
;     const float lgf2 = log_sigmoid(dec_f[h]) * LOG2E, lgb2 = log_sigmoid(dec_b[h]) * LOG2E;
; #pragma unroll
;     for (int ii = 0; ii < 2; ++ii) { const int it = tid + 512 * ii, dc = it & 7, j = it >> 3;
;         const u32x4 w1 = raw.k1[ii], w2 = raw.k2[ii];
;         const float p = raw.p[ii];
;         const float zf = fexp2(lgf2 * (float)(127 - j)) * 0.08838834764831845f, zb = fexp2(lgb2 * (float)j) * 0.08838834764831845f;
;         const int jsw = (((j >> 3) ^ (dc & 7)) << 3) | (j & 7);
; #pragma unroll
;         for (int e = 0; e < 8; ++e) { const int i = dc * 8 + e; const float inv = fexp2(-(float)i * 0.20762050593046015f);
;             float sn, cs; fast_sincos(p * inv, sn, cs);
;             const float k1 = bfe(w1, e), k2 = bfe(w2, e), r1 = k1 * cs - k2 * sn, r2 = k2 * cs + k1 * sn;
;             const unsigned pf = pk2(r1 * zf, r2 * zf), pb = pk2(r1 * zb, r2 * zb);
;             KTf[i * LDT + jsw] = (bf16)(pf & 0xffffu); KTf[(i + 64) * LDT + jsw] = (bf16)(pf >> 16);
;             KTb[i * LDT + jsw] = (bf16)(pb & 0xffffu); KTb[(i + 64) * LDT + jsw] = (bf16)(pb >> 16); }
	v_mov_b32_e32 v115, v112
	v_mov_b32_e32 v111, v116
	v_pk_add_f32 v[116:117], v[114:115], v[124:125] neg_lo:[0,1] neg_hi:[0,1]
	s_nop 0
	v_sub_f32_e32 v53, v114, v116
	v_pk_add_f32 v[110:111], v[110:111], v[116:117] neg_lo:[0,1] neg_hi:[0,1]
	v_sub_f32_e32 v53, v124, v53
	v_add_f32_e32 v53, v110, v53
	v_add_f32_e32 v110, 1.0, v127
	v_add_f32_e32 v53, v53, v111
	v_add_f32_e32 v111, -1.0, v110
	v_sub_f32_e32 v111, v127, v111
	v_add_f32_e32 v111, v129, v111
	v_add_f32_e32 v53, v112, v53
	v_add_f32_e32 v118, v110, v111
	v_cndmask_b32_e32 v53, v109, v53, vcc
	v_cmp_lt_f32_e64 vcc, |v51|, s31
	v_rcp_f32_e32 v120, v118
	v_sub_f32_e32 v110, v110, v118
	v_cndmask_b32_e32 v51, v53, v51, vcc
	v_sub_f32_e32 v53, v127, v131
	v_add_f32_e32 v53, v129, v53
	v_add_f32_e32 v119, v111, v110
	v_add_f32_e32 v111, v130, v53
	v_mul_f32_e32 v121, v111, v120
	v_mul_f32_e32 v112, v118, v121
	v_fma_f32 v114, v121, v118, -v112
	v_sub_f32_e32 v110, v130, v111
	v_fmac_f32_e32 v114, v121, v119
	v_add_f32_e32 v53, v53, v110
	v_add_f32_e32 v110, v112, v114
	v_sub_f32_e32 v113, v111, v110
	v_pk_add_f32 v[116:117], v[110:111], v[112:113] neg_lo:[0,1] neg_hi:[0,1]
	v_mov_b32_e32 v115, v110
	v_pk_add_f32 v[110:111], v[116:117], v[114:115] neg_lo:[0,1] neg_hi:[0,1]
	v_cmp_neq_f32_e32 vcc, s28, v49
	v_add_f32_e32 v53, v53, v111
	v_add_f32_e32 v53, v110, v53
	v_add_f32_e32 v111, v113, v53
	v_mul_f32_e32 v122, v120, v111
	v_mul_f32_e32 v112, v118, v122
	v_fma_f32 v114, v122, v118, -v112
	v_fmac_f32_e32 v114, v122, v119
	v_sub_f32_e32 v110, v113, v111
	v_add_f32_e32 v53, v53, v110
	v_add_f32_e32 v110, v112, v114
	v_sub_f32_e32 v113, v111, v110
	v_pk_add_f32 v[116:117], v[110:111], v[112:113] neg_lo:[0,1] neg_hi:[0,1]
	v_mov_b32_e32 v115, v110
	v_pk_add_f32 v[110:111], v[116:117], v[114:115] neg_lo:[0,1] neg_hi:[0,1]
	v_mul_f32_e32 v51, 0xbfb8aa3b, v51
	v_add_f32_e32 v53, v53, v111
	v_add_f32_e32 v53, v110, v53
	v_add_f32_e32 v111, v121, v122
	v_add_f32_e32 v53, v113, v53
	v_sub_f32_e32 v110, v111, v121
	v_mul_f32_e32 v53, v120, v53
	v_sub_f32_e32 v110, v122, v110
	v_add_f32_e32 v112, v110, v53
	v_add_f32_e32 v114, v111, v112
	v_cvt_f32_i32_e32 v110, v126
	v_mul_f32_e32 v115, v114, v114
	v_sub_f32_e32 v111, v114, v111
	v_fmamk_f32 v53, v115, 0x3e9b6dac, v104
	v_sub_f32_e32 v111, v112, v111
	v_fmaak_f32 v53, v115, v53, 0x3f2aaada
	v_ldexp_f32 v116, v111, 1
	v_mul_f32_e32 v111, v114, v115
	v_ldexp_f32 v113, v114, 1
	v_pk_mul_f32 v[114:115], v[110:111], v[52:53]
	s_nop 0
	v_fma_f32 v112, v110, s30, -v114
	v_fmac_f32_e32 v112, 0xb102e308, v110
	v_pk_add_f32 v[110:111], v[114:115], v[112:113]
	s_nop 0
	v_sub_f32_e32 v53, v111, v113
	v_sub_f32_e32 v53, v115, v53
	v_add_f32_e32 v117, v116, v53
	v_mov_b32_e32 v116, v114
	v_pk_add_f32 v[114:115], v[110:111], v[114:115] neg_lo:[0,1] neg_hi:[0,1]
	v_pk_add_f32 v[118:119], v[110:111], v[116:117]
	v_mov_b32_e32 v113, v110
	v_mov_b32_e32 v115, v119
	v_pk_add_f32 v[120:121], v[112:113], v[114:115] neg_lo:[0,1] neg_hi:[0,1]
	v_pk_add_f32 v[112:113], v[112:113], v[114:115]
	v_mov_b32_e32 v124, v111
	v_pk_add_f32 v[114:115], v[112:113], v[110:111] op_sel:[1,0] op_sel_hi:[0,1] neg_lo:[0,1] neg_hi:[0,1]
	v_pk_add_f32 v[122:123], v[118:119], v[114:115] op_sel_hi:[1,0] neg_lo:[0,1] neg_hi:[0,1]
	v_mov_b32_e32 v118, v119
	v_mov_b32_e32 v119, v113
	v_mov_b32_e32 v125, v114
	v_pk_add_f32 v[114:115], v[118:119], v[124:125] neg_lo:[0,1] neg_hi:[0,1]
	v_mov_b32_e32 v116, v117
	v_mov_b32_e32 v117, v110
	v_pk_add_f32 v[110:111], v[116:117], v[114:115] neg_lo:[0,1] neg_hi:[0,1]
	v_mov_b32_e32 v122, v120
	v_pk_add_f32 v[114:115], v[122:123], v[110:111]
	v_mov_b32_e32 v121, v113
	v_pk_add_f32 v[116:117], v[114:115], v[114:115] op_sel:[0,1] op_sel_hi:[1,0]
	s_nop 0
	v_pk_add_f32 v[112:113], v[112:113], v[116:117] op_sel:[1,0] op_sel_hi:[0,1]
	v_mov_b32_e32 v115, v112
	v_pk_add_f32 v[118:119], v[114:115], v[120:121] neg_lo:[0,1] neg_hi:[0,1]
	v_mov_b32_e32 v111, v116
	v_sub_f32_e32 v53, v114, v118
	v_pk_add_f32 v[110:111], v[110:111], v[118:119] neg_lo:[0,1] neg_hi:[0,1]
	v_sub_f32_e32 v53, v120, v53
	v_add_f32_e32 v53, v110, v53
	v_add_f32_e32 v53, v53, v111
	v_add_f32_e32 v53, v112, v53
	v_cndmask_b32_e32 v53, v109, v53, vcc
	v_cmp_lt_f32_e64 vcc, |v49|, s31
	v_lshlrev_b32_e32 v119, 16, v4
	v_lshlrev_b32_e32 v118, 16, v0
	v_cndmask_b32_e32 v49, v53, v49, vcc
	v_mul_f32_e32 v49, 0xbfb8aa3b, v49
	v_mul_f32_e32 v53, v51, v41
	v_exp_f32_e32 v53, v53
	v_mul_f32_e32 v110, v49, v43
	v_exp_f32_e32 v111, v110
	v_mul_f32_e32 v110, 0x3db504f3, v53
	v_mul_f32_e32 v53, v35, v54
	v_mul_f32_e32 v112, 0x3db504f3, v111
	v_mul_f32_e32 v111, 0.15915494, v53
	v_rndne_f32_e32 v111, v111
	v_fmac_f32_e32 v53, 0xc0c90000, v111
	v_fmac_f32_e32 v53, 0xbafdaa22, v111
	v_mul_f32_e32 v53, 0.15915494, v53
	v_sin_f32_e32 v114, v53
	v_cos_f32_e32 v116, v53
	v_pk_mul_f32 v[114:115], v[114:115], v[118:119] op_sel:[0,1] op_sel_hi:[0,0]
	v_pk_fma_f32 v[120:121], v[116:117], v[118:119], v[114:115] neg_lo:[0,0,1] neg_hi:[0,0,1]
	v_pk_fma_f32 v[114:115], v[116:117], v[118:119], v[114:115] op_sel_hi:[0,1,1]
	v_mov_b32_e32 v121, v115
	v_pk_mul_f32 v[114:115], v[120:121], v[110:111] op_sel_hi:[1,0]
	v_and_b32_e32 v119, 0xffff0000, v4
	v_cvt_pk_bf16_f32 v53, v114, v115
	v_pk_mul_f32 v[114:115], v[120:121], v[112:113] op_sel_hi:[1,0]
	v_and_b32_e32 v118, 0xffff0000, v0
	v_cvt_pk_bf16_f32 v111, v114, v115
	ds_write_b16 v55, v53
	ds_write_b16_d16_hi v55, v53 offset:17408
	ds_write_b16 v55, v111 offset:34816
	ds_write_b16_d16_hi v55, v111 offset:52224
	v_mul_f32_e32 v53, v56, v54
	v_mul_f32_e32 v111, 0.15915494, v53
	v_rndne_f32_e32 v111, v111
	v_fmac_f32_e32 v53, 0xc0c90000, v111
	v_fmac_f32_e32 v53, 0xbafdaa22, v111
; __device__ __forceinline__ unsigned pk2(float lo, float hi) { return pg8::cvt_pk_bf16(lo, hi); }
; __device__ __forceinline__ float bfe(const u32x4& w, int e) { const unsigned x = w[e >> 1]; return (e & 1) ? bfhi(x) : bflo(x); }
; __device__ __forceinline__ float fexp2(float x) { return __builtin_amdgcn_exp2f(x); }
; __device__ __forceinline__ void kv_unit(LAS unsigned char* lds, int u, const bf16* PROJ, const int* pos, const float* dec_f, const float* dec_b, bf16* KVc, int tid, UnitRaw& raw, int next_u) {
;     ...
;         for (int e = 0; e < 8; ++e) { const int i = dc * 8 + e; const float inv = fexp2(-(float)i * 0.20762050593046015f);
;             float sn, cs; fast_sincos(p * inv, sn, cs);
;             const float k1 = bfe(w1, e), k2 = bfe(w2, e), r1 = k1 * cs - k2 * sn, r2 = k2 * cs + k1 * sn;
;             const unsigned pf = pk2(r1 * zf, r2 * zf), pb = pk2(r1 * zb, r2 * zb);
;             KTf[i * LDT + jsw] = (bf16)(pf & 0xffffu); KTf[(i + 64) * LDT + jsw] = (bf16)(pf >> 16);
;             KTb[i * LDT + jsw] = (bf16)(pb & 0xffffu); KTb[(i + 64) * LDT + jsw] = (bf16)(pb >> 16); }
	v_mul_f32_e32 v53, 0.15915494, v53
	v_sin_f32_e32 v114, v53
	v_cos_f32_e32 v116, v53
	v_pk_mul_f32 v[114:115], v[114:115], v[118:119] op_sel:[0,1] op_sel_hi:[0,0]
	v_pk_fma_f32 v[120:121], v[116:117], v[118:119], v[114:115] neg_lo:[0,0,1] neg_hi:[0,0,1]
	v_pk_fma_f32 v[114:115], v[116:117], v[118:119], v[114:115] op_sel_hi:[0,1,1]
	v_mov_b32_e32 v121, v115
	v_pk_mul_f32 v[114:115], v[120:121], v[110:111] op_sel_hi:[1,0]
	v_lshlrev_b32_e32 v119, 16, v5
	v_cvt_pk_bf16_f32 v53, v114, v115
	v_pk_mul_f32 v[114:115], v[120:121], v[112:113] op_sel_hi:[1,0]
	v_lshlrev_b32_e32 v118, 16, v1
	v_cvt_pk_bf16_f32 v111, v114, v115
	ds_write_b16 v57, v53
	ds_write_b16_d16_hi v57, v53 offset:17408
	ds_write_b16 v57, v111 offset:34816
	ds_write_b16_d16_hi v57, v111 offset:52224
	v_mul_f32_e32 v53, v58, v54
	v_mul_f32_e32 v111, 0.15915494, v53
	v_rndne_f32_e32 v111, v111
	v_fmac_f32_e32 v53, 0xc0c90000, v111
	v_fmac_f32_e32 v53, 0xbafdaa22, v111
	v_mul_f32_e32 v53, 0.15915494, v53
	v_sin_f32_e32 v114, v53
	v_cos_f32_e32 v116, v53
	v_pk_mul_f32 v[114:115], v[114:115], v[118:119] op_sel:[0,1] op_sel_hi:[0,0]
	v_pk_fma_f32 v[120:121], v[116:117], v[118:119], v[114:115] neg_lo:[0,0,1] neg_hi:[0,0,1]
	v_pk_fma_f32 v[114:115], v[116:117], v[118:119], v[114:115] op_sel_hi:[0,1,1]
	v_mov_b32_e32 v121, v115
	v_pk_mul_f32 v[114:115], v[120:121], v[110:111] op_sel_hi:[1,0]
	v_and_b32_e32 v119, 0xffff0000, v5
	v_cvt_pk_bf16_f32 v53, v114, v115
	v_pk_mul_f32 v[114:115], v[120:121], v[112:113] op_sel_hi:[1,0]
	v_and_b32_e32 v118, 0xffff0000, v1
	v_cvt_pk_bf16_f32 v111, v114, v115
	ds_write_b16 v59, v53
	ds_write_b16_d16_hi v59, v53 offset:17408
	ds_write_b16 v59, v111 offset:34816
	ds_write_b16_d16_hi v59, v111 offset:52224
	v_mul_f32_e32 v53, v60, v54
	v_mul_f32_e32 v111, 0.15915494, v53
	v_rndne_f32_e32 v111, v111
	v_fmac_f32_e32 v53, 0xc0c90000, v111
	v_fmac_f32_e32 v53, 0xbafdaa22, v111
	v_mul_f32_e32 v53, 0.15915494, v53
	v_sin_f32_e32 v114, v53
	v_cos_f32_e32 v116, v53
	v_pk_mul_f32 v[114:115], v[114:115], v[118:119] op_sel:[0,1] op_sel_hi:[0,0]
	v_pk_fma_f32 v[120:121], v[116:117], v[118:119], v[114:115] neg_lo:[0,0,1] neg_hi:[0,0,1]
	v_pk_fma_f32 v[114:115], v[116:117], v[118:119], v[114:115] op_sel_hi:[0,1,1]
	v_mov_b32_e32 v121, v115
	v_pk_mul_f32 v[114:115], v[120:121], v[110:111] op_sel_hi:[1,0]
	v_lshlrev_b32_e32 v119, 16, v6
	v_cvt_pk_bf16_f32 v53, v114, v115
	v_pk_mul_f32 v[114:115], v[120:121], v[112:113] op_sel_hi:[1,0]
	v_lshlrev_b32_e32 v118, 16, v2
	v_cvt_pk_bf16_f32 v111, v114, v115
	ds_write_b16 v61, v53
	ds_write_b16_d16_hi v61, v53 offset:17408
	ds_write_b16 v61, v111 offset:34816
	ds_write_b16_d16_hi v61, v111 offset:52224
	v_mul_f32_e32 v53, v62, v54
	v_mul_f32_e32 v111, 0.15915494, v53
	v_rndne_f32_e32 v111, v111
	v_fmac_f32_e32 v53, 0xc0c90000, v111
	v_fmac_f32_e32 v53, 0xbafdaa22, v111
	v_mul_f32_e32 v53, 0.15915494, v53
	v_sin_f32_e32 v114, v53
	v_cos_f32_e32 v116, v53
	v_pk_mul_f32 v[114:115], v[114:115], v[118:119] op_sel:[0,1] op_sel_hi:[0,0]
	v_pk_fma_f32 v[120:121], v[116:117], v[118:119], v[114:115] neg_lo:[0,0,1] neg_hi:[0,0,1]
	v_pk_fma_f32 v[114:115], v[116:117], v[118:119], v[114:115] op_sel_hi:[0,1,1]
	v_mov_b32_e32 v121, v115
	v_pk_mul_f32 v[114:115], v[120:121], v[110:111] op_sel_hi:[1,0]
	v_and_b32_e32 v119, 0xffff0000, v6
	v_cvt_pk_bf16_f32 v53, v114, v115
	v_pk_mul_f32 v[114:115], v[120:121], v[112:113] op_sel_hi:[1,0]
	v_and_b32_e32 v118, 0xffff0000, v2
	v_cvt_pk_bf16_f32 v111, v114, v115
	ds_write_b16 v63, v53
	ds_write_b16_d16_hi v63, v53 offset:17408
	ds_write_b16 v63, v111 offset:34816
	ds_write_b16_d16_hi v63, v111 offset:52224
	v_mul_f32_e32 v53, v64, v54
	v_mul_f32_e32 v111, 0.15915494, v53
	v_rndne_f32_e32 v111, v111
	v_fmac_f32_e32 v53, 0xc0c90000, v111
	v_fmac_f32_e32 v53, 0xbafdaa22, v111
	v_mul_f32_e32 v53, 0.15915494, v53
	v_sin_f32_e32 v114, v53
	v_cos_f32_e32 v116, v53
	v_pk_mul_f32 v[114:115], v[114:115], v[118:119] op_sel:[0,1] op_sel_hi:[0,0]
	v_pk_fma_f32 v[120:121], v[116:117], v[118:119], v[114:115] neg_lo:[0,0,1] neg_hi:[0,0,1]
	v_pk_fma_f32 v[114:115], v[116:117], v[118:119], v[114:115] op_sel_hi:[0,1,1]
	v_mov_b32_e32 v121, v115
	v_pk_mul_f32 v[114:115], v[120:121], v[110:111] op_sel_hi:[1,0]
	v_lshlrev_b32_e32 v119, 16, v7
	v_cvt_pk_bf16_f32 v53, v114, v115
	v_pk_mul_f32 v[114:115], v[120:121], v[112:113] op_sel_hi:[1,0]
	v_lshlrev_b32_e32 v118, 16, v3
	v_cvt_pk_bf16_f32 v111, v114, v115
	ds_write_b16 v65, v53
	ds_write_b16_d16_hi v65, v53 offset:17408
	ds_write_b16 v65, v111 offset:34816
	ds_write_b16_d16_hi v65, v111 offset:52224
	v_mul_f32_e32 v53, v66, v54
	v_mul_f32_e32 v111, 0.15915494, v53
	v_rndne_f32_e32 v111, v111
	v_fmac_f32_e32 v53, 0xc0c90000, v111
	v_fmac_f32_e32 v53, 0xbafdaa22, v111
	v_mul_f32_e32 v53, 0.15915494, v53
	v_sin_f32_e32 v114, v53
	v_cos_f32_e32 v116, v53
	v_pk_mul_f32 v[114:115], v[114:115], v[118:119] op_sel:[0,1] op_sel_hi:[0,0]
	v_pk_fma_f32 v[120:121], v[116:117], v[118:119], v[114:115] neg_lo:[0,0,1] neg_hi:[0,0,1]
	v_pk_fma_f32 v[114:115], v[116:117], v[118:119], v[114:115] op_sel_hi:[0,1,1]
	v_mov_b32_e32 v121, v115
	v_pk_mul_f32 v[114:115], v[120:121], v[110:111] op_sel_hi:[1,0]
	v_and_b32_e32 v119, 0xffff0000, v7
	v_cvt_pk_bf16_f32 v53, v114, v115
	v_pk_mul_f32 v[114:115], v[120:121], v[112:113] op_sel_hi:[1,0]
	v_and_b32_e32 v118, 0xffff0000, v3
	v_cvt_pk_bf16_f32 v111, v114, v115
	ds_write_b16 v67, v53
	ds_write_b16_d16_hi v67, v53 offset:17408
	ds_write_b16 v67, v111 offset:34816
	ds_write_b16_d16_hi v67, v111 offset:52224
	v_mul_f32_e32 v53, v68, v54
	v_mul_f32_e32 v111, 0.15915494, v53
	v_rndne_f32_e32 v111, v111
	v_fmac_f32_e32 v53, 0xc0c90000, v111
; __device__ __forceinline__ unsigned pk2(float lo, float hi) { return pg8::cvt_pk_bf16(lo, hi); }
; __device__ __forceinline__ float bfe(const u32x4& w, int e) { const unsigned x = w[e >> 1]; return (e & 1) ? bfhi(x) : bflo(x); }
; __device__ __forceinline__ float fexp2(float x) { return __builtin_amdgcn_exp2f(x); }
; __device__ __forceinline__ void kv_unit(LAS unsigned char* lds, int u, const bf16* PROJ, const int* pos, const float* dec_f, const float* dec_b, bf16* KVc, int tid, UnitRaw& raw, int next_u) {
;     ...
;     for (int ii = 0; ii < 2; ++ii) { const int it = tid + 512 * ii, dc = it & 7, j = it >> 3;
;         const u32x4 w1 = raw.k1[ii], w2 = raw.k2[ii];
;         const float p = raw.p[ii];
;         const float zf = fexp2(lgf2 * (float)(127 - j)) * 0.08838834764831845f, zb = fexp2(lgb2 * (float)j) * 0.08838834764831845f;
;         const int jsw = (((j >> 3) ^ (dc & 7)) << 3) | (j & 7);
; #pragma unroll
;         for (int e = 0; e < 8; ++e) { const int i = dc * 8 + e; const float inv = fexp2(-(float)i * 0.20762050593046015f);
;             float sn, cs; fast_sincos(p * inv, sn, cs);
;             const float k1 = bfe(w1, e), k2 = bfe(w2, e), r1 = k1 * cs - k2 * sn, r2 = k2 * cs + k1 * sn;
;             const unsigned pf = pk2(r1 * zf, r2 * zf), pb = pk2(r1 * zb, r2 * zb);
;             KTf[i * LDT + jsw] = (bf16)(pf & 0xffffu); KTf[(i + 64) * LDT + jsw] = (bf16)(pf >> 16);
;             KTb[i * LDT + jsw] = (bf16)(pb & 0xffffu); KTb[(i + 64) * LDT + jsw] = (bf16)(pb >> 16); }
	v_fmac_f32_e32 v53, 0xbafdaa22, v111
	v_mul_f32_e32 v53, 0.15915494, v53
	v_sin_f32_e32 v114, v53
	v_cos_f32_e32 v116, v53
	v_pk_mul_f32 v[114:115], v[114:115], v[118:119] op_sel:[0,1] op_sel_hi:[0,0]
	v_pk_fma_f32 v[120:121], v[116:117], v[118:119], v[114:115] neg_lo:[0,0,1] neg_hi:[0,0,1]
	v_pk_fma_f32 v[114:115], v[116:117], v[118:119], v[114:115] op_sel_hi:[0,1,1]
	v_mov_b32_e32 v121, v115
	v_pk_mul_f32 v[110:111], v[120:121], v[110:111] op_sel_hi:[1,0]
	s_nop 0
	v_cvt_pk_bf16_f32 v53, v110, v111
	v_pk_mul_f32 v[110:111], v[120:121], v[112:113] op_sel_hi:[1,0]
	s_nop 0
	v_cvt_pk_bf16_f32 v110, v110, v111
	ds_write_b16 v69, v53
	ds_write_b16_d16_hi v69, v53 offset:17408
	ds_write_b16 v69, v110 offset:34816
	ds_write_b16_d16_hi v69, v110 offset:52224
	v_mul_f32_e32 v49, v49, v71
	v_mul_f32_e32 v51, v51, v70
	v_exp_f32_e32 v49, v49
	v_exp_f32_e32 v51, v51
	v_lshlrev_b32_e32 v119, 16, v12
	v_lshlrev_b32_e32 v118, 16, v8
	v_mul_f32_e32 v112, 0x3db504f3, v49
	v_mul_f32_e32 v49, v35, v33
	v_mul_f32_e32 v110, 0x3db504f3, v51
	v_mul_f32_e32 v51, 0.15915494, v49
	v_rndne_f32_e32 v51, v51
	v_fmac_f32_e32 v49, 0xc0c90000, v51
	v_fmac_f32_e32 v49, 0xbafdaa22, v51
	v_mul_f32_e32 v49, 0.15915494, v49
	v_sin_f32_e32 v114, v49
	v_cos_f32_e32 v116, v49
	v_pk_mul_f32 v[114:115], v[114:115], v[118:119] op_sel:[0,1] op_sel_hi:[0,0]
	v_pk_fma_f32 v[120:121], v[116:117], v[118:119], v[114:115] neg_lo:[0,0,1] neg_hi:[0,0,1]
	v_pk_fma_f32 v[114:115], v[116:117], v[118:119], v[114:115] op_sel_hi:[0,1,1]
	v_mov_b32_e32 v121, v115
	v_pk_mul_f32 v[114:115], v[120:121], v[110:111] op_sel_hi:[1,0]
	v_and_b32_e32 v119, 0xffff0000, v12
	v_cvt_pk_bf16_f32 v49, v114, v115
	v_pk_mul_f32 v[114:115], v[120:121], v[112:113] op_sel_hi:[1,0]
	v_and_b32_e32 v118, 0xffff0000, v8
	v_cvt_pk_bf16_f32 v51, v114, v115
	ds_write_b16 v72, v49
	ds_write_b16_d16_hi v72, v49 offset:17408
	ds_write_b16 v72, v51 offset:34816
	ds_write_b16_d16_hi v72, v51 offset:52224
	v_mul_f32_e32 v49, v56, v33
	v_mul_f32_e32 v51, 0.15915494, v49
	v_rndne_f32_e32 v51, v51
	v_fmac_f32_e32 v49, 0xc0c90000, v51
	v_fmac_f32_e32 v49, 0xbafdaa22, v51
	v_mul_f32_e32 v49, 0.15915494, v49
	v_sin_f32_e32 v114, v49
	v_cos_f32_e32 v116, v49
	v_pk_mul_f32 v[114:115], v[114:115], v[118:119] op_sel:[0,1] op_sel_hi:[0,0]
	v_pk_fma_f32 v[120:121], v[116:117], v[118:119], v[114:115] neg_lo:[0,0,1] neg_hi:[0,0,1]
	v_pk_fma_f32 v[114:115], v[116:117], v[118:119], v[114:115] op_sel_hi:[0,1,1]
	v_mov_b32_e32 v121, v115
	v_pk_mul_f32 v[114:115], v[120:121], v[110:111] op_sel_hi:[1,0]
	v_lshlrev_b32_e32 v119, 16, v13
	v_cvt_pk_bf16_f32 v49, v114, v115
	v_pk_mul_f32 v[114:115], v[120:121], v[112:113] op_sel_hi:[1,0]
	v_lshlrev_b32_e32 v118, 16, v9
	v_cvt_pk_bf16_f32 v51, v114, v115
	ds_write_b16 v73, v49
	ds_write_b16_d16_hi v73, v49 offset:17408
	ds_write_b16 v73, v51 offset:34816
	ds_write_b16_d16_hi v73, v51 offset:52224
	v_mul_f32_e32 v49, v58, v33
	v_mul_f32_e32 v51, 0.15915494, v49
	v_rndne_f32_e32 v51, v51
	v_fmac_f32_e32 v49, 0xc0c90000, v51
	v_fmac_f32_e32 v49, 0xbafdaa22, v51
	v_mul_f32_e32 v49, 0.15915494, v49
	v_sin_f32_e32 v114, v49
	v_cos_f32_e32 v116, v49
	v_pk_mul_f32 v[114:115], v[114:115], v[118:119] op_sel:[0,1] op_sel_hi:[0,0]
	v_pk_fma_f32 v[120:121], v[116:117], v[118:119], v[114:115] neg_lo:[0,0,1] neg_hi:[0,0,1]
	v_pk_fma_f32 v[114:115], v[116:117], v[118:119], v[114:115] op_sel_hi:[0,1,1]
	v_mov_b32_e32 v121, v115
	v_pk_mul_f32 v[114:115], v[120:121], v[110:111] op_sel_hi:[1,0]
	v_and_b32_e32 v119, 0xffff0000, v13
	v_cvt_pk_bf16_f32 v49, v114, v115
	v_pk_mul_f32 v[114:115], v[120:121], v[112:113] op_sel_hi:[1,0]
	v_and_b32_e32 v118, 0xffff0000, v9
	v_cvt_pk_bf16_f32 v51, v114, v115
	ds_write_b16 v74, v49
	ds_write_b16_d16_hi v74, v49 offset:17408
	ds_write_b16 v74, v51 offset:34816
	ds_write_b16_d16_hi v74, v51 offset:52224
	v_mul_f32_e32 v49, v60, v33
	v_mul_f32_e32 v51, 0.15915494, v49
	v_rndne_f32_e32 v51, v51
	v_fmac_f32_e32 v49, 0xc0c90000, v51
	v_fmac_f32_e32 v49, 0xbafdaa22, v51
	v_mul_f32_e32 v49, 0.15915494, v49
	v_sin_f32_e32 v114, v49
	v_cos_f32_e32 v116, v49
	v_pk_mul_f32 v[114:115], v[114:115], v[118:119] op_sel:[0,1] op_sel_hi:[0,0]
	v_pk_fma_f32 v[120:121], v[116:117], v[118:119], v[114:115] neg_lo:[0,0,1] neg_hi:[0,0,1]
	v_pk_fma_f32 v[114:115], v[116:117], v[118:119], v[114:115] op_sel_hi:[0,1,1]
	v_mov_b32_e32 v121, v115
	v_pk_mul_f32 v[114:115], v[120:121], v[110:111] op_sel_hi:[1,0]
	v_lshlrev_b32_e32 v119, 16, v14
	v_cvt_pk_bf16_f32 v49, v114, v115
	v_pk_mul_f32 v[114:115], v[120:121], v[112:113] op_sel_hi:[1,0]
	v_lshlrev_b32_e32 v118, 16, v10
	v_cvt_pk_bf16_f32 v51, v114, v115
	ds_write_b16 v77, v49
	ds_write_b16_d16_hi v77, v49 offset:17408
	ds_write_b16 v77, v51 offset:34816
	ds_write_b16_d16_hi v77, v51 offset:52224
	v_mul_f32_e32 v49, v62, v33
	v_mul_f32_e32 v51, 0.15915494, v49
	v_rndne_f32_e32 v51, v51
	v_fmac_f32_e32 v49, 0xc0c90000, v51
	v_fmac_f32_e32 v49, 0xbafdaa22, v51
	v_mul_f32_e32 v49, 0.15915494, v49
	v_sin_f32_e32 v114, v49
	v_cos_f32_e32 v116, v49
	v_pk_mul_f32 v[114:115], v[114:115], v[118:119] op_sel:[0,1] op_sel_hi:[0,0]
	v_pk_fma_f32 v[120:121], v[116:117], v[118:119], v[114:115] neg_lo:[0,0,1] neg_hi:[0,0,1]
	v_pk_fma_f32 v[114:115], v[116:117], v[118:119], v[114:115] op_sel_hi:[0,1,1]
	v_mov_b32_e32 v121, v115
	v_pk_mul_f32 v[114:115], v[120:121], v[110:111] op_sel_hi:[1,0]
	v_and_b32_e32 v119, 0xffff0000, v14
	v_cvt_pk_bf16_f32 v49, v114, v115
	v_pk_mul_f32 v[114:115], v[120:121], v[112:113] op_sel_hi:[1,0]
	v_and_b32_e32 v118, 0xffff0000, v10
	v_cvt_pk_bf16_f32 v51, v114, v115
	ds_write_b16 v78, v49
	ds_write_b16_d16_hi v78, v49 offset:17408
; #define LAS __attribute__((address_space(3)))
; template <bool WITHQ> __device__ __forceinline__ void raw_load(UnitRaw& r, int u, const bf16* PROJ, const int* pos, int tid) {
;     const int bh = u >> 6, c = u & 63, b = bh >> 2, h = bh & 3; const size_t row0 = (size_t)b * SEQ + (size_t)c * 128;
; #pragma unroll
;     for (int i = 0; i < 2; ++i) { const int it = tid + 512 * i, dc = it & 7, j = it >> 3; const bf16* qr = PROJ + (row0 + j) * INC + h * 128 + dc * 8; const bf16* kr = qr + 512;
;         if (WITHQ) { r.a1[i] = *(const u32x4*)qr; r.a2[i] = *(const u32x4*)(qr + 64); }
;         r.k1[i] = *(const u32x4*)kr; r.k2[i] = *(const u32x4*)(kr + 64); r.p[i] = (float)pos[row0 + j]; }
; #pragma unroll
;     for (int i = 0; i < 4; ++i) { const int it = tid + 512 * i, ec = it & 15, j = it >> 4; r.v[i] = *(const u32x4*)(PROJ + (row0 + j) * INC + 1024 + h * 128 + ec * 8); }
; __device__ __forceinline__ void stage_vt_regs(LAS bf16* VT, const UnitRaw& r, int tid) {
; #pragma unroll
;     for (int i = 0; i < 4; ++i) { const int it = tid + 512 * i, ec = it & 15, j = it >> 4; const u32x4 w = r.v[i];
;         const int jsw = (((j >> 3) ^ (ec & 7)) << 3) | (j & 7);
; #pragma unroll
;         for (int e = 0; e < 4; ++e) { VT[(ec * 8 + 2 * e) * LDT + jsw] = (bf16)(w[e] & 0xffffu); VT[(ec * 8 + 2 * e + 1) * LDT + jsw] = (bf16)(w[e] >> 16); } }
	ds_write_b16 v78, v51 offset:34816
	ds_write_b16_d16_hi v78, v51 offset:52224
	v_mul_f32_e32 v49, v64, v33
	v_mul_f32_e32 v51, 0.15915494, v49
	v_rndne_f32_e32 v51, v51
	v_fmac_f32_e32 v49, 0xc0c90000, v51
	v_fmac_f32_e32 v49, 0xbafdaa22, v51
	v_mul_f32_e32 v49, 0.15915494, v49
	v_sin_f32_e32 v114, v49
	v_cos_f32_e32 v116, v49
	v_pk_mul_f32 v[114:115], v[114:115], v[118:119] op_sel:[0,1] op_sel_hi:[0,0]
	v_pk_fma_f32 v[120:121], v[116:117], v[118:119], v[114:115] neg_lo:[0,0,1] neg_hi:[0,0,1]
	v_pk_fma_f32 v[114:115], v[116:117], v[118:119], v[114:115] op_sel_hi:[0,1,1]
	v_mov_b32_e32 v121, v115
	v_pk_mul_f32 v[114:115], v[120:121], v[110:111] op_sel_hi:[1,0]
	v_lshlrev_b32_e32 v119, 16, v15
	v_cvt_pk_bf16_f32 v49, v114, v115
	v_pk_mul_f32 v[114:115], v[120:121], v[112:113] op_sel_hi:[1,0]
	v_lshlrev_b32_e32 v118, 16, v11
	v_cvt_pk_bf16_f32 v51, v114, v115
	ds_write_b16 v79, v49
	ds_write_b16_d16_hi v79, v49 offset:17408
	ds_write_b16 v79, v51 offset:34816
	ds_write_b16_d16_hi v79, v51 offset:52224
	v_mul_f32_e32 v49, v66, v33
	v_mul_f32_e32 v51, 0.15915494, v49
	v_rndne_f32_e32 v51, v51
	v_fmac_f32_e32 v49, 0xc0c90000, v51
	v_fmac_f32_e32 v49, 0xbafdaa22, v51
	v_mul_f32_e32 v49, 0.15915494, v49
	v_sin_f32_e32 v114, v49
	v_cos_f32_e32 v116, v49
	v_pk_mul_f32 v[114:115], v[114:115], v[118:119] op_sel:[0,1] op_sel_hi:[0,0]
	v_pk_fma_f32 v[120:121], v[116:117], v[118:119], v[114:115] neg_lo:[0,0,1] neg_hi:[0,0,1]
	v_pk_fma_f32 v[114:115], v[116:117], v[118:119], v[114:115] op_sel_hi:[0,1,1]
	v_mov_b32_e32 v121, v115
	v_pk_mul_f32 v[114:115], v[120:121], v[110:111] op_sel_hi:[1,0]
	v_and_b32_e32 v119, 0xffff0000, v15
	v_cvt_pk_bf16_f32 v49, v114, v115
	v_pk_mul_f32 v[114:115], v[120:121], v[112:113] op_sel_hi:[1,0]
	v_and_b32_e32 v118, 0xffff0000, v11
	v_cvt_pk_bf16_f32 v51, v114, v115
	ds_write_b16 v80, v49
	ds_write_b16_d16_hi v80, v49 offset:17408
	ds_write_b16 v80, v51 offset:34816
	ds_write_b16_d16_hi v80, v51 offset:52224
	v_mul_f32_e32 v49, v68, v33
	v_mul_f32_e32 v51, 0.15915494, v49
	v_rndne_f32_e32 v51, v51
	v_fmac_f32_e32 v49, 0xc0c90000, v51
	v_fmac_f32_e32 v49, 0xbafdaa22, v51
	v_mul_f32_e32 v49, 0.15915494, v49
	v_sin_f32_e32 v114, v49
	v_cos_f32_e32 v116, v49
	v_pk_mul_f32 v[114:115], v[114:115], v[118:119] op_sel:[0,1] op_sel_hi:[0,0]
	v_pk_fma_f32 v[120:121], v[116:117], v[118:119], v[114:115] neg_lo:[0,0,1] neg_hi:[0,0,1]
	v_pk_fma_f32 v[114:115], v[116:117], v[118:119], v[114:115] op_sel_hi:[0,1,1]
	v_mov_b32_e32 v121, v115
	v_pk_mul_f32 v[110:111], v[120:121], v[110:111] op_sel_hi:[1,0]
	s_nop 0
	v_cvt_pk_bf16_f32 v49, v110, v111
	v_pk_mul_f32 v[110:111], v[120:121], v[112:113] op_sel_hi:[1,0]
	s_nop 0
	v_cvt_pk_bf16_f32 v51, v110, v111
	ds_write_b16 v81, v49
	ds_write_b16_d16_hi v81, v49 offset:17408
	ds_write_b16 v81, v51 offset:34816
	ds_write_b16_d16_hi v81, v51 offset:52224
	s_cmp_lt_i32 s3, 0
	ds_write_b16 v82, v16
	ds_write_b16_d16_hi v82, v16 offset:272
	ds_write_b16 v82, v17 offset:544
	ds_write_b16_d16_hi v82, v17 offset:816
	ds_write_b16 v82, v18 offset:1088
	ds_write_b16_d16_hi v82, v18 offset:1360
	ds_write_b16 v82, v19 offset:1632
	ds_write_b16_d16_hi v82, v19 offset:1904
	ds_write_b16 v83, v20
	ds_write_b16_d16_hi v83, v20 offset:272
	ds_write_b16 v83, v21 offset:544
	ds_write_b16_d16_hi v83, v21 offset:816
	ds_write_b16 v83, v22 offset:1088
	ds_write_b16_d16_hi v83, v22 offset:1360
	ds_write_b16 v83, v23 offset:1632
	ds_write_b16_d16_hi v83, v23 offset:1904
	ds_write_b16 v84, v24
	ds_write_b16_d16_hi v84, v24 offset:272
	ds_write_b16 v84, v25 offset:544
	ds_write_b16_d16_hi v84, v25 offset:816
	ds_write_b16 v84, v26 offset:1088
	ds_write_b16_d16_hi v84, v26 offset:1360
	ds_write_b16 v84, v27 offset:1632
	ds_write_b16_d16_hi v84, v27 offset:1904
	ds_write_b16 v85, v28
	ds_write_b16_d16_hi v85, v28 offset:272
	ds_write_b16 v85, v29 offset:544
	ds_write_b16_d16_hi v85, v29 offset:816
	ds_write_b16 v85, v30 offset:1088
	ds_write_b16_d16_hi v85, v30 offset:1360
	ds_write_b16 v85, v31 offset:1632
	ds_write_b16_d16_hi v85, v31 offset:1904
	s_waitcnt lgkmcnt(0)
	s_barrier
	s_cbranch_scc1 .LBB0_216
	s_lshr_b32 s4, s3, 8
	s_lshl_b64 s[50:51], s[4:5], 13
	s_lshl_b32 s4, s3, 7
	s_and_b32 s4, s4, 0x1f80
	s_lshl_b32 s3, s3, 2
	s_or_b32 s50, s50, s4
	s_and_b32 s4, s3, 0x300
	v_lshl_add_u64 v[8:9], v[46:47], 0, s[4:5]
	v_or_b32_e32 v10, s50, v34
	v_lshl_add_u64 v[18:19], s[50:51], 0, v[36:37]
	v_mov_b32_e32 v11, s51
	v_mad_u64_u32 v[4:5], s[52:53], v10, s14, v[8:9]
	v_mad_u64_u32 v[12:13], s[52:53], v18, s14, v[8:9]
	v_mad_u32_u24 v5, s51, v87, v5
	v_lshl_add_u64 v[16:17], v[10:11], 2, s[12:13]
	v_mad_u32_u24 v13, v19, s14, v13
	v_lshl_add_u64 v[18:19], v[18:19], 2, s[12:13]
	global_load_dwordx4 v[0:3], v[4:5], off offset:1024 nt
	s_nop 0
	global_load_dwordx4 v[4:7], v[4:5], off offset:1152 nt
	s_nop 0
	global_load_dwordx4 v[8:11], v[12:13], off offset:1024 nt
	s_nop 0
	global_load_dwordx4 v[12:15], v[12:13], off offset:1152 nt
	s_nop 0
	global_load_dword v33, v[16:17], off
	global_load_dword v51, v[18:19], off
	v_or_b32_e32 v16, s50, v32
	v_mov_b64_e32 v[24:25], s[6:7]
	v_or_b32_e32 v18, s50, v40
	v_or_b32_e32 v26, s50, v42
	v_mad_u64_u32 v[16:17], s[52:53], v16, s14, v[24:25]
	v_mad_u64_u32 v[18:19], s[52:53], v18, s14, v[24:25]
	v_mad_u64_u32 v[26:27], s[52:53], v26, s14, v[24:25]
	v_lshl_add_u64 v[28:29], s[50:51], 0, v[44:45]
	v_mad_u32_u24 v17, s51, v87, v17
	v_mad_u32_u24 v19, s51, v87, v19
	v_mad_u32_u24 v27, s51, v87, v27
	v_mad_u64_u32 v[24:25], s[50:51], v28, s14, v[24:25]
	v_mad_u32_u24 v25, v29, s14, v25
	v_lshl_add_u64 v[16:17], v[16:17], 0, s[4:5]
	v_mov_b32_e32 v49, v39
	v_lshl_add_u64 v[18:19], v[18:19], 0, s[4:5]
	v_lshl_add_u64 v[26:27], v[26:27], 0, s[4:5]
	v_lshl_add_u64 v[24:25], v[24:25], 0, s[4:5]
	v_lshl_add_u64 v[16:17], v[16:17], 0, v[48:49]
	v_lshl_add_u64 v[20:21], v[18:19], 0, v[48:49]
	v_lshl_add_u64 v[26:27], v[26:27], 0, v[48:49]
	v_lshl_add_u64 v[28:29], v[24:25], 0, v[48:49]
	global_load_dwordx4 v[16:19], v[16:17], off offset:2048 nt
	s_nop 0
	global_load_dwordx4 v[20:23], v[20:21], off offset:2048 nt
	s_nop 0
	global_load_dwordx4 v[24:27], v[26:27], off offset:2048 nt
	s_nop 0
	global_load_dwordx4 v[28:31], v[28:29], off offset:2048 nt
	s_waitcnt vmcnt(5)
	v_cvt_f32_i32_e32 v54, v33
	s_waitcnt vmcnt(4)
	v_cvt_f32_i32_e32 v33, v51
	s_branch .LBB0_216

; #define LAS __attribute__((address_space(3)))
; __device__ __forceinline__ float bflo(unsigned w) { return __uint_as_float(w << 16); }
; __device__ __forceinline__ float bfhi(unsigned w) { return __uint_as_float(w & 0xffff0000u); }
; __device__ __forceinline__ void conv_unit(LAS unsigned char* lds, int u, const bf16* PROJ, const float* conv_w, const float* conv_b, const float* ln_w, const float* ln_b, bf16* MIX, int tid, const WsRef& wsr) {
;     ...
;     for (int it = tid; it < 62 * 64; it += 512) { const int r = it >> 6, cc = it & 63; const int t = t0 - 15 + r;
;         f32x4 u0 = (f32x4){0.f, 0.f, 0.f, 0.f}, u1 = u0;
;         if (t >= 0 && t < SEQ) { const bf16* pr = PROJ + (rowb + t) * INC + 2048 + cc * 8; const u32x4 a = *(const u32x4*)pr, g = *(const u32x4*)(pr + 512);
; #pragma unroll
;             for (int e = 0; e < 4; ++e) { const float a0 = bflo(a[e]), a1 = bfhi(a[e]), g0 = bflo(g[e]), g1 = bfhi(g[e]);
;                 const float v0 = a0 * __builtin_amdgcn_rcpf(1.f + __expf(-g0)), v1 = a1 * __builtin_amdgcn_rcpf(1.f + __expf(-g1));
;                 if (e < 2) { u0[2 * e] = v0; u0[2 * e + 1] = v1; } else { u1[2 * e - 4] = v0; u1[2 * e - 3] = v1; } } }
;         *(LAS f32x4*)(U + r * 512 + cc * 8) = u0; *(LAS f32x4*)(U + r * 512 + cc * 8 + 4) = u1; }
.LBB0_223:
	v_cmp_gt_u32_e32 vcc, s24, v84
	v_mov_b32_e32 v0, 0
	v_mov_b32_e32 v1, 0
	v_mov_b32_e32 v2, 0
	v_mov_b32_e32 v3, 0
	v_mov_b32_e32 v4, 0
	v_mov_b32_e32 v5, 0
	v_mov_b32_e32 v6, 0
	v_mov_b32_e32 v7, 0
	s_and_saveexec_b64 s[14:15], vcc
	s_cbranch_execz .LBB0_222
	v_or_b32_e32 v2, s8, v84
	v_mov_b64_e32 v[0:1], s[6:7]
	v_mad_u64_u32 v[0:1], s[30:31], v2, s25, v[0:1]
	v_mad_i32_i24 v1, s9, v218, v1
	v_lshl_add_u64 v[4:5], v[0:1], 0, v[8:9]
	v_lshl_add_u64 v[0:1], v[4:5], 0, s[4:5]
	v_add_co_u32_e32 v4, vcc, 0x1000, v4
	global_load_dwordx4 v[0:3], v[0:1], off offset:1024 nt
	s_nop 0
	v_addc_co_u32_e32 v5, vcc, 0, v5, vcc
	global_load_dwordx4 v[4:7], v[4:5], off nt
	s_waitcnt vmcnt(1)
	v_and_b32_e32 v90, 0xffff0000, v0
	v_lshlrev_b32_e32 v92, 16, v0
	v_lshlrev_b32_e32 v94, 16, v1
	s_waitcnt vmcnt(0)
	v_lshlrev_b32_e32 v142, 16, v4
	v_and_b32_e32 v143, 0xffff0000, v4
	v_and_b32_e32 v4, 0xffff0000, v1
	v_lshlrev_b32_e32 v0, 16, v5
	v_and_b32_e32 v1, 0xffff0000, v5
	v_and_b32_e32 v5, 0xffff0000, v2
	v_lshlrev_b32_e32 v96, 16, v2
	v_lshlrev_b32_e32 v144, 16, v6
	v_and_b32_e32 v145, 0xffff0000, v6
	v_lshlrev_b32_e32 v6, 16, v3
	v_and_b32_e32 v98, 0xffff0000, v3
	v_lshlrev_b32_e32 v2, 16, v7
	v_and_b32_e32 v3, 0xffff0000, v7
	v_mul_f32_e32 v7, 0xbfb8aa3b, v90
	v_mul_f32_e32 v90, 0xbfb8aa3b, v92
	v_mul_f32_e32 v4, 0xbfb8aa3b, v4
	v_mul_f32_e32 v92, 0xbfb8aa3b, v94
	v_mul_f32_e32 v5, 0xbfb8aa3b, v5
	v_mul_f32_e32 v94, 0xbfb8aa3b, v96
	v_mul_f32_e32 v6, 0xbfb8aa3b, v6
	v_mul_f32_e32 v96, 0xbfb8aa3b, v98
	v_exp_f32_e32 v7, v7
	v_exp_f32_e32 v90, v90
	v_exp_f32_e32 v4, v4
	v_exp_f32_e32 v92, v92
	v_exp_f32_e32 v5, v5
	v_exp_f32_e32 v94, v94
	v_exp_f32_e32 v6, v6
	v_exp_f32_e32 v96, v96
	v_add_f32_e32 v7, 1.0, v7
	v_add_f32_e32 v90, 1.0, v90
	v_add_f32_e32 v98, 1.0, v4
	v_add_f32_e32 v92, 1.0, v92
	v_add_f32_e32 v100, 1.0, v5
	v_add_f32_e32 v94, 1.0, v94
	v_add_f32_e32 v102, 1.0, v6
	v_add_f32_e32 v96, 1.0, v96
	v_rcp_f32_e32 v5, v7
	v_rcp_f32_e32 v4, v90
	v_rcp_f32_e32 v7, v98
	v_rcp_f32_e32 v6, v92
	v_rcp_f32_e32 v147, v100
	v_rcp_f32_e32 v146, v94
	v_rcp_f32_e32 v148, v102
	v_rcp_f32_e32 v149, v96
	v_pk_mul_f32 v[4:5], v[4:5], v[142:143]
	v_pk_mul_f32 v[6:7], v[6:7], v[0:1]
	v_pk_mul_f32 v[0:1], v[146:147], v[144:145]
	v_pk_mul_f32 v[2:3], v[148:149], v[2:3]
	s_branch .LBB0_222

; __device__ __forceinline__ float log_sigmoid(float x) { return -log1pf(expf(-x)); }
; __global__ void __launch_bounds__(512, 2) fwd_mega(Args a) {
;     ...
;         for (int idx = sb * 512 + tid; idx < 131072; idx += sG * 512) {
;             const int p = idx & 8191, bh = (idx >> 13) & 7, dir = idx >> 16, h = bh & 3;
;             const float lg = log_sigmoid(dir ? a.in[6][h] : a.in[5][h]); const float dec = expf(lg * 128.f);
;             const size_t base = (size_t)(dir * 8 + bh) * 64 * 16384 + (size_t)p * 2;
;             const bf16* kv = KVC + base; bf16* st = ST + base;
;             float s0 = 0.f, s1 = 0.f;
;             const unsigned* kvw = (const unsigned*)kv; unsigned* stw = (unsigned*)st;
.LBB0_377:
	v_cmp_gt_u32_e32 vcc, s26, v26
	v_lshrrev_b32_e32 v0, 11, v26
	v_and_b32_e32 v0, 12, v0
	v_cndmask_b32_e32 v3, v27, v28, vcc
	v_cndmask_b32_e32 v2, v29, v30, vcc
	v_lshl_add_u64 v[2:3], v[2:3], 0, v[0:1]
	global_load_dword v0, v[2:3], off nt
	v_lshrrev_b32_e32 v3, 13, v26
	v_ashrrev_i32_e32 v4, 13, v26
	v_bfi_b32 v4, -8, v4, v3
	v_lshlrev_b32_e32 v8, 2, v26
	v_readlane_b32 s44, v255, 10
	v_readlane_b32 s58, v255, 24
	v_readlane_b32 s59, v255, 25
	s_mov_b32 s42, 0
	s_mov_b32 s43, 63
	v_mov_b32_e32 v2, v1
	v_readlane_b32 s45, v255, 11
	v_readlane_b32 s46, v255, 12
	v_readlane_b32 s47, v255, 13
	v_readlane_b32 s48, v255, 14
	v_readlane_b32 s49, v255, 15
	v_readlane_b32 s50, v255, 16
	v_readlane_b32 s51, v255, 17
	v_readlane_b32 s52, v255, 18
	v_readlane_b32 s53, v255, 19
	v_readlane_b32 s54, v255, 20
	v_readlane_b32 s55, v255, 21
	v_readlane_b32 s56, v255, 22
	v_readlane_b32 s57, v255, 23
	s_waitcnt vmcnt(0)
	v_mul_f32_e32 v5, 0xbfb8aa3b, v0
	v_fma_f32 v6, v0, s27, -v5
	v_rndne_f32_e32 v7, v5
	v_fmac_f32_e32 v6, 0xb2a5705f, v0
	v_sub_f32_e32 v5, v5, v7
	v_add_f32_e32 v5, v5, v6
	v_cvt_i32_f32_e32 v9, v7
	v_exp_f32_e32 v10, v5
	v_cmp_nlt_f32_e64 s[0:1], s28, v0
	v_ashrrev_i32_e32 v5, 31, v4
	v_lshlrev_b64 v[6:7], 21, v[4:5]
	v_ldexp_f32 v3, v10, v9
	v_cndmask_b32_e64 v3, 0, v3, s[0:1]
	v_cmp_ngt_f32_e64 s[0:1], s29, v0
	v_and_or_b32 v6, v8, s40, v6
	s_nop 0
	v_cndmask_b32_e64 v0, v31, v3, s[0:1]
	v_add_f32_e32 v3, 1.0, v0
	v_add_f32_e32 v9, -1.0, v3
	v_frexp_mant_f32_e32 v10, v3
	v_cvt_f64_f32_e32 v[4:5], v3
	v_sub_f32_e32 v11, v9, v3
	v_frexp_exp_i32_f64_e32 v4, v[4:5]
	v_cmp_gt_f32_e64 s[0:1], s31, v10
	v_sub_f32_e32 v9, v0, v9
	v_add_f32_e32 v5, 1.0, v11
	v_subbrev_co_u32_e64 v4, s[0:1], 0, v4, s[0:1]
	v_add_f32_e32 v5, v9, v5
	v_sub_u32_e32 v9, 0, v4
	v_cvt_f32_i32_e32 v4, v4
	v_ldexp_f32 v3, v3, v9
	v_ldexp_f32 v5, v5, v9
	v_add_f32_e32 v9, -1.0, v3
	v_add_f32_e32 v10, 1.0, v3
	v_add_f32_e32 v11, 1.0, v9
	v_add_f32_e32 v12, -1.0, v10
	v_sub_f32_e32 v11, v3, v11
	v_sub_f32_e32 v3, v3, v12
	v_mul_f32_e32 v12, 0x3f317218, v4
	v_add_f32_e32 v11, v5, v11
	v_add_f32_e32 v3, v5, v3
	v_fma_f32 v5, v4, s33, -v12
	v_add_f32_e32 v13, v9, v11
	v_add_f32_e32 v14, v10, v3
	v_fmac_f32_e32 v5, 0xb102e308, v4
	v_sub_f32_e32 v4, v9, v13
	v_sub_f32_e32 v9, v10, v14
	v_rcp_f32_e32 v10, v14
	v_add_f32_e32 v15, v12, v5
	v_add_f32_e32 v3, v3, v9
	v_sub_f32_e32 v9, v15, v12
	v_sub_f32_e32 v5, v5, v9
	v_mul_f32_e32 v9, v13, v10
	v_add_f32_e32 v4, v11, v4
	v_mul_f32_e32 v11, v14, v9
	v_fma_f32 v12, v9, v14, -v11
	v_fmac_f32_e32 v12, v9, v3
	v_add_f32_e32 v16, v11, v12
	v_sub_f32_e32 v17, v13, v16
	v_sub_f32_e32 v11, v16, v11
	v_sub_f32_e32 v13, v13, v17
	v_sub_f32_e32 v11, v11, v12
	v_sub_f32_e32 v12, v13, v16
	v_add_f32_e32 v4, v4, v12
	v_add_f32_e32 v4, v11, v4
	v_add_f32_e32 v11, v17, v4
	v_mul_f32_e32 v12, v10, v11
	v_sub_f32_e32 v13, v17, v11
	v_mul_f32_e32 v16, v14, v12
	v_add_f32_e32 v4, v4, v13
	v_add_f32_e32 v13, v9, v12
	v_fma_f32 v14, v12, v14, -v16
	v_sub_f32_e32 v9, v13, v9
	v_fmac_f32_e32 v14, v12, v3
	v_sub_f32_e32 v3, v12, v9
	v_add_f32_e32 v9, v16, v14
	v_sub_f32_e32 v12, v9, v16
	v_sub_f32_e32 v16, v11, v9
	v_sub_f32_e32 v11, v11, v16
	v_sub_f32_e32 v9, v11, v9
	v_sub_f32_e32 v12, v12, v14
	v_add_f32_e32 v4, v4, v9
	v_add_f32_e32 v4, v12, v4
	v_add_f32_e32 v4, v16, v4
	v_mul_f32_e32 v4, v10, v4
	v_add_f32_e32 v3, v3, v4
	v_add_f32_e32 v4, v13, v3
	v_mul_f32_e32 v9, v4, v4
	v_fmamk_f32 v12, v9, 0x3e9b6dac, v32
	v_sub_f32_e32 v10, v4, v13
	v_ldexp_f32 v11, v4, 1
	v_mul_f32_e32 v4, v4, v9
	v_fmaak_f32 v9, v9, v12, 0x3f2aaada
	v_mul_f32_e32 v4, v4, v9
	v_add_f32_e32 v9, v11, v4
	v_sub_f32_e32 v3, v3, v10
	v_sub_f32_e32 v10, v9, v11
	v_ldexp_f32 v3, v3, 1
	v_sub_f32_e32 v4, v4, v10
	v_add_f32_e32 v3, v3, v4
	v_add_f32_e32 v4, v9, v3
	v_sub_f32_e32 v9, v4, v9
	v_add_f32_e32 v10, v15, v4
	v_sub_f32_e32 v3, v3, v9
	v_sub_f32_e32 v9, v10, v15
	v_sub_f32_e32 v11, v10, v9
	v_sub_f32_e32 v4, v4, v9
	v_add_f32_e32 v9, v5, v3
	v_sub_f32_e32 v11, v15, v11
	v_sub_f32_e32 v12, v9, v5
	v_add_f32_e32 v4, v4, v11
	v_sub_f32_e32 v11, v9, v12
	v_sub_f32_e32 v3, v3, v12
	v_sub_f32_e32 v5, v5, v11
	v_add_f32_e32 v4, v9, v4
	v_add_f32_e32 v3, v3, v5
	v_add_f32_e32 v5, v10, v4
	v_sub_f32_e32 v9, v5, v10
	v_sub_f32_e32 v4, v4, v9
	v_add_f32_e32 v3, v3, v4
	v_add_f32_e32 v3, v5, v3
	v_cmp_neq_f32_e64 s[0:1], s30, v0
	s_nop 1
	v_cndmask_b32_e64 v3, v31, v3, s[0:1]
	v_cmp_lt_f32_e64 s[0:1], |v0|, s34
	s_nop 1
	v_cndmask_b32_e64 v0, v3, v0, s[0:1]
	v_mul_f32_e32 v0, 0xc3000000, v0
	v_mul_f32_e32 v3, 0x3fb8aa3b, v0
	v_fma_f32 v4, v0, s35, -v3
	v_rndne_f32_e32 v5, v3
	v_fmac_f32_e32 v4, 0x32a5705f, v0
	v_sub_f32_e32 v3, v3, v5
	v_add_f32_e32 v3, v3, v4
	v_cvt_i32_f32_e32 v9, v5
	v_exp_f32_e32 v3, v3
	v_readlane_b32 s0, v255, 26
	v_readlane_b32 s1, v255, 27
	v_ldexp_f32 v3, v3, v9
	s_nop 0
	v_lshl_add_u64 v[4:5], s[0:1], 0, v[6:7]
	v_cmp_ngt_f32_e64 s[0:1], s38, v0
	v_lshl_add_u64 v[6:7], s[58:59], 0, v[6:7]
	s_nop 0
	v_cndmask_b32_e64 v3, 0, v3, s[0:1]
	v_cmp_nlt_f32_e64 s[0:1], s39, v0
	s_nop 1
	v_cndmask_b32_e64 v8, v31, v3, s[0:1]
	v_mov_b32_e32 v9, v8
	v_mov_b32_e32 v3, v1
; __device__ __forceinline__ unsigned pk2(float lo, float hi) { return pg8::cvt_pk_bf16(lo, hi); }
; __device__ __forceinline__ float bflo(unsigned w) { return __uint_as_float(w << 16); }
; __device__ __forceinline__ float bfhi(unsigned w) { return __uint_as_float(w & 0xffff0000u); }
; __global__ void __launch_bounds__(512, 2) fwd_mega(Args a) {
;     ...
;             for (int c0 = 0; c0 < 64; c0 += 16) {
;                 unsigned w[16];
; #pragma unroll
;                 for (int i = 0; i < 16; ++i) { const int cc = dir ? 63 - (c0 + i) : c0 + i; w[i] = kvw[(size_t)cc * 8192]; }
; #pragma unroll
;                 for (int i = 0; i < 16; ++i) { const int cc = dir ? 63 - (c0 + i) : c0 + i; stw[(size_t)cc * 8192] = pk2(s0, s1); s0 = fmaf(dec, s0, bflo(w[i])); s1 = fmaf(dec, s1, bfhi(w[i])); }
.LBB0_378:
	v_mov_b32_e32 v0, s43
	v_mov_b32_e32 v10, s42
	v_cndmask_b32_e32 v0, v0, v10, vcc
	v_lshlrev_b32_e32 v0, 15, v0
	v_lshl_add_u64 v[10:11], v[4:5], 0, v[0:1]
	s_add_i32 s0, s43, -1
	s_add_i32 s1, s42, 1
	global_load_dword v33, v[10:11], off nt
	v_mov_b32_e32 v10, s0
	v_mov_b32_e32 v11, s1
	v_cndmask_b32_e32 v10, v10, v11, vcc
	v_lshlrev_b32_e32 v10, 15, v10
	v_mov_b32_e32 v11, v1
	v_lshl_add_u64 v[12:13], v[4:5], 0, v[10:11]
	s_add_i32 s0, s43, -2
	s_add_i32 s1, s42, 2
	global_load_dword v50, v[12:13], off nt
	v_mov_b32_e32 v12, s0
	v_mov_b32_e32 v13, s1
	v_cndmask_b32_e32 v12, v12, v13, vcc
	v_lshlrev_b32_e32 v12, 15, v12
	v_mov_b32_e32 v13, v1
	v_lshl_add_u64 v[14:15], v[4:5], 0, v[12:13]
	s_add_i32 s0, s43, -3
	s_add_i32 s1, s42, 3
	global_load_dword v51, v[14:15], off nt
	v_mov_b32_e32 v14, s0
	v_mov_b32_e32 v15, s1
	v_cndmask_b32_e32 v14, v14, v15, vcc
	v_lshlrev_b32_e32 v14, 15, v14
	v_mov_b32_e32 v15, v1
	v_lshl_add_u64 v[16:17], v[4:5], 0, v[14:15]
	s_add_i32 s0, s43, -4
	s_add_i32 s1, s42, 4
	global_load_dword v52, v[16:17], off nt
	v_mov_b32_e32 v16, s0
	v_mov_b32_e32 v17, s1
	v_cndmask_b32_e32 v16, v16, v17, vcc
	v_lshlrev_b32_e32 v16, 15, v16
	v_mov_b32_e32 v17, v1
	v_lshl_add_u64 v[18:19], v[4:5], 0, v[16:17]
	s_add_i32 s0, s43, -5
	s_add_i32 s1, s42, 5
	global_load_dword v53, v[18:19], off nt
	v_mov_b32_e32 v18, s0
	v_mov_b32_e32 v19, s1
	v_cndmask_b32_e32 v18, v18, v19, vcc
	v_lshlrev_b32_e32 v18, 15, v18
	v_mov_b32_e32 v19, v1
	v_lshl_add_u64 v[20:21], v[4:5], 0, v[18:19]
	s_add_i32 s0, s43, -6
	s_add_i32 s1, s42, 6
	global_load_dword v54, v[20:21], off nt
	v_mov_b32_e32 v20, s0
	v_mov_b32_e32 v21, s1
	v_cndmask_b32_e32 v20, v20, v21, vcc
	v_lshlrev_b32_e32 v20, 15, v20
	v_mov_b32_e32 v21, v1
	v_lshl_add_u64 v[22:23], v[4:5], 0, v[20:21]
	s_add_i32 s0, s43, -7
	s_add_i32 s1, s42, 7
	global_load_dword v55, v[22:23], off nt
	v_mov_b32_e32 v22, s0
	v_mov_b32_e32 v23, s1
	v_cndmask_b32_e32 v22, v22, v23, vcc
	v_lshlrev_b32_e32 v22, 15, v22
	v_mov_b32_e32 v23, v1
	v_lshl_add_u64 v[24:25], v[4:5], 0, v[22:23]
	s_add_i32 s0, s43, -8
	s_add_i32 s1, s42, 8
	global_load_dword v56, v[24:25], off nt
	v_mov_b32_e32 v24, s0
	v_mov_b32_e32 v25, s1
	v_cndmask_b32_e32 v24, v24, v25, vcc
	v_lshlrev_b32_e32 v24, 15, v24
	v_mov_b32_e32 v25, v1
	v_lshl_add_u64 v[34:35], v[4:5], 0, v[24:25]
	s_add_i32 s0, s43, -9
	s_add_i32 s1, s42, 9
	global_load_dword v57, v[34:35], off nt
	v_mov_b32_e32 v34, s0
	v_mov_b32_e32 v35, s1
	v_cndmask_b32_e32 v34, v34, v35, vcc
	v_lshlrev_b32_e32 v34, 15, v34
	v_mov_b32_e32 v35, v1
	v_lshl_add_u64 v[36:37], v[4:5], 0, v[34:35]
	s_add_i32 s0, s43, -10
	s_add_i32 s1, s42, 10
	global_load_dword v58, v[36:37], off nt
	v_mov_b32_e32 v36, s0
	v_mov_b32_e32 v37, s1
	v_cndmask_b32_e32 v36, v36, v37, vcc
	v_lshlrev_b32_e32 v36, 15, v36
	v_mov_b32_e32 v37, v1
	v_lshl_add_u64 v[38:39], v[4:5], 0, v[36:37]
	s_add_i32 s0, s43, -11
	s_add_i32 s1, s42, 11
	global_load_dword v59, v[38:39], off nt
	v_mov_b32_e32 v38, s0
	v_mov_b32_e32 v39, s1
	v_cndmask_b32_e32 v38, v38, v39, vcc
	v_lshlrev_b32_e32 v38, 15, v38
	v_mov_b32_e32 v39, v1
	v_lshl_add_u64 v[40:41], v[4:5], 0, v[38:39]
	s_add_i32 s0, s43, -12
	s_add_i32 s1, s42, 12
	global_load_dword v60, v[40:41], off nt
	v_mov_b32_e32 v40, s0
	v_mov_b32_e32 v41, s1
	v_cndmask_b32_e32 v40, v40, v41, vcc
	v_lshlrev_b32_e32 v40, 15, v40
	v_mov_b32_e32 v41, v1
	v_lshl_add_u64 v[42:43], v[4:5], 0, v[40:41]
	s_add_i32 s0, s43, -13
	s_add_i32 s1, s42, 13
	global_load_dword v61, v[42:43], off nt
	v_mov_b32_e32 v42, s0
	v_mov_b32_e32 v43, s1
	v_cndmask_b32_e32 v42, v42, v43, vcc
	v_lshlrev_b32_e32 v42, 15, v42
	v_mov_b32_e32 v43, v1
	v_lshl_add_u64 v[44:45], v[4:5], 0, v[42:43]
	s_add_i32 s0, s43, -14
	s_add_i32 s1, s42, 14
	global_load_dword v62, v[44:45], off nt
	v_mov_b32_e32 v44, s0
	v_mov_b32_e32 v45, s1
	v_cndmask_b32_e32 v44, v44, v45, vcc
	v_lshlrev_b32_e32 v44, 15, v44
	v_mov_b32_e32 v45, v1
	v_lshl_add_u64 v[46:47], v[4:5], 0, v[44:45]
	s_add_i32 s0, s43, -15
	s_add_i32 s1, s42, 15
	global_load_dword v63, v[46:47], off nt
	v_mov_b32_e32 v46, s0
	v_mov_b32_e32 v47, s1
	v_cndmask_b32_e32 v46, v46, v47, vcc
	v_lshlrev_b32_e32 v46, 15, v46
	v_mov_b32_e32 v47, v1
	v_lshl_add_u64 v[48:49], v[4:5], 0, v[46:47]
	global_load_dword v64, v[48:49], off nt
	v_cvt_pk_bf16_f32 v65, v2, v3
	v_lshl_add_u64 v[48:49], v[6:7], 0, v[0:1]
	global_store_dword v[48:49], v65, off
	s_waitcnt vmcnt(16)
; __device__ __forceinline__ unsigned pk2(float lo, float hi) { return pg8::cvt_pk_bf16(lo, hi); }
; __device__ __forceinline__ float bflo(unsigned w) { return __uint_as_float(w << 16); }
; __device__ __forceinline__ float bfhi(unsigned w) { return __uint_as_float(w & 0xffff0000u); }
; __global__ void __launch_bounds__(512, 2) fwd_mega(Args a) {
;     ...
;                 for (int i = 0; i < 16; ++i) { const int cc = dir ? 63 - (c0 + i) : c0 + i; w[i] = kvw[(size_t)cc * 8192]; }
; #pragma unroll
;                 for (int i = 0; i < 16; ++i) { const int cc = dir ? 63 - (c0 + i) : c0 + i; stw[(size_t)cc * 8192] = pk2(s0, s1); s0 = fmaf(dec, s0, bflo(w[i])); s1 = fmaf(dec, s1, bfhi(w[i])); }
;             }
	v_lshlrev_b32_e32 v48, 16, v33
	v_and_b32_e32 v49, 0xffff0000, v33
	v_pk_fma_f32 v[2:3], v[8:9], v[2:3], v[48:49]
	v_lshl_add_u64 v[10:11], v[6:7], 0, v[10:11]
	v_cvt_pk_bf16_f32 v0, v2, v3
	global_store_dword v[10:11], v0, off
	s_waitcnt vmcnt(16)
	v_lshlrev_b32_e32 v10, 16, v50
	v_and_b32_e32 v11, 0xffff0000, v50
	v_pk_fma_f32 v[2:3], v[8:9], v[2:3], v[10:11]
	v_lshl_add_u64 v[10:11], v[6:7], 0, v[12:13]
	v_cvt_pk_bf16_f32 v0, v2, v3
	global_store_dword v[10:11], v0, off
	s_waitcnt vmcnt(16)
	v_lshlrev_b32_e32 v10, 16, v51
	v_and_b32_e32 v11, 0xffff0000, v51
	v_pk_fma_f32 v[2:3], v[8:9], v[2:3], v[10:11]
	v_lshl_add_u64 v[10:11], v[6:7], 0, v[14:15]
	v_cvt_pk_bf16_f32 v0, v2, v3
	global_store_dword v[10:11], v0, off
	s_waitcnt vmcnt(16)
	v_lshlrev_b32_e32 v10, 16, v52
	v_and_b32_e32 v11, 0xffff0000, v52
	v_pk_fma_f32 v[2:3], v[8:9], v[2:3], v[10:11]
	v_lshl_add_u64 v[10:11], v[6:7], 0, v[16:17]
	v_cvt_pk_bf16_f32 v0, v2, v3
	global_store_dword v[10:11], v0, off
	s_waitcnt vmcnt(16)
	v_lshlrev_b32_e32 v10, 16, v53
	v_and_b32_e32 v11, 0xffff0000, v53
	v_pk_fma_f32 v[2:3], v[8:9], v[2:3], v[10:11]
	v_lshl_add_u64 v[10:11], v[6:7], 0, v[18:19]
	v_cvt_pk_bf16_f32 v0, v2, v3
	global_store_dword v[10:11], v0, off
	s_waitcnt vmcnt(16)
	v_lshlrev_b32_e32 v10, 16, v54
	v_and_b32_e32 v11, 0xffff0000, v54
	s_waitcnt vmcnt(15)
	v_lshlrev_b32_e32 v14, 16, v55
	v_and_b32_e32 v15, 0xffff0000, v55
	v_pk_fma_f32 v[2:3], v[8:9], v[2:3], v[10:11]
	v_lshl_add_u64 v[12:13], v[6:7], 0, v[20:21]
	s_waitcnt vmcnt(14)
	v_lshlrev_b32_e32 v18, 16, v56
	v_and_b32_e32 v19, 0xffff0000, v56
	v_cvt_pk_bf16_f32 v0, v2, v3
	v_pk_fma_f32 v[2:3], v[8:9], v[2:3], v[14:15]
	v_lshl_add_u64 v[16:17], v[6:7], 0, v[22:23]
	s_waitcnt vmcnt(13)
	v_lshlrev_b32_e32 v22, 16, v57
	v_and_b32_e32 v23, 0xffff0000, v57
	global_store_dword v[12:13], v0, off
	v_cvt_pk_bf16_f32 v0, v2, v3
	v_pk_fma_f32 v[2:3], v[8:9], v[2:3], v[18:19]
	v_lshl_add_u64 v[20:21], v[6:7], 0, v[24:25]
	v_lshl_add_u64 v[24:25], v[6:7], 0, v[34:35]
	s_waitcnt vmcnt(13)
	v_lshlrev_b32_e32 v34, 16, v58
	v_and_b32_e32 v35, 0xffff0000, v58
	global_store_dword v[16:17], v0, off
	v_cvt_pk_bf16_f32 v0, v2, v3
	v_pk_fma_f32 v[2:3], v[8:9], v[2:3], v[22:23]
	s_waitcnt vmcnt(13)
	v_lshlrev_b32_e32 v48, 16, v59
	v_and_b32_e32 v49, 0xffff0000, v59
	global_store_dword v[20:21], v0, off
	v_cvt_pk_bf16_f32 v0, v2, v3
	v_pk_fma_f32 v[2:3], v[8:9], v[2:3], v[34:35]
	v_lshl_add_u64 v[36:37], v[6:7], 0, v[36:37]
	s_waitcnt vmcnt(13)
	v_lshlrev_b32_e32 v50, 16, v60
	v_and_b32_e32 v51, 0xffff0000, v60
	global_store_dword v[24:25], v0, off
	v_cvt_pk_bf16_f32 v0, v2, v3
	v_pk_fma_f32 v[2:3], v[8:9], v[2:3], v[48:49]
	v_lshl_add_u64 v[38:39], v[6:7], 0, v[38:39]
	s_waitcnt vmcnt(13)
	v_lshlrev_b32_e32 v52, 16, v61
	v_and_b32_e32 v53, 0xffff0000, v61
	global_store_dword v[36:37], v0, off
	v_cvt_pk_bf16_f32 v0, v2, v3
	v_pk_fma_f32 v[2:3], v[8:9], v[2:3], v[50:51]
	v_lshl_add_u64 v[40:41], v[6:7], 0, v[40:41]
	s_waitcnt vmcnt(13)
	v_lshlrev_b32_e32 v54, 16, v62
	v_and_b32_e32 v55, 0xffff0000, v62
	global_store_dword v[38:39], v0, off
	v_cvt_pk_bf16_f32 v0, v2, v3
	v_pk_fma_f32 v[2:3], v[8:9], v[2:3], v[52:53]
	v_lshl_add_u64 v[42:43], v[6:7], 0, v[42:43]
	s_waitcnt vmcnt(13)
	v_lshlrev_b32_e32 v56, 16, v63
	v_and_b32_e32 v57, 0xffff0000, v63
	global_store_dword v[40:41], v0, off
	v_cvt_pk_bf16_f32 v0, v2, v3
	v_pk_fma_f32 v[2:3], v[8:9], v[2:3], v[54:55]
	v_lshl_add_u64 v[44:45], v[6:7], 0, v[44:45]
	s_waitcnt vmcnt(13)
	v_lshlrev_b32_e32 v58, 16, v64
	v_and_b32_e32 v59, 0xffff0000, v64
	global_store_dword v[42:43], v0, off
	v_cvt_pk_bf16_f32 v0, v2, v3
	v_pk_fma_f32 v[2:3], v[8:9], v[2:3], v[56:57]
	s_add_i32 s43, s43, -16
	s_add_i32 s0, s42, 16
	v_lshl_add_u64 v[46:47], v[6:7], 0, v[46:47]
	global_store_dword v[44:45], v0, off
	v_cvt_pk_bf16_f32 v0, v2, v3
	v_pk_fma_f32 v[2:3], v[8:9], v[2:3], v[58:59]
	s_cmp_lt_u32 s42, 48
	s_mov_b32 s42, s0
	global_store_dword v[46:47], v0, off
	s_cbranch_scc1 .LBB0_378
	v_add_u32_e32 v26, s3, v26
	v_cmp_lt_i32_e32 vcc, s41, v26
	s_or_b64 s[10:11], vcc, s[10:11]
	s_andn2_b64 exec, exec, s[10:11]
	s_cbranch_execnz .LBB0_377

; #define LAS __attribute__((address_space(3)))
; __device__ __forceinline__ u32x4 ws_load16(const WsRef& w, unsigned byte_off) { return __builtin_bit_cast(u32x4, __builtin_amdgcn_raw_buffer_load_b128(w.r, byte_off, 0, 0)); }
; __device__ __forceinline__ float log_sigmoid(float x) { return -log1pf(expf(-x)); }
; __device__ __forceinline__ void ret_unit(LAS unsigned char* lds, int u, const bf16* PROJ, const int* pos, const float* dec_f, const float* dec_b, const bf16* ST,
;                                          const float* gn_w, const float* gn_b, bf16* MIX, int tid, const WsRef& wsr) {
;     ...
;     const int bh = u >> 6, c = u & 63, b = bh >> 2, h = bh & 3;
;     const size_t row0 = (size_t)b * SEQ + (size_t)c * 128;
;     LAS bf16* Qs = (LAS bf16*)lds; LAS bf16* Ks = (LAS bf16*)(lds + TILE_B); LAS bf16* VT = (LAS bf16*)(lds + 2 * TILE_B);
;     const float lgf2 = log_sigmoid(dec_f[h]) * LOG2E, lgb2 = log_sigmoid(dec_b[h]) * LOG2E;
;     const u32x4* sfp = (const u32x4*)(ST + ((size_t)bh * 64 + c) * 16384); const u32x4* sbp = (const u32x4*)(ST + ((size_t)(8 + bh) * 64 + c) * 16384);
;     u32x4 sf[4], sb[4];
; #pragma unroll
;     for (int i = 0; i < 4; ++i) { sf[i] = sfp[tid + 512 * i]; sb[i] = sbp[tid + 512 * i]; }
;     u32x4 rq1[2], rq2[2], rk1[2], rk2[2], rv[4]; float rp[2];
; #pragma unroll
;     for (int ii = 0; ii < 2; ++ii) { const int it = tid + 512 * ii, dc = it & 7, j = it >> 3; const unsigned qo = (unsigned)WS_PROJ + (unsigned)(((unsigned)(row0 + j) * INC + h * 128 + dc * 8) * 2u);
;         rq1[ii] = ws_load16(wsr, qo); rq2[ii] = ws_load16(wsr, qo + 128u); rk1[ii] = ws_load16(wsr, qo + 1024u); rk2[ii] = ws_load16(wsr, qo + 1152u); rp[ii] = (float)pos[row0 + j]; }
.LBB0_438:
	s_ashr_i32 s0, s73, 6
	s_and_b32 s80, s0, 3
	s_lshl_b32 s1, s80, 2
	v_mov_b32_e32 v86, s1
	global_load_dword v68, v86, s[18:19]
	global_load_dword v87, v86, s[20:21]
	s_and_b32 s82, s73, 63
	s_ashr_i32 s4, s73, 8
	s_ashr_i32 s5, s4, 31
	s_lshl_b32 s81, s82, 7
	s_ashr_i32 s1, s0, 31
	s_lshl_b64 s[0:1], s[0:1], 21
	s_add_u32 s0, s54, s0
	s_addc_u32 s1, s55, s1
	s_mov_b32 s88, s84
	s_movk_i32 s8, 0x2000
	s_lshl_b32 s68, s82, 15
	s_add_u32 s0, s0, s68
	s_addc_u32 s1, s1, 0
	s_add_u32 s82, s0, 0x1000000
	v_lshl_add_u64 v[2:3], s[0:1], 0, v[96:97]
	s_addc_u32 s83, s1, 0
	v_add_co_u32_e64 v8, s[68:69], s8, v2
	v_lshl_add_u64 v[28:29], s[82:83], 0, v[96:97]
	s_nop 0
	v_addc_co_u32_e64 v9, s[68:69], 0, v3, s[68:69]
	v_add_co_u32_e64 v16, s[68:69], s8, v28
	global_load_dwordx4 v[4:7], v96, s[0:1] nt
	global_load_dwordx4 v[12:15], v96, s[82:83] nt
	v_addc_co_u32_e64 v17, s[68:69], 0, v29, s[68:69]
	global_load_dwordx4 v[8:11], v[8:9], off nt
	s_nop 0
	global_load_dwordx4 v[16:19], v[16:17], off nt
	s_nop 0
	global_load_dwordx4 v[24:27], v224, s[0:1] nt
	global_load_dwordx4 v[20:23], v224, s[82:83] nt
	s_movk_i32 s0, 0x6000
	v_add_co_u32_e64 v2, s[68:69], s0, v2
	s_lshl_b64 s[4:5], s[4:5], 13
	s_nop 0
	v_addc_co_u32_e64 v3, s[68:69], 0, v3, s[68:69]
	global_load_dwordx4 v[32:35], v[2:3], off nt
	v_add_co_u32_e64 v2, s[68:69], s0, v28
	s_or_b32 s4, s4, s81
	s_nop 0
	v_addc_co_u32_e64 v3, s[68:69], 0, v29, s[68:69]
	s_lshl_b32 s0, s80, 7
	v_or_b32_e32 v0, s4, v98
	global_load_dwordx4 v[36:39], v[2:3], off nt
	v_or_b32_e32 v2, s0, v106
	v_mul_lo_u32 v3, v0, s9
	v_mov_b32_e32 v1, s5
	v_or_b32_e32 v3, v3, v2
	v_lshl_add_u32 v3, v3, 1, v229
	v_lshl_add_u64 v[0:1], v[0:1], 2, s[12:13]
	buffer_load_dwordx4 v[50:53], v3, s[88:91], 0 offen nt
	buffer_load_dwordx4 v[54:57], v3, s[88:91], 0 offen offset:128 nt
	buffer_load_dwordx4 v[58:61], v3, s[88:91], 0 offen offset:1024 nt
	buffer_load_dwordx4 v[62:65], v3, s[88:91], 0 offen offset:1152 nt
	v_lshl_add_u64 v[66:67], s[4:5], 0, v[100:101]
	global_load_dword v0, v[0:1], off
	s_waitcnt vmcnt(13)
	s_add_i32 s101, s80, 1
	s_cmp_eq_u32 s100, s101
	s_cbranch_scc0 .Lp4_log
	v_mov_b32_e32 v48, s98
	v_mov_b32_e32 v105, s99
	s_branch .Lp4_logdone

; __device__ __forceinline__ unsigned pk2(float lo, float hi) { return pg8::cvt_pk_bf16(lo, hi); }
; __device__ __forceinline__ float bflo(unsigned w) { return __uint_as_float(w << 16); }
; __device__ __forceinline__ float bfhi(unsigned w) { return __uint_as_float(w & 0xffff0000u); }
; __device__ __forceinline__ u32x4 ws_load16(const WsRef& w, unsigned byte_off) { return __builtin_bit_cast(u32x4, __builtin_amdgcn_raw_buffer_load_b128(w.r, byte_off, 0, 0)); }
; __device__ __forceinline__ float fexp2(float x) { return __builtin_amdgcn_exp2f(x); }
; __device__ __forceinline__ void ret_unit(LAS unsigned char* lds, int u, const bf16* PROJ, const int* pos, const float* dec_f, const float* dec_b, const bf16* ST,
;                                          const float* gn_w, const float* gn_b, bf16* MIX, int tid, const WsRef& wsr) {
;     ...
;     for (int ii = 0; ii < 2; ++ii) { const int it = tid + 512 * ii, dc = it & 7, j = it >> 3; const unsigned qo = (unsigned)WS_PROJ + (unsigned)(((unsigned)(row0 + j) * INC + h * 128 + dc * 8) * 2u);
;         rq1[ii] = ws_load16(wsr, qo); rq2[ii] = ws_load16(wsr, qo + 128u); rk1[ii] = ws_load16(wsr, qo + 1024u); rk2[ii] = ws_load16(wsr, qo + 1152u); rp[ii] = (float)pos[row0 + j]; }
; #pragma unroll
;     for (int ii = 0; ii < 2; ++ii) { const int it = tid + 512 * ii, dc = it & 7, j = it >> 3;
;         const u32x4 q1 = rq1[ii], q2 = rq2[ii], k1 = rk1[ii], k2 = rk2[ii];
;         const float p = rp[ii];
;         float sn[8], cs[8];
; #pragma unroll
;         for (int e = 0; e < 8; ++e) { const int i = dc * 8 + e; const float inv = fexp2(-(float)i * 0.20762050593046015f); fast_sincos(p * inv, sn[e], cs[e]); }
;         u32x4 oq1, oq2, ok1, ok2;
; #pragma unroll
;         for (int e = 0; e < 4; ++e) { const int e0 = 2 * e, e1 = 2 * e + 1;
;             const float a0 = bflo(q1[e]), a1 = bfhi(q1[e]), b0 = bflo(q2[e]), b1 = bfhi(q2[e]);
;             oq1[e] = pk2(a0 * cs[e0] - b0 * sn[e0], a1 * cs[e1] - b1 * sn[e1]); oq2[e] = pk2(b0 * cs[e0] + a0 * sn[e0], b1 * cs[e1] + a1 * sn[e1]);
;             const float c0 = bflo(k1[e]) * 0.08838834764831845f, c1 = bfhi(k1[e]) * 0.08838834764831845f, d0 = bflo(k2[e]) * 0.08838834764831845f, d1 = bfhi(k2[e]) * 0.08838834764831845f;
;             ok1[e] = pk2(c0 * cs[e0] - d0 * sn[e0], c1 * cs[e1] - d1 * sn[e1]); ok2[e] = pk2(d0 * cs[e0] + c0 * sn[e0], d1 * cs[e1] + c1 * sn[e1]); }
.Lp4_logdone:
	v_mul_f32_e32 v230, 0xbfb8aa3b, v48
	v_cndmask_b32_e64 v89, v105, v230, s[30:31]
	v_cndmask_b32_e64 v94, v105, v230, s[56:57]
	v_cndmask_b32_e64 v95, v105, v230, s[58:59]
	v_mul_f32_e32 v89, v89, v137
	v_cndmask_b32_e64 v92, v105, v230, s[74:75]
	v_cndmask_b32_e64 v93, v105, v230, s[76:77]
	v_mul_f32_e32 v94, v94, v142
	v_mul_f32_e32 v95, v95, v143
	v_exp_f32_e32 v89, v89
	v_mul_f32_e32 v92, v92, v140
	v_mul_f32_e32 v93, v93, v141
	v_exp_f32_e32 v94, v94
	v_exp_f32_e32 v95, v95
	v_exp_f32_e32 v92, v92
	v_exp_f32_e32 v93, v93
	v_cndmask_b32_e64 v130, v105, v230, s[60:61]
	v_cndmask_b32_e64 v131, v105, v230, s[62:63]
	v_cndmask_b32_e64 v48, v105, v230, s[42:43]
	v_mul_f32_e32 v130, v130, v144
	v_mul_f32_e32 v131, v131, v145
	v_mul_f32_e32 v48, v48, v127
	v_exp_f32_e32 v130, v130
	v_exp_f32_e32 v131, v131
	v_exp_f32_e32 v48, v48
	v_cndmask_b32_e64 v90, v105, v230, s[34:35]
	v_cndmask_b32_e64 v91, v105, v230, s[38:39]
	v_mul_f32_e32 v90, v90, v138
	v_mul_f32_e32 v91, v91, v139
	v_exp_f32_e32 v90, v90
	v_exp_f32_e32 v91, v91
	v_cndmask_b32_e64 v238, v105, v230, s[94:95]
	v_mul_f32_e32 v238, v238, v154
	v_exp_f32_e32 v238, v238
	v_cndmask_b32_e64 v234, v105, v230, s[78:79]
	v_cndmask_b32_e64 v235, v105, v230, s[2:3]
	v_cndmask_b32_e64 v236, v105, v230, s[92:93]
	v_cndmask_b32_e32 v237, v105, v230, vcc
	v_mul_f32_e32 v234, v234, v150
	v_mul_f32_e32 v235, v235, v151
	v_mul_f32_e32 v236, v236, v152
	v_mul_f32_e32 v237, v237, v153
	v_exp_f32_e32 v234, v234
	v_exp_f32_e32 v235, v235
	v_exp_f32_e32 v236, v236
	v_exp_f32_e32 v237, v237
	v_cndmask_b32_e64 v132, v105, v230, s[64:65]
	v_cndmask_b32_e64 v133, v105, v230, s[14:15]
	v_cndmask_b32_e64 v232, v105, v230, s[16:17]
	v_cndmask_b32_e64 v233, v105, v230, s[24:25]
	v_mul_f32_e32 v132, v132, v146
	v_mul_f32_e32 v133, v133, v147
	v_mul_f32_e32 v232, v232, v148
	v_mul_f32_e32 v233, v233, v149
	v_exp_f32_e32 v132, v132
	v_exp_f32_e32 v133, v133
	v_exp_f32_e32 v232, v232
	v_exp_f32_e32 v233, v233
	s_mov_b32 s1, 0x800000
	s_add_i32 s73, s73, s40
	s_cmpk_lt_i32 s73, 0x200
	s_waitcnt vmcnt(4)
	v_lshlrev_b32_e32 v82, 16, v50
	s_waitcnt vmcnt(3)
	v_lshlrev_b32_e32 v84, 16, v54
	v_and_b32_e32 v85, 0xffff0000, v54
	v_and_b32_e32 v83, 0xffff0000, v50
	s_waitcnt vmcnt(0)
	v_cvt_f32_i32_e32 v49, v0
	v_mul_lo_u32 v0, v66, s9
	v_or_b32_e32 v0, v0, v2
	v_lshl_add_u32 v0, v0, 1, v229
	v_lshl_add_u64 v[66:67], v[66:67], 2, s[12:13]
	buffer_load_dwordx4 v[44:47], v0, s[88:91], 0 offen nt
	buffer_load_dwordx4 v[40:43], v0, s[88:91], 0 offen offset:128 nt
	buffer_load_dwordx4 v[28:31], v0, s[88:91], 0 offen offset:1024 nt
	s_nop 0
	buffer_load_dwordx4 v[0:3], v0, s[88:91], 0 offen offset:1152 nt
	v_mul_f32_e32 v70, v109, v49
	global_load_dword v66, v[66:67], off
	v_mul_f32_e32 v71, 0.15915494, v70
	v_rndne_f32_e32 v71, v71
	v_fmac_f32_e32 v70, 0xc0c90000, v71
	v_fmac_f32_e32 v70, 0xbafdaa22, v71
	v_mul_f32_e32 v71, 0.15915494, v70
	v_sin_f32_e32 v70, v71
	v_cos_f32_e32 v72, v71
	v_mul_f32_e32 v71, v110, v49
	v_mul_f32_e32 v73, 0.15915494, v71
	v_mul_f32_e32 v74, v111, v49
	v_rndne_f32_e32 v73, v73
	v_mul_f32_e32 v75, 0.15915494, v74
	v_fmac_f32_e32 v71, 0xc0c90000, v73
	v_rndne_f32_e32 v75, v75
	v_fmac_f32_e32 v71, 0xbafdaa22, v73
	v_fmac_f32_e32 v74, 0xc0c90000, v75
	v_mul_f32_e32 v73, 0.15915494, v71
	v_fmac_f32_e32 v74, 0xbafdaa22, v75
	v_sin_f32_e32 v71, v73
	v_mul_f32_e32 v75, 0.15915494, v74
	v_cos_f32_e32 v73, v73
	v_sin_f32_e32 v74, v75
	v_cos_f32_e32 v76, v75
	v_mul_f32_e32 v75, v112, v49
	v_mul_f32_e32 v77, 0.15915494, v75
	v_rndne_f32_e32 v77, v77
	v_mul_f32_e32 v78, v113, v49
	v_fmac_f32_e32 v75, 0xc0c90000, v77
	v_mul_f32_e32 v79, 0.15915494, v78
	v_fmac_f32_e32 v75, 0xbafdaa22, v77
	v_rndne_f32_e32 v79, v79
	v_mul_f32_e32 v77, 0.15915494, v75
	v_fmac_f32_e32 v78, 0xc0c90000, v79
	v_sin_f32_e32 v75, v77
	v_fmac_f32_e32 v78, 0xbafdaa22, v79
	v_cos_f32_e32 v77, v77
	v_mul_f32_e32 v79, 0.15915494, v78
	v_sin_f32_e32 v78, v79
	v_cos_f32_e32 v80, v79
	s_waitcnt vmcnt(0)
	v_cvt_f32_i32_e32 v88, v66
	v_mul_f32_e32 v66, v107, v49
	v_mul_f32_e32 v67, 0.15915494, v66
	v_rndne_f32_e32 v67, v67
	v_fmac_f32_e32 v66, 0xc0c90000, v67
	v_fmac_f32_e32 v66, 0xbafdaa22, v67
	v_mul_f32_e32 v67, 0.15915494, v66
	v_sin_f32_e32 v66, v67
	v_cos_f32_e32 v68, v67
	v_mul_f32_e32 v67, v108, v49
	v_mul_f32_e32 v69, 0.15915494, v67
	v_rndne_f32_e32 v69, v69
	v_fmac_f32_e32 v67, 0xc0c90000, v69
	v_fmac_f32_e32 v67, 0xbafdaa22, v69
	v_mul_f32_e32 v69, 0.15915494, v67
	v_sin_f32_e32 v67, v69
	v_cos_f32_e32 v69, v69
	v_mul_f32_e32 v49, v114, v49
	v_mul_f32_e32 v79, 0.15915494, v49
	v_pk_mul_f32 v[86:87], v[66:67], v[84:85]
	v_rndne_f32_e32 v79, v79
	v_pk_fma_f32 v[86:87], v[68:69], v[82:83], v[86:87] neg_lo:[0,0,1] neg_hi:[0,0,1]
	v_pk_mul_f32 v[82:83], v[66:67], v[82:83]
	v_cvt_pk_bf16_f32 v50, v86, v87
	v_pk_fma_f32 v[82:83], v[68:69], v[84:85], v[82:83]
	v_lshlrev_b32_e32 v84, 16, v62
	v_cvt_pk_bf16_f32 v54, v82, v83
	v_lshlrev_b32_e32 v82, 16, v58
	v_and_b32_e32 v83, 0xffff0000, v58
	v_and_b32_e32 v85, 0xffff0000, v62
	v_pk_mul_f32 v[82:83], v[82:83], s[10:11] op_sel_hi:[1,0]
	v_pk_mul_f32 v[84:85], v[84:85], s[10:11] op_sel_hi:[1,0]
	v_fmac_f32_e32 v49, 0xc0c90000, v79
	v_pk_mul_f32 v[86:87], v[84:85], v[66:67]
	v_pk_mul_f32 v[66:67], v[82:83], v[66:67]
	v_pk_fma_f32 v[86:87], v[82:83], v[68:69], v[86:87] neg_lo:[0,0,1] neg_hi:[0,0,1]
	v_pk_fma_f32 v[66:67], v[84:85], v[68:69], v[66:67]
	v_lshlrev_b32_e32 v68, 16, v55
	v_and_b32_e32 v69, 0xffff0000, v55
	v_cvt_pk_bf16_f32 v62, v66, v67
	v_lshlrev_b32_e32 v66, 16, v51
	v_and_b32_e32 v67, 0xffff0000, v51
	v_pk_mul_f32 v[82:83], v[70:71], v[68:69]
	v_fmac_f32_e32 v49, 0xbafdaa22, v79
; #define LAS __attribute__((address_space(3)))
; __device__ __forceinline__ unsigned pk2(float lo, float hi) { return pg8::cvt_pk_bf16(lo, hi); }
; __device__ __forceinline__ float bflo(unsigned w) { return __uint_as_float(w << 16); }
; __device__ __forceinline__ float bfhi(unsigned w) { return __uint_as_float(w & 0xffff0000u); }
; __device__ __forceinline__ float fexp2(float x) { return __builtin_amdgcn_exp2f(x); }
; __device__ __forceinline__ void ret_unit(LAS unsigned char* lds, int u, const bf16* PROJ, const int* pos, const float* dec_f, const float* dec_b, const bf16* ST,
;                                          const float* gn_w, const float* gn_b, bf16* MIX, int tid, const WsRef& wsr) {
;     ...
;     for (int ii = 0; ii < 2; ++ii) { const int it = tid + 512 * ii, dc = it & 7, j = it >> 3;
;         const u32x4 q1 = rq1[ii], q2 = rq2[ii], k1 = rk1[ii], k2 = rk2[ii];
;         const float p = rp[ii];
;         float sn[8], cs[8];
; #pragma unroll
;         for (int e = 0; e < 8; ++e) { const int i = dc * 8 + e; const float inv = fexp2(-(float)i * 0.20762050593046015f); fast_sincos(p * inv, sn[e], cs[e]); }
;         u32x4 oq1, oq2, ok1, ok2;
; #pragma unroll
;         for (int e = 0; e < 4; ++e) { const int e0 = 2 * e, e1 = 2 * e + 1;
;             const float a0 = bflo(q1[e]), a1 = bfhi(q1[e]), b0 = bflo(q2[e]), b1 = bfhi(q2[e]);
;             oq1[e] = pk2(a0 * cs[e0] - b0 * sn[e0], a1 * cs[e1] - b1 * sn[e1]); oq2[e] = pk2(b0 * cs[e0] + a0 * sn[e0], b1 * cs[e1] + a1 * sn[e1]);
;             const float c0 = bflo(k1[e]) * 0.08838834764831845f, c1 = bfhi(k1[e]) * 0.08838834764831845f, d0 = bflo(k2[e]) * 0.08838834764831845f, d1 = bfhi(k2[e]) * 0.08838834764831845f;
;             ok1[e] = pk2(c0 * cs[e0] - d0 * sn[e0], c1 * cs[e1] - d1 * sn[e1]); ok2[e] = pk2(d0 * cs[e0] + c0 * sn[e0], d1 * cs[e1] + c1 * sn[e1]); }
;         *(LAS u32x4*)(Qs + j * LDT + dc * 8) = oq1; *(LAS u32x4*)(Qs + j * LDT + 64 + dc * 8) = oq2;
;         *(LAS u32x4*)(Ks + j * LDT + dc * 8) = ok1; *(LAS u32x4*)(Ks + j * LDT + 64 + dc * 8) = ok2; }
	v_pk_fma_f32 v[82:83], v[72:73], v[66:67], v[82:83] neg_lo:[0,0,1] neg_hi:[0,0,1]
	v_pk_mul_f32 v[66:67], v[70:71], v[66:67]
	v_cvt_pk_bf16_f32 v51, v82, v83
	v_pk_fma_f32 v[66:67], v[72:73], v[68:69], v[66:67]
	v_lshlrev_b32_e32 v68, 16, v63
	v_and_b32_e32 v69, 0xffff0000, v63
	v_cvt_pk_bf16_f32 v55, v66, v67
	v_lshlrev_b32_e32 v66, 16, v59
	v_and_b32_e32 v67, 0xffff0000, v59
	v_pk_mul_f32 v[68:69], v[68:69], s[10:11] op_sel_hi:[1,0]
	v_pk_mul_f32 v[66:67], v[66:67], s[10:11] op_sel_hi:[1,0]
	v_pk_mul_f32 v[82:83], v[68:69], v[70:71]
	v_mul_f32_e32 v49, 0.15915494, v49
	v_pk_fma_f32 v[82:83], v[66:67], v[72:73], v[82:83] neg_lo:[0,0,1] neg_hi:[0,0,1]
	v_pk_mul_f32 v[66:67], v[66:67], v[70:71]
	v_sin_f32_e32 v79, v49
	v_pk_fma_f32 v[66:67], v[68:69], v[72:73], v[66:67]
	v_lshlrev_b32_e32 v68, 16, v56
	v_and_b32_e32 v69, 0xffff0000, v56
	v_cvt_pk_bf16_f32 v63, v66, v67
	v_lshlrev_b32_e32 v66, 16, v52
	v_and_b32_e32 v67, 0xffff0000, v52
	v_pk_mul_f32 v[70:71], v[74:75], v[68:69]
	v_cos_f32_e32 v81, v49
	v_pk_fma_f32 v[70:71], v[76:77], v[66:67], v[70:71] neg_lo:[0,0,1] neg_hi:[0,0,1]
	v_pk_mul_f32 v[66:67], v[74:75], v[66:67]
	v_cvt_pk_bf16_f32 v52, v70, v71
	v_pk_fma_f32 v[66:67], v[76:77], v[68:69], v[66:67]
	v_lshlrev_b32_e32 v68, 16, v64
	v_and_b32_e32 v69, 0xffff0000, v64
	v_cvt_pk_bf16_f32 v56, v66, v67
	v_lshlrev_b32_e32 v66, 16, v60
	v_and_b32_e32 v67, 0xffff0000, v60
	v_pk_mul_f32 v[68:69], v[68:69], s[10:11] op_sel_hi:[1,0]
	v_pk_mul_f32 v[66:67], v[66:67], s[10:11] op_sel_hi:[1,0]
	v_pk_mul_f32 v[70:71], v[68:69], v[74:75]
	v_mul_f32_e32 v49, v107, v88
	v_pk_fma_f32 v[70:71], v[66:67], v[76:77], v[70:71] neg_lo:[0,0,1] neg_hi:[0,0,1]
	v_pk_mul_f32 v[66:67], v[66:67], v[74:75]
	v_cvt_pk_bf16_f32 v60, v70, v71
	v_pk_fma_f32 v[66:67], v[68:69], v[76:77], v[66:67]
	v_lshlrev_b32_e32 v68, 16, v57
	v_and_b32_e32 v69, 0xffff0000, v57
	v_cvt_pk_bf16_f32 v64, v66, v67
	v_lshlrev_b32_e32 v66, 16, v53
	v_and_b32_e32 v67, 0xffff0000, v53
	v_pk_mul_f32 v[70:71], v[78:79], v[68:69]
	v_cvt_pk_bf16_f32 v58, v86, v87
	v_pk_fma_f32 v[70:71], v[80:81], v[66:67], v[70:71] neg_lo:[0,0,1] neg_hi:[0,0,1]
	v_pk_mul_f32 v[66:67], v[78:79], v[66:67]
	v_cvt_pk_bf16_f32 v53, v70, v71
	v_pk_fma_f32 v[66:67], v[80:81], v[68:69], v[66:67]
	v_lshlrev_b32_e32 v68, 16, v65
	v_and_b32_e32 v69, 0xffff0000, v65
	v_cvt_pk_bf16_f32 v57, v66, v67
	v_lshlrev_b32_e32 v66, 16, v61
	v_and_b32_e32 v67, 0xffff0000, v61
	v_pk_mul_f32 v[68:69], v[68:69], s[10:11] op_sel_hi:[1,0]
	v_pk_mul_f32 v[66:67], v[66:67], s[10:11] op_sel_hi:[1,0]
	v_pk_mul_f32 v[70:71], v[68:69], v[78:79]
	v_cvt_pk_bf16_f32 v59, v82, v83
	v_pk_fma_f32 v[70:71], v[66:67], v[80:81], v[70:71] neg_lo:[0,0,1] neg_hi:[0,0,1]
	v_pk_mul_f32 v[66:67], v[66:67], v[78:79]
	v_cvt_pk_bf16_f32 v61, v70, v71
	v_pk_fma_f32 v[66:67], v[68:69], v[80:81], v[66:67]
	v_lshlrev_b32_e32 v68, 16, v40
	v_cvt_pk_bf16_f32 v65, v66, v67
	ds_write_b128 v115, v[50:53]
	ds_write_b128 v115, v[54:57] offset:128
	ds_write_b128 v115, v[58:61] offset:34816
	ds_write_b128 v115, v[62:65] offset:34944
	v_mul_f32_e32 v50, 0.15915494, v49
	v_rndne_f32_e32 v50, v50
	v_fmac_f32_e32 v49, 0xc0c90000, v50
	v_fmac_f32_e32 v49, 0xbafdaa22, v50
	v_mul_f32_e32 v49, 0.15915494, v49
	v_sin_f32_e32 v50, v49
	v_cos_f32_e32 v52, v49
	v_mul_f32_e32 v49, v108, v88
	v_mul_f32_e32 v51, 0.15915494, v49
	v_rndne_f32_e32 v51, v51
	v_fmac_f32_e32 v49, 0xc0c90000, v51
	v_fmac_f32_e32 v49, 0xbafdaa22, v51
	v_mul_f32_e32 v49, 0.15915494, v49
	v_sin_f32_e32 v51, v49
	v_cos_f32_e32 v53, v49
	v_mul_f32_e32 v49, v109, v88
	v_mul_f32_e32 v54, 0.15915494, v49
	v_rndne_f32_e32 v54, v54
	v_fmac_f32_e32 v49, 0xc0c90000, v54
	v_fmac_f32_e32 v49, 0xbafdaa22, v54
	v_mul_f32_e32 v49, 0.15915494, v49
	v_sin_f32_e32 v54, v49
	v_cos_f32_e32 v56, v49
	v_mul_f32_e32 v49, v110, v88
	v_mul_f32_e32 v55, 0.15915494, v49
	v_rndne_f32_e32 v55, v55
	v_fmac_f32_e32 v49, 0xc0c90000, v55
	v_fmac_f32_e32 v49, 0xbafdaa22, v55
	v_mul_f32_e32 v49, 0.15915494, v49
	v_sin_f32_e32 v55, v49
	v_cos_f32_e32 v57, v49
	v_mul_f32_e32 v49, v111, v88
	v_mul_f32_e32 v58, 0.15915494, v49
	v_rndne_f32_e32 v58, v58
	v_fmac_f32_e32 v49, 0xc0c90000, v58
	v_fmac_f32_e32 v49, 0xbafdaa22, v58
	v_mul_f32_e32 v49, 0.15915494, v49
	v_sin_f32_e32 v58, v49
	v_cos_f32_e32 v60, v49
	v_mul_f32_e32 v49, v112, v88
	v_and_b32_e32 v69, 0xffff0000, v40
	v_mul_f32_e32 v59, 0.15915494, v49
	v_lshlrev_b32_e32 v66, 16, v44
	v_and_b32_e32 v67, 0xffff0000, v44
	v_pk_mul_f32 v[70:71], v[50:51], v[68:69]
	v_rndne_f32_e32 v59, v59
	v_pk_fma_f32 v[70:71], v[52:53], v[66:67], v[70:71] neg_lo:[0,0,1] neg_hi:[0,0,1]
	v_pk_mul_f32 v[66:67], v[50:51], v[66:67]
	v_fmac_f32_e32 v49, 0xc0c90000, v59
	v_pk_fma_f32 v[66:67], v[52:53], v[68:69], v[66:67]
	v_fmac_f32_e32 v49, 0xbafdaa22, v59
	v_cvt_pk_bf16_f32 v44, v66, v67
	v_lshlrev_b32_e32 v66, 16, v28
	v_and_b32_e32 v67, 0xffff0000, v28
	v_lshlrev_b32_e32 v68, 16, v0
	v_and_b32_e32 v69, 0xffff0000, v0
	v_mul_f32_e32 v49, 0.15915494, v49
	v_pk_mul_f32 v[66:67], v[66:67], s[10:11] op_sel_hi:[1,0]
	v_pk_mul_f32 v[68:69], v[68:69], s[10:11] op_sel_hi:[1,0]
	v_sin_f32_e32 v59, v49
	v_cos_f32_e32 v61, v49
	v_mul_f32_e32 v49, v113, v88
	v_cvt_pk_bf16_f32 v40, v70, v71
	v_pk_mul_f32 v[70:71], v[68:69], v[50:51]
	v_pk_mul_f32 v[50:51], v[66:67], v[50:51]
	v_mul_f32_e32 v62, 0.15915494, v49
	v_pk_fma_f32 v[70:71], v[66:67], v[52:53], v[70:71] neg_lo:[0,0,1] neg_hi:[0,0,1]
	v_pk_fma_f32 v[50:51], v[68:69], v[52:53], v[50:51]
	v_lshlrev_b32_e32 v52, 16, v41
	v_and_b32_e32 v53, 0xffff0000, v41
	v_rndne_f32_e32 v62, v62
	v_cvt_pk_bf16_f32 v28, v50, v51
	v_lshlrev_b32_e32 v50, 16, v45
	v_and_b32_e32 v51, 0xffff0000, v45
; #define LAS __attribute__((address_space(3)))
; __device__ __forceinline__ unsigned pk2(float lo, float hi) { return pg8::cvt_pk_bf16(lo, hi); }
; __device__ __forceinline__ float bflo(unsigned w) { return __uint_as_float(w << 16); }
; __device__ __forceinline__ float bfhi(unsigned w) { return __uint_as_float(w & 0xffff0000u); }
; __device__ __forceinline__ u32x4 ws_load16(const WsRef& w, unsigned byte_off) { return __builtin_bit_cast(u32x4, __builtin_amdgcn_raw_buffer_load_b128(w.r, byte_off, 0, 0)); }
; __device__ __forceinline__ void ret_unit(LAS unsigned char* lds, int u, const bf16* PROJ, const int* pos, const float* dec_f, const float* dec_b, const bf16* ST,
;                                          const float* gn_w, const float* gn_b, bf16* MIX, int tid, const WsRef& wsr) {
;     ...
;         for (int e = 0; e < 4; ++e) { const int e0 = 2 * e, e1 = 2 * e + 1;
;             const float a0 = bflo(q1[e]), a1 = bfhi(q1[e]), b0 = bflo(q2[e]), b1 = bfhi(q2[e]);
;             oq1[e] = pk2(a0 * cs[e0] - b0 * sn[e0], a1 * cs[e1] - b1 * sn[e1]); oq2[e] = pk2(b0 * cs[e0] + a0 * sn[e0], b1 * cs[e1] + a1 * sn[e1]);
;             const float c0 = bflo(k1[e]) * 0.08838834764831845f, c1 = bfhi(k1[e]) * 0.08838834764831845f, d0 = bflo(k2[e]) * 0.08838834764831845f, d1 = bfhi(k2[e]) * 0.08838834764831845f;
;             ok1[e] = pk2(c0 * cs[e0] - d0 * sn[e0], c1 * cs[e1] - d1 * sn[e1]); ok2[e] = pk2(d0 * cs[e0] + c0 * sn[e0], d1 * cs[e1] + c1 * sn[e1]); }
;         *(LAS u32x4*)(Qs + j * LDT + dc * 8) = oq1; *(LAS u32x4*)(Qs + j * LDT + 64 + dc * 8) = oq2;
;         *(LAS u32x4*)(Ks + j * LDT + dc * 8) = ok1; *(LAS u32x4*)(Ks + j * LDT + 64 + dc * 8) = ok2; }
; #pragma unroll
;     for (int ii = 0; ii < 4; ++ii) { const int it = tid + 512 * ii, ec = it & 15, j = it >> 4; rv[ii] = ws_load16(wsr, (unsigned)WS_PROJ + (unsigned)(((unsigned)(row0 + j) * INC + 1024 + h * 128 + ec * 8) * 2u)); }
; #pragma unroll
;     for (int ii = 0; ii < 4; ++ii) { const int it = tid + 512 * ii, ec = it & 15, j = it >> 4; const u32x4 w = rv[ii];
;         const int jsw = (((j >> 3) ^ (ec & 7)) << 3) | (j & 7);
; #pragma unroll
;         for (int e = 0; e < 4; ++e) { VT[(ec * 8 + 2 * e) * LDT + jsw] = (bf16)(w[e] & 0xffffu); VT[(ec * 8 + 2 * e + 1) * LDT + jsw] = (bf16)(w[e] >> 16); } }
;     __syncthreads();
	v_pk_mul_f32 v[66:67], v[54:55], v[52:53]
	v_fmac_f32_e32 v49, 0xc0c90000, v62
	v_pk_fma_f32 v[66:67], v[56:57], v[50:51], v[66:67] neg_lo:[0,0,1] neg_hi:[0,0,1]
	v_pk_mul_f32 v[50:51], v[54:55], v[50:51]
	v_fmac_f32_e32 v49, 0xbafdaa22, v62
	v_pk_fma_f32 v[50:51], v[56:57], v[52:53], v[50:51]
	v_lshlrev_b32_e32 v52, 16, v1
	v_and_b32_e32 v53, 0xffff0000, v1
	v_mul_f32_e32 v49, 0.15915494, v49
	v_cvt_pk_bf16_f32 v45, v50, v51
	v_lshlrev_b32_e32 v50, 16, v29
	v_and_b32_e32 v51, 0xffff0000, v29
	v_pk_mul_f32 v[52:53], v[52:53], s[10:11] op_sel_hi:[1,0]
	v_sin_f32_e32 v62, v49
	v_cos_f32_e32 v64, v49
	v_mul_f32_e32 v49, v114, v88
	v_cvt_pk_bf16_f32 v41, v66, v67
	v_pk_mul_f32 v[50:51], v[50:51], s[10:11] op_sel_hi:[1,0]
	v_pk_mul_f32 v[66:67], v[52:53], v[54:55]
	v_mul_f32_e32 v63, 0.15915494, v49
	v_pk_fma_f32 v[66:67], v[50:51], v[56:57], v[66:67] neg_lo:[0,0,1] neg_hi:[0,0,1]
	v_pk_mul_f32 v[50:51], v[50:51], v[54:55]
	v_rndne_f32_e32 v63, v63
	v_pk_fma_f32 v[50:51], v[52:53], v[56:57], v[50:51]
	v_lshlrev_b32_e32 v52, 16, v42
	v_and_b32_e32 v53, 0xffff0000, v42
	v_fmac_f32_e32 v49, 0xc0c90000, v63
	v_cvt_pk_bf16_f32 v29, v50, v51
	v_lshlrev_b32_e32 v50, 16, v46
	v_and_b32_e32 v51, 0xffff0000, v46
	v_pk_mul_f32 v[54:55], v[58:59], v[52:53]
	v_fmac_f32_e32 v49, 0xbafdaa22, v63
	v_pk_fma_f32 v[54:55], v[60:61], v[50:51], v[54:55] neg_lo:[0,0,1] neg_hi:[0,0,1]
	v_pk_mul_f32 v[50:51], v[58:59], v[50:51]
	v_mul_f32_e32 v49, 0.15915494, v49
	v_pk_fma_f32 v[50:51], v[60:61], v[52:53], v[50:51]
	v_lshlrev_b32_e32 v52, 16, v2
	v_and_b32_e32 v53, 0xffff0000, v2
	v_sin_f32_e32 v63, v49
	v_cvt_pk_bf16_f32 v46, v50, v51
	v_lshlrev_b32_e32 v50, 16, v30
	v_and_b32_e32 v51, 0xffff0000, v30
	v_pk_mul_f32 v[52:53], v[52:53], s[10:11] op_sel_hi:[1,0]
	v_cos_f32_e32 v65, v49
	v_cvt_pk_bf16_f32 v42, v54, v55
	v_pk_mul_f32 v[50:51], v[50:51], s[10:11] op_sel_hi:[1,0]
	v_pk_mul_f32 v[54:55], v[52:53], v[58:59]
	v_cvt_pk_bf16_f32 v0, v70, v71
	v_pk_fma_f32 v[54:55], v[50:51], v[60:61], v[54:55] neg_lo:[0,0,1] neg_hi:[0,0,1]
	v_pk_mul_f32 v[50:51], v[50:51], v[58:59]
	v_cvt_pk_bf16_f32 v2, v54, v55
	v_pk_fma_f32 v[50:51], v[52:53], v[60:61], v[50:51]
	v_lshlrev_b32_e32 v52, 16, v43
	v_and_b32_e32 v53, 0xffff0000, v43
	v_cvt_pk_bf16_f32 v30, v50, v51
	v_lshlrev_b32_e32 v50, 16, v47
	v_and_b32_e32 v51, 0xffff0000, v47
	v_pk_mul_f32 v[54:55], v[62:63], v[52:53]
	v_cvt_pk_bf16_f32 v1, v66, v67
	v_pk_fma_f32 v[54:55], v[64:65], v[50:51], v[54:55] neg_lo:[0,0,1] neg_hi:[0,0,1]
	v_pk_mul_f32 v[50:51], v[62:63], v[50:51]
	v_cvt_pk_bf16_f32 v43, v54, v55
	v_pk_fma_f32 v[50:51], v[64:65], v[52:53], v[50:51]
	v_lshlrev_b32_e32 v52, 16, v3
	v_and_b32_e32 v53, 0xffff0000, v3
	v_cvt_pk_bf16_f32 v47, v50, v51
	v_lshlrev_b32_e32 v50, 16, v31
	v_and_b32_e32 v51, 0xffff0000, v31
	v_pk_mul_f32 v[52:53], v[52:53], s[10:11] op_sel_hi:[1,0]
	v_pk_mul_f32 v[50:51], v[50:51], s[10:11] op_sel_hi:[1,0]
	v_pk_mul_f32 v[54:55], v[52:53], v[62:63]
	v_add_u32_e32 v49, v124, v125
	v_pk_fma_f32 v[54:55], v[50:51], v[64:65], v[54:55] neg_lo:[0,0,1] neg_hi:[0,0,1]
	v_pk_mul_f32 v[50:51], v[50:51], v[62:63]
	v_cvt_pk_bf16_f32 v3, v54, v55
	v_pk_fma_f32 v[50:51], v[52:53], v[64:65], v[50:51]
	v_cndmask_b32_e64 v86, v105, v230, s[66:67]
	v_cvt_pk_bf16_f32 v31, v50, v51
	ds_write_b128 v116, v[40:43]
	ds_write_b128 v116, v[44:47] offset:128
	ds_write_b128 v116, v[0:3] offset:34816
	ds_write_b128 v116, v[28:31] offset:34944
	v_or_b32_e32 v44, s0, v222
	v_or_b32_e32 v0, s4, v99
	v_mad_u64_u32 v[0:1], s[68:69], v0, s9, v[44:45]
	v_lshl_add_u32 v0, v0, 1, v229
	buffer_load_dwordx4 v[0:3], v0, s[88:91], 0 offen nt
	v_or_b32_e32 v28, s4, v117
	v_mad_u64_u32 v[28:29], s[68:69], v28, s9, v[44:45]
	v_lshl_add_u32 v28, v28, 1, v229
	buffer_load_dwordx4 v[28:31], v28, s[88:91], 0 offen nt
	v_or_b32_e32 v40, s4, v118
	v_mad_u64_u32 v[40:41], s[68:69], v40, s9, v[44:45]
	v_lshl_add_u32 v40, v40, 1, v229
	buffer_load_dwordx4 v[40:43], v40, s[88:91], 0 offen nt
	v_add_u32_e32 v45, s4, v119
	v_mad_u64_u32 v[44:45], s[68:69], v45, s9, v[44:45]
	v_lshl_add_u32 v44, v44, 1, v229
	buffer_load_dwordx4 v[44:47], v44, s[88:91], 0 offen nt
	s_waitcnt vmcnt(3)
	ds_write_b16 v120, v0
	ds_write_b16_d16_hi v120, v0 offset:272
	ds_write_b16 v120, v1 offset:544
	ds_write_b16_d16_hi v120, v1 offset:816
	ds_write_b16 v120, v2 offset:1088
	ds_write_b16_d16_hi v120, v2 offset:1360
	ds_write_b16 v120, v3 offset:1632
	ds_write_b16_d16_hi v120, v3 offset:1904
	s_waitcnt vmcnt(2)
	ds_write_b16 v121, v28
	ds_write_b16_d16_hi v121, v28 offset:272
	ds_write_b16 v121, v29 offset:544
	ds_write_b16_d16_hi v121, v29 offset:816
	ds_write_b16 v121, v30 offset:1088
	ds_write_b16_d16_hi v121, v30 offset:1360
	ds_write_b16 v121, v31 offset:1632
	ds_write_b16_d16_hi v121, v31 offset:1904
	s_waitcnt vmcnt(1)
	ds_write_b16 v122, v40
	ds_write_b16_d16_hi v122, v40 offset:272
	ds_write_b16 v122, v41 offset:544
	ds_write_b16_d16_hi v122, v41 offset:816
	ds_write_b16 v122, v42 offset:1088
	ds_write_b16_d16_hi v122, v42 offset:1360
	ds_write_b16 v122, v43 offset:1632
	ds_write_b16_d16_hi v122, v43 offset:1904
	s_waitcnt vmcnt(0)
	ds_write_b16 v123, v44
	ds_write_b16_d16_hi v123, v44 offset:272
	ds_write_b16 v123, v45 offset:544
	ds_write_b16_d16_hi v123, v45 offset:816
	ds_write_b16 v123, v46 offset:1088
	ds_write_b16_d16_hi v123, v46 offset:1360
	ds_write_b16 v123, v47 offset:1632
	ds_write_b16_d16_hi v123, v47 offset:1904
	s_waitcnt lgkmcnt(0)
	s_barrier
; #define LAS __attribute__((address_space(3)))
; __device__ __forceinline__ unsigned pk2(float lo, float hi) { return pg8::cvt_pk_bf16(lo, hi); }
; __device__ __forceinline__ float fexp2(float x) { return __builtin_amdgcn_exp2f(x); }
; #define MFMA16(a, b, c) __builtin_amdgcn_mfma_f32_16x16x32_bf16((a), (b), (c), 0, 0, 0)
; __device__ __forceinline__ void ret_unit(LAS unsigned char* lds, int u, const bf16* PROJ, const int* pos, const float* dec_f, const float* dec_b, const bf16* ST,
;                                          const float* gn_w, const float* gn_b, bf16* MIX, int tid, const WsRef& wsr) {
;     ...
;     const int q = wave * 16 + fr;
;     bf16x8 qf[4];
; #pragma unroll
;     for (int kk = 0; kk < 4; ++kk) qf[kk] = *(const LAS bf16x8*)(Qs + q * LDT + kk * 32 + fq * 8);
;     f32x4 s[8];
; #pragma unroll
;     for (int n = 0; n < 8; ++n) s[n] = (f32x4){0.f, 0.f, 0.f, 0.f};
; #pragma unroll
;     for (int kk = 0; kk < 4; ++kk)
; #pragma unroll
;         for (int n = 0; n < 8; ++n) { const bf16x8 kf = *(const LAS bf16x8*)(Ks + (n * 16 + fr) * LDT + kk * 32 + fq * 8); s[n] = MFMA16(kf, qf[kk], s[n]); }
;     bf16x8 pf[4];
; #pragma unroll
;     for (int n = 0; n < 8; ++n) {
; #pragma unroll
;         for (int r = 0; r < 4; ++r) { const int key = n * 16 + 4 * fq + r; const int df = q - key; const float f = df >= 0 ? fexp2(lgf2 * (float)df) : fexp2(lgb2 * (float)(-df)); s[n][r] *= f; } }
; #pragma unroll
;     for (int kk = 0; kk < 4; ++kk) { u32x4 w; w.x = pk2(s[2 * kk][0], s[2 * kk][1]); w.y = pk2(s[2 * kk][2], s[2 * kk][3]); w.z = pk2(s[2 * kk + 1][0], s[2 * kk + 1][1]); w.w = pk2(s[2 * kk + 1][2], s[2 * kk + 1][3]);
;         pf[kk] = __builtin_bit_cast(bf16x8, w); }
	ds_read_b128 v[44:47], v225
	ds_read_b128 v[40:43], v225 offset:64
	ds_read_b128 v[28:31], v225 offset:128
	ds_read_b128 v[0:3], v225 offset:192
	ds_read_b128 v[50:53], v226 offset:34816
	ds_read_b128 v[54:57], v226 offset:39168
	ds_read_b128 v[82:85], v226 offset:34880
	s_waitcnt lgkmcnt(2)
	v_mfma_f32_16x16x32_bf16 v[50:53], v[50:53], v[44:47], 0
	ds_read_b128 v[58:61], v226 offset:43520
	ds_read_b128 v[62:65], v226 offset:47872
	ds_read_b128 v[66:69], v226 offset:52224
	s_waitcnt lgkmcnt(3)
	v_mfma_f32_16x16x32_bf16 v[50:53], v[82:85], v[40:43], v[50:53]
	ds_read_b128 v[82:85], v226 offset:39232
	ds_read_b128 v[70:73], v49 offset:34816
	ds_read_b128 v[74:77], v49 offset:39168
	v_mfma_f32_16x16x32_bf16 v[54:57], v[54:57], v[44:47], 0
	ds_read_b128 v[78:81], v49 offset:43520
	v_cndmask_b32_e64 v87, v105, v230, s[26:27]
	v_cndmask_b32_e64 v88, v105, v230, s[28:29]
	s_waitcnt lgkmcnt(3)
	v_mfma_f32_16x16x32_bf16 v[54:57], v[82:85], v[40:43], v[54:57]
	ds_read_b128 v[82:85], v226 offset:43584
	v_mul_f32_e32 v86, v86, v134
	v_mul_f32_e32 v87, v87, v135
	v_mfma_f32_16x16x32_bf16 v[58:61], v[58:61], v[44:47], 0
	v_mul_f32_e32 v88, v88, v136
	v_exp_f32_e32 v86, v86
	v_exp_f32_e32 v87, v87
	s_waitcnt lgkmcnt(0)
	v_mfma_f32_16x16x32_bf16 v[58:61], v[82:85], v[40:43], v[58:61]
	ds_read_b128 v[82:85], v226 offset:47936
	v_exp_f32_e32 v88, v88
	v_readlane_b32 s68, v255, 4
	v_mfma_f32_16x16x32_bf16 v[62:65], v[62:65], v[44:47], 0
	v_readlane_b32 s69, v255, 5
	s_waitcnt lgkmcnt(0)
	v_mfma_f32_16x16x32_bf16 v[62:65], v[82:85], v[40:43], v[62:65]
	ds_read_b128 v[82:85], v226 offset:52288
	v_cndmask_b32_e64 v239, v105, v230, s[68:69]
	v_readlane_b32 s68, v255, 50
	v_mfma_f32_16x16x32_bf16 v[66:69], v[66:69], v[44:47], 0
	v_readlane_b32 s69, v255, 51
	v_mul_f32_e32 v239, v239, v155
	v_exp_f32_e32 v239, v239
	s_waitcnt lgkmcnt(0)
	v_mfma_f32_16x16x32_bf16 v[66:69], v[82:85], v[40:43], v[66:69]
	ds_read_b128 v[82:85], v49 offset:34880
	v_cndmask_b32_e64 v240, v105, v230, s[68:69]
	v_readlane_b32 s68, v255, 52
	v_mfma_f32_16x16x32_bf16 v[70:73], v[70:73], v[44:47], 0
	v_readlane_b32 s69, v255, 53
	v_mul_f32_e32 v240, v240, v156
	v_exp_f32_e32 v240, v240
	s_waitcnt lgkmcnt(0)
	v_mfma_f32_16x16x32_bf16 v[70:73], v[82:85], v[40:43], v[70:73]
	ds_read_b128 v[82:85], v49 offset:39232
	v_cndmask_b32_e64 v241, v105, v230, s[68:69]
	v_readlane_b32 s68, v255, 54
	v_mfma_f32_16x16x32_bf16 v[74:77], v[74:77], v[44:47], 0
	v_readlane_b32 s69, v255, 55
	v_mul_f32_e32 v241, v241, v157
	v_exp_f32_e32 v241, v241
	s_waitcnt lgkmcnt(0)
	v_mfma_f32_16x16x32_bf16 v[74:77], v[82:85], v[40:43], v[74:77]
	ds_read_b128 v[82:85], v49 offset:43584
	v_cndmask_b32_e64 v242, v105, v230, s[68:69]
	v_readlane_b32 s68, v255, 56
	v_mfma_f32_16x16x32_bf16 v[78:81], v[78:81], v[44:47], 0
	v_readlane_b32 s69, v255, 57
	v_mul_f32_e32 v242, v242, v158
	v_exp_f32_e32 v242, v242
	s_waitcnt lgkmcnt(0)
	v_mfma_f32_16x16x32_bf16 v[78:81], v[82:85], v[40:43], v[78:81]
	ds_read_b128 v[82:85], v226 offset:34944
	v_cndmask_b32_e64 v243, v105, v230, s[68:69]
	v_mul_f32_e32 v243, v243, v159
	s_waitcnt lgkmcnt(0)
	v_mfma_f32_16x16x32_bf16 v[50:53], v[82:85], v[28:31], v[50:53]
	ds_read_b128 v[82:85], v226 offset:39296
	v_exp_f32_e32 v243, v243
	s_waitcnt lgkmcnt(0)
	v_mfma_f32_16x16x32_bf16 v[54:57], v[82:85], v[28:31], v[54:57]
	ds_read_b128 v[82:85], v226 offset:43648
	s_waitcnt lgkmcnt(0)
	v_mfma_f32_16x16x32_bf16 v[58:61], v[82:85], v[28:31], v[58:61]
	ds_read_b128 v[82:85], v226 offset:48000
	s_waitcnt lgkmcnt(0)
	v_mfma_f32_16x16x32_bf16 v[62:65], v[82:85], v[28:31], v[62:65]
	ds_read_b128 v[82:85], v226 offset:52352
	s_waitcnt lgkmcnt(0)
	v_mfma_f32_16x16x32_bf16 v[66:69], v[82:85], v[28:31], v[66:69]
	ds_read_b128 v[82:85], v49 offset:34944
	s_waitcnt lgkmcnt(0)
	v_mfma_f32_16x16x32_bf16 v[70:73], v[82:85], v[28:31], v[70:73]
	ds_read_b128 v[82:85], v49 offset:39296
	s_waitcnt lgkmcnt(0)
	v_mfma_f32_16x16x32_bf16 v[74:77], v[82:85], v[28:31], v[74:77]
	ds_read_b128 v[82:85], v49 offset:43648
	s_waitcnt lgkmcnt(0)
	v_mfma_f32_16x16x32_bf16 v[78:81], v[82:85], v[28:31], v[78:81]
	ds_read_b128 v[82:85], v226 offset:35008
	s_waitcnt lgkmcnt(0)
	v_mfma_f32_16x16x32_bf16 v[50:53], v[82:85], v[0:3], v[50:53]
	ds_read_b128 v[82:85], v226 offset:39360
	s_waitcnt lgkmcnt(0)
	v_mfma_f32_16x16x32_bf16 v[54:57], v[82:85], v[0:3], v[54:57]
	ds_read_b128 v[82:85], v226 offset:43712
	s_nop 6
	v_pk_mul_f32 v[56:57], v[86:87], v[56:57]
	s_waitcnt lgkmcnt(0)
	v_mfma_f32_16x16x32_bf16 v[58:61], v[82:85], v[0:3], v[58:61]
	ds_read_b128 v[82:85], v226 offset:48064
	s_nop 6
	v_pk_mul_f32 v[58:59], v[88:89], v[58:59]
	s_waitcnt lgkmcnt(0)
	v_mfma_f32_16x16x32_bf16 v[62:65], v[82:85], v[0:3], v[62:65]
	ds_read_b128 v[82:85], v226 offset:52416
	v_pk_mul_f32 v[88:89], v[90:91], v[60:61]
	s_nop 5
	v_pk_mul_f32 v[64:65], v[94:95], v[64:65]
	s_waitcnt lgkmcnt(0)
	v_mfma_f32_16x16x32_bf16 v[66:69], v[82:85], v[0:3], v[66:69]
	ds_read_b128 v[82:85], v49 offset:35008
	v_pk_mul_f32 v[92:93], v[92:93], v[62:63]
	v_cvt_pk_bf16_f32 v63, v56, v57
	v_cvt_pk_bf16_f32 v56, v58, v59
	v_cvt_pk_bf16_f32 v59, v64, v65
	v_add_u32_e32 v64, v160, v161
	ds_read_b64 v[64:65], v64
	s_waitcnt lgkmcnt(1)
	v_mfma_f32_16x16x32_bf16 v[70:73], v[82:85], v[0:3], v[70:73]
	ds_read_b128 v[82:85], v49 offset:39360
	v_cvt_pk_bf16_f32 v58, v92, v93
	v_add_u32_e32 v92, v175, v170
	ds_read_b64 v[92:93], v92
	s_waitcnt lgkmcnt(1)
	v_mfma_f32_16x16x32_bf16 v[74:77], v[82:85], v[0:3], v[74:77]
	ds_read_b128 v[82:85], v49 offset:43712
	v_add_u32_e32 v94, v175, v171
	ds_read_b64 v[94:95], v94
	s_waitcnt lgkmcnt(1)
; #define LAS __attribute__((address_space(3)))
; __device__ __forceinline__ unsigned pk2(float lo, float hi) { return pg8::cvt_pk_bf16(lo, hi); }
; __device__ __forceinline__ float fexp2(float x) { return __builtin_amdgcn_exp2f(x); }
; #define MFMA16(a, b, c) __builtin_amdgcn_mfma_f32_16x16x32_bf16((a), (b), (c), 0, 0, 0)
; __device__ __forceinline__ void ret_unit(LAS unsigned char* lds, int u, const bf16* PROJ, const int* pos, const float* dec_f, const float* dec_b, const bf16* ST,
;                                          const float* gn_w, const float* gn_b, bf16* MIX, int tid, const WsRef& wsr) {
;     ...
;     bf16x8 pf[4];
; #pragma unroll
;     for (int n = 0; n < 8; ++n) {
; #pragma unroll
;         for (int r = 0; r < 4; ++r) { const int key = n * 16 + 4 * fq + r; const int df = q - key; const float f = df >= 0 ? fexp2(lgf2 * (float)df) : fexp2(lgb2 * (float)(-df)); s[n][r] *= f; } }
; #pragma unroll
;     for (int kk = 0; kk < 4; ++kk) { u32x4 w; w.x = pk2(s[2 * kk][0], s[2 * kk][1]); w.y = pk2(s[2 * kk][2], s[2 * kk][3]); w.z = pk2(s[2 * kk + 1][0], s[2 * kk + 1][1]); w.w = pk2(s[2 * kk + 1][2], s[2 * kk + 1][3]);
;         pf[kk] = __builtin_bit_cast(bf16x8, w); }
;     f32x4 o[8];
; #pragma unroll
;     for (int n = 0; n < 8; ++n) o[n] = (f32x4){0.f, 0.f, 0.f, 0.f};
; #pragma unroll
;     for (int kk = 0; kk < 4; ++kk)
; #pragma unroll
;         for (int n = 0; n < 8; ++n) { const int sw = (2 * n + (fr >> 3)) & 7, jc = kk * 4 + (fq >> 1); const LAS bf16* vr = VT + (n * 16 + fr) * LDT + 4 * (fq & 1);
;             const u32x2 lo = *(const LAS u32x2*)(vr + ((jc ^ sw) << 3)), hi = *(const LAS u32x2*)(vr + (((jc + 2) ^ sw) << 3)); u32x4 w; w.x = lo.x; w.y = lo.y; w.z = hi.x; w.w = hi.y;
;             o[n] = MFMA16(__builtin_bit_cast(bf16x8, w), pf[kk], o[n]); }
	v_mfma_f32_16x16x32_bf16 v[78:81], v[82:85], v[0:3], v[78:81]
	v_cndmask_b32_e64 v49, v105, v230, s[44:45]
	v_cndmask_b32_e64 v82, v105, v230, s[46:47]
	v_cndmask_b32_e64 v83, v105, v230, s[48:49]
	v_mul_f32_e32 v49, v49, v129
	v_mul_f32_e32 v82, v82, v231
	v_mul_f32_e32 v83, v83, v252
	v_exp_f32_e32 v49, v49
	v_exp_f32_e32 v82, v82
	v_exp_f32_e32 v83, v83
	v_pk_mul_f32 v[66:67], v[130:131], v[66:67]
	v_pk_mul_f32 v[48:49], v[48:49], v[50:51]
	v_cndmask_b32_e64 v84, v105, v230, s[50:51]
	v_pk_mul_f32 v[50:51], v[82:83], v[52:53]
	v_cvt_pk_bf16_f32 v52, v66, v67
	v_add_u32_e32 v66, v160, v162
	ds_read_b64 v[66:67], v66
	v_cndmask_b32_e64 v85, v105, v230, s[52:53]
	v_mul_f32_e32 v84, v84, v253
	v_mul_f32_e32 v85, v85, v254
	v_exp_f32_e32 v84, v84
	v_exp_f32_e32 v85, v85
	v_cvt_pk_bf16_f32 v60, v48, v49
	v_cvt_pk_bf16_f32 v61, v50, v51
	v_pk_mul_f32 v[80:81], v[242:243], v[80:81]
	v_pk_mul_f32 v[54:55], v[84:85], v[54:55]
	v_cvt_pk_bf16_f32 v51, v80, v81
	v_cvt_pk_bf16_f32 v62, v54, v55
	v_cvt_pk_bf16_f32 v57, v88, v89
	v_pk_mul_f32 v[78:79], v[240:241], v[78:79]
	s_waitcnt lgkmcnt(0)
	v_mfma_f32_16x16x32_bf16 v[84:87], v[64:67], v[60:63], 0
	v_add_u32_e32 v64, v163, v164
	v_add_u32_e32 v66, v163, v165
	ds_read_b64 v[64:65], v64
	ds_read_b64 v[66:67], v66
	s_waitcnt lgkmcnt(0)
	v_mfma_f32_16x16x32_bf16 v[80:83], v[64:67], v[60:63], 0
	v_add_u32_e32 v64, v166, v167
	v_add_u32_e32 v66, v166, v168
	ds_read_b64 v[64:65], v64
	ds_read_b64 v[66:67], v66
	s_waitcnt lgkmcnt(0)
	v_mfma_f32_16x16x32_bf16 v[88:91], v[64:67], v[60:63], 0
	v_add_u32_e32 v64, v169, v170
	v_add_u32_e32 v66, v169, v171
	ds_read_b64 v[64:65], v64
	ds_read_b64 v[66:67], v66
	v_pk_mul_f32 v[76:77], v[238:239], v[76:77]
	v_cvt_pk_bf16_f32 v50, v78, v79
	v_cvt_pk_bf16_f32 v49, v76, v77
	s_waitcnt lgkmcnt(0)
	v_mfma_f32_16x16x32_bf16 v[76:79], v[64:67], v[60:63], 0
	v_add_u32_e32 v64, v172, v161
	v_add_u32_e32 v66, v172, v162
	ds_read_b64 v[64:65], v64
	ds_read_b64 v[66:67], v66
	v_pk_mul_f32 v[74:75], v[236:237], v[74:75]
	v_pk_mul_f32 v[72:73], v[234:235], v[72:73]
	v_cvt_pk_bf16_f32 v48, v74, v75
	v_cvt_pk_bf16_f32 v55, v72, v73
	s_waitcnt lgkmcnt(0)
	v_mfma_f32_16x16x32_bf16 v[72:75], v[64:67], v[60:63], 0
	v_add_u32_e32 v64, v173, v164
	v_add_u32_e32 v66, v173, v165
	ds_read_b64 v[64:65], v64
	ds_read_b64 v[66:67], v66
	v_pk_mul_f32 v[70:71], v[232:233], v[70:71]
	v_pk_mul_f32 v[68:69], v[132:133], v[68:69]
	v_cvt_pk_bf16_f32 v54, v70, v71
	v_cvt_pk_bf16_f32 v53, v68, v69
	s_waitcnt lgkmcnt(0)
	v_mfma_f32_16x16x32_bf16 v[68:71], v[64:67], v[60:63], 0
	v_add_u32_e32 v64, v174, v167
	v_add_u32_e32 v66, v174, v168
	ds_read_b64 v[64:65], v64
	ds_read_b64 v[66:67], v66
	s_waitcnt lgkmcnt(0)
	v_mfma_f32_16x16x32_bf16 v[64:67], v[64:67], v[60:63], 0
	v_mfma_f32_16x16x32_bf16 v[60:63], v[92:95], v[60:63], 0
	v_add_u32_e32 v92, v160, v176
	v_add_u32_e32 v94, v160, v177
	ds_read_b64 v[92:93], v92
	ds_read_b64 v[94:95], v94
	s_waitcnt lgkmcnt(0)
	v_mfma_f32_16x16x32_bf16 v[84:87], v[92:95], v[56:59], v[84:87]
	v_add_u32_e32 v92, v163, v178
	v_add_u32_e32 v94, v163, v179
	ds_read_b64 v[92:93], v92
	ds_read_b64 v[94:95], v94
	s_waitcnt lgkmcnt(0)
	v_mfma_f32_16x16x32_bf16 v[80:83], v[92:95], v[56:59], v[80:83]
	v_add_u32_e32 v92, v166, v180
	v_add_u32_e32 v94, v166, v181
	ds_read_b64 v[92:93], v92
	ds_read_b64 v[94:95], v94
	s_waitcnt lgkmcnt(0)
	v_mfma_f32_16x16x32_bf16 v[88:91], v[92:95], v[56:59], v[88:91]
	v_add_u32_e32 v92, v169, v182
	v_add_u32_e32 v94, v169, v183
	ds_read_b64 v[92:93], v92
	ds_read_b64 v[94:95], v94
	s_waitcnt lgkmcnt(0)
	v_mfma_f32_16x16x32_bf16 v[92:95], v[92:95], v[56:59], v[76:79]
	s_nop 2
	v_add_u32_e32 v76, v172, v176
	v_add_u32_e32 v78, v172, v177
	ds_read_b64 v[76:77], v76
	ds_read_b64 v[78:79], v78
	s_waitcnt lgkmcnt(0)
	v_mfma_f32_16x16x32_bf16 v[72:75], v[76:79], v[56:59], v[72:75]
	v_add_u32_e32 v76, v173, v178
	v_add_u32_e32 v78, v173, v179
	ds_read_b64 v[76:77], v76
	ds_read_b64 v[78:79], v78
	s_waitcnt lgkmcnt(0)
	v_mfma_f32_16x16x32_bf16 v[68:71], v[76:79], v[56:59], v[68:71]
	v_add_u32_e32 v76, v174, v180
	v_add_u32_e32 v78, v174, v181
	ds_read_b64 v[76:77], v76
	ds_read_b64 v[78:79], v78
	s_waitcnt lgkmcnt(0)
	v_mfma_f32_16x16x32_bf16 v[64:67], v[76:79], v[56:59], v[64:67]
	v_add_u32_e32 v76, v175, v182
	v_add_u32_e32 v78, v175, v183
	ds_read_b64 v[76:77], v76
	ds_read_b64 v[78:79], v78
	s_waitcnt lgkmcnt(0)
	v_mfma_f32_16x16x32_bf16 v[56:59], v[76:79], v[56:59], v[60:63]
	v_add_u32_e32 v76, v163, v186
	v_add_u32_e32 v78, v163, v187
	ds_read_b64 v[76:77], v76
	ds_read_b64 v[78:79], v78
	s_waitcnt lgkmcnt(0)
	v_mfma_f32_16x16x32_bf16 v[76:79], v[76:79], v[52:55], v[80:83]
	s_nop 2
	v_add_u32_e32 v80, v166, v188
	v_add_u32_e32 v82, v166, v189
	ds_read_b64 v[80:81], v80
	ds_read_b64 v[82:83], v82
	s_waitcnt lgkmcnt(0)
	v_mfma_f32_16x16x32_bf16 v[80:83], v[80:83], v[52:55], v[88:91]
	s_nop 2
	v_add_u32_e32 v88, v172, v184
	v_add_u32_e32 v90, v172, v185
	ds_read_b64 v[88:89], v88
	ds_read_b64 v[90:91], v90
	s_waitcnt lgkmcnt(0)
	v_mfma_f32_16x16x32_bf16 v[72:75], v[88:91], v[52:55], v[72:75]
	v_add_u32_e32 v88, v173, v186
	v_add_u32_e32 v90, v173, v187
	v_add_u32_e32 v60, v160, v184
	v_add_u32_e32 v62, v160, v185
	ds_read_b64 v[88:89], v88
	ds_read_b64 v[90:91], v90
	ds_read_b64 v[60:61], v60
	ds_read_b64 v[62:63], v62
	s_waitcnt lgkmcnt(2)
	v_mfma_f32_16x16x32_bf16 v[88:91], v[88:91], v[52:55], v[68:71]
	s_nop 2
	v_add_u32_e32 v68, v174, v188
	v_add_u32_e32 v70, v174, v189
	ds_read_b64 v[68:69], v68
	ds_read_b64 v[70:71], v70
	s_waitcnt lgkmcnt(2)
; #define LAS __attribute__((address_space(3)))
; #define MFMA16(a, b, c) __builtin_amdgcn_mfma_f32_16x16x32_bf16((a), (b), (c), 0, 0, 0)
; __device__ __forceinline__ void ret_unit(LAS unsigned char* lds, int u, const bf16* PROJ, const int* pos, const float* dec_f, const float* dec_b, const bf16* ST,
;                                          const float* gn_w, const float* gn_b, bf16* MIX, int tid, const WsRef& wsr) {
;     ...
;     for (int kk = 0; kk < 4; ++kk)
; #pragma unroll
;         for (int n = 0; n < 8; ++n) { const int sw = (2 * n + (fr >> 3)) & 7, jc = kk * 4 + (fq >> 1); const LAS bf16* vr = VT + (n * 16 + fr) * LDT + 4 * (fq & 1);
;             const u32x2 lo = *(const LAS u32x2*)(vr + ((jc ^ sw) << 3)), hi = *(const LAS u32x2*)(vr + (((jc + 2) ^ sw) << 3)); u32x4 w; w.x = lo.x; w.y = lo.y; w.z = hi.x; w.w = hi.y;
;             o[n] = MFMA16(__builtin_bit_cast(bf16x8, w), pf[kk], o[n]); }
;     __syncthreads();
; #pragma unroll
;     for (int i = 0; i < 4; ++i) { const int id = tid + 512 * i, e = id >> 4, dch = id & 15;
;         *(LAS u32x4*)(Ks + e * LDT + dch * 8) = sf[i]; *(LAS u32x4*)(VT + e * LDT + dch * 8) = sb[i]; }
;     __syncthreads();
;     {
;         f32x4 tf[8], tb[8];
; #pragma unroll
;         for (int n = 0; n < 8; ++n) { tf[n] = (f32x4){0.f, 0.f, 0.f, 0.f}; tb[n] = (f32x4){0.f, 0.f, 0.f, 0.f}; }
; #pragma unroll
;         for (int kk = 0; kk < 4; ++kk)
; #pragma unroll
;             for (int n = 0; n < 8; ++n) { const bf16x8 yf = *(const LAS bf16x8*)(Ks + (n * 16 + fr) * LDT + kk * 32 + fq * 8); const bf16x8 yb = *(const LAS bf16x8*)(VT + (n * 16 + fr) * LDT + kk * 32 + fq * 8);
;                 tf[n] = MFMA16(yf, qf[kk], tf[n]); tb[n] = MFMA16(yb, qf[kk], tb[n]); }
	v_mfma_f32_16x16x32_bf16 v[60:63], v[60:63], v[52:55], v[84:87]
	s_nop 2
	v_add_u32_e32 v84, v169, v190
	v_add_u32_e32 v86, v169, v191
	ds_read_b64 v[84:85], v84
	ds_read_b64 v[86:87], v86
	s_waitcnt lgkmcnt(0)
	v_mfma_f32_16x16x32_bf16 v[84:87], v[84:87], v[52:55], v[92:95]
	v_mfma_f32_16x16x32_bf16 v[92:95], v[68:71], v[52:55], v[64:67]
	v_add_u32_e32 v68, v172, v192
	v_add_u32_e32 v70, v172, v193
	ds_read_b64 v[68:69], v68
	ds_read_b64 v[70:71], v70
	v_add_u32_e32 v64, v175, v190
	v_add_u32_e32 v66, v175, v191
	ds_read_b64 v[64:65], v64
	ds_read_b64 v[66:67], v66
	s_waitcnt lgkmcnt(0)
	v_mfma_f32_16x16x32_bf16 v[232:235], v[64:67], v[52:55], v[56:59]
	v_add_u32_e32 v52, v160, v192
	v_add_u32_e32 v54, v160, v193
	ds_read_b64 v[52:53], v52
	ds_read_b64 v[54:55], v54
	v_add_u32_e32 v56, v163, v194
	v_add_u32_e32 v58, v163, v195
	ds_read_b64 v[56:57], v56
	ds_read_b64 v[58:59], v58
	s_waitcnt lgkmcnt(2)
	v_mfma_f32_16x16x32_bf16 v[52:55], v[52:55], v[48:51], v[60:63]
	s_nop 2
	v_add_u32_e32 v60, v166, v196
	v_add_u32_e32 v62, v166, v197
	ds_read_b64 v[60:61], v60
	ds_read_b64 v[62:63], v62
	v_add_u32_e32 v64, v169, v198
	v_add_u32_e32 v66, v169, v199
	s_waitcnt lgkmcnt(2)
	v_mfma_f32_16x16x32_bf16 v[56:59], v[56:59], v[48:51], v[76:79]
	ds_read_b64 v[64:65], v64
	ds_read_b64 v[66:67], v66
	s_waitcnt lgkmcnt(2)
	v_mfma_f32_16x16x32_bf16 v[60:63], v[60:63], v[48:51], v[80:83]
	v_add_u32_e32 v76, v174, v196
	v_add_u32_e32 v78, v174, v197
	s_nop 0
	v_add_u32_e32 v80, v175, v198
	v_mfma_f32_16x16x32_bf16 v[68:71], v[68:71], v[48:51], v[72:75]
	v_add_u32_e32 v82, v175, v199
	ds_read_b64 v[76:77], v76
	ds_read_b64 v[78:79], v78
	v_add_u32_e32 v72, v173, v194
	v_add_u32_e32 v74, v173, v195
	ds_read_b64 v[72:73], v72
	ds_read_b64 v[74:75], v74
	ds_read_b64 v[80:81], v80
	ds_read_b64 v[82:83], v82
	s_waitcnt lgkmcnt(0)
	s_barrier
	ds_write_b128 v200, v[4:7] offset:34816
	ds_write_b128 v201, v[12:15]
	ds_write_b128 v202, v[8:11] offset:34816
	ds_write_b128 v203, v[16:19]
	ds_write_b128 v205, v[24:27] offset:34816
	ds_write_b128 v206, v[20:23]
	ds_write_b128 v207, v[32:35] offset:34816
	ds_write_b128 v208, v[36:39]
	s_waitcnt lgkmcnt(0)
	s_barrier
	ds_read_b128 v[4:7], v209 offset:34816
	ds_read_b128 v[8:11], v210
	s_waitcnt lgkmcnt(1)
	v_mfma_f32_16x16x32_bf16 v[12:15], v[4:7], v[44:47], 0
	s_waitcnt lgkmcnt(0)
	v_mfma_f32_16x16x32_bf16 v[16:19], v[8:11], v[44:47], 0
	ds_read_b128 v[4:7], v209 offset:39168
	ds_read_b128 v[8:11], v211
	s_waitcnt lgkmcnt(1)
	v_mfma_f32_16x16x32_bf16 v[32:35], v[4:7], v[44:47], 0
	s_waitcnt lgkmcnt(0)
	v_mfma_f32_16x16x32_bf16 v[36:39], v[8:11], v[44:47], 0
	ds_read_b128 v[4:7], v209 offset:43520
	ds_read_b128 v[8:11], v212
	v_mfma_f32_16x16x32_bf16 v[72:75], v[72:75], v[48:51], v[88:91]
	v_mfma_f32_16x16x32_bf16 v[76:79], v[76:79], v[48:51], v[92:95]
	s_waitcnt lgkmcnt(1)
	v_mfma_f32_16x16x32_bf16 v[88:91], v[4:7], v[44:47], 0
	s_waitcnt lgkmcnt(0)
	v_mfma_f32_16x16x32_bf16 v[92:95], v[8:11], v[44:47], 0
	ds_read_b128 v[4:7], v209 offset:47872
	ds_read_b128 v[8:11], v213
	v_mfma_f32_16x16x32_bf16 v[64:67], v[64:67], v[48:51], v[84:87]
	v_mfma_f32_16x16x32_bf16 v[48:51], v[80:83], v[48:51], v[232:235]
	s_waitcnt lgkmcnt(1)
	v_mfma_f32_16x16x32_bf16 v[232:235], v[4:7], v[44:47], 0
	s_waitcnt lgkmcnt(0)
	v_mfma_f32_16x16x32_bf16 v[236:239], v[8:11], v[44:47], 0
	ds_read_b128 v[4:7], v209 offset:52224
	ds_read_b128 v[8:11], v214
	s_waitcnt lgkmcnt(1)
	v_mfma_f32_16x16x32_bf16 v[240:243], v[4:7], v[44:47], 0
	s_waitcnt lgkmcnt(0)
	v_mfma_f32_16x16x32_bf16 v[244:247], v[8:11], v[44:47], 0
	ds_read_b128 v[4:7], v209 offset:56576
	ds_read_b128 v[8:11], v215
	s_waitcnt lgkmcnt(1)
	v_mfma_f32_16x16x32_bf16 v[80:83], v[4:7], v[44:47], 0
	s_waitcnt lgkmcnt(0)
	v_mfma_f32_16x16x32_bf16 v[84:87], v[8:11], v[44:47], 0
	ds_read_b128 v[4:7], v209 offset:60928
	ds_read_b128 v[8:11], v216
	s_waitcnt lgkmcnt(1)
	v_mfma_f32_16x16x32_bf16 v[20:23], v[4:7], v[44:47], 0
	ds_read_b128 v[4:7], v209 offset:65280
	ds_read_b128 v[248:251], v217
	s_waitcnt lgkmcnt(2)
	v_mfma_f32_16x16x32_bf16 v[24:27], v[8:11], v[44:47], 0
	s_waitcnt lgkmcnt(1)
	v_mfma_f32_16x16x32_bf16 v[8:11], v[4:7], v[44:47], 0
	s_waitcnt lgkmcnt(0)
	v_mfma_f32_16x16x32_bf16 v[4:7], v[248:251], v[44:47], 0
	ds_read_b128 v[44:47], v209 offset:34880
	ds_read_b128 v[248:251], v210 offset:64
	s_waitcnt lgkmcnt(1)
	v_mfma_f32_16x16x32_bf16 v[12:15], v[44:47], v[40:43], v[12:15]
	s_waitcnt lgkmcnt(0)
	v_mfma_f32_16x16x32_bf16 v[16:19], v[248:251], v[40:43], v[16:19]
	ds_read_b128 v[44:47], v209 offset:39232
	ds_read_b128 v[248:251], v211 offset:64
	s_waitcnt lgkmcnt(1)
	v_mfma_f32_16x16x32_bf16 v[32:35], v[44:47], v[40:43], v[32:35]
	s_waitcnt lgkmcnt(0)
	v_mfma_f32_16x16x32_bf16 v[36:39], v[248:251], v[40:43], v[36:39]
	ds_read_b128 v[44:47], v209 offset:43584
	ds_read_b128 v[248:251], v212 offset:64
	s_waitcnt lgkmcnt(1)
	v_mfma_f32_16x16x32_bf16 v[44:47], v[44:47], v[40:43], v[88:91]
	s_waitcnt lgkmcnt(0)
	v_mfma_f32_16x16x32_bf16 v[88:91], v[248:251], v[40:43], v[92:95]
	s_nop 2
	ds_read_b128 v[92:95], v209 offset:47936
	ds_read_b128 v[248:251], v213 offset:64
	s_waitcnt lgkmcnt(1)
	v_mfma_f32_16x16x32_bf16 v[92:95], v[92:95], v[40:43], v[232:235]
	s_waitcnt lgkmcnt(0)
	v_mfma_f32_16x16x32_bf16 v[232:235], v[248:251], v[40:43], v[236:239]
	s_nop 2
	ds_read_b128 v[236:239], v209 offset:52288
	ds_read_b128 v[248:251], v214 offset:64
	s_waitcnt lgkmcnt(1)
	v_mfma_f32_16x16x32_bf16 v[236:239], v[236:239], v[40:43], v[240:243]
	s_waitcnt lgkmcnt(0)
	v_mfma_f32_16x16x32_bf16 v[240:243], v[248:251], v[40:43], v[244:247]
	s_nop 2
	ds_read_b128 v[244:247], v209 offset:56640
	ds_read_b128 v[248:251], v215 offset:64
	s_waitcnt lgkmcnt(1)
; #define LAS __attribute__((address_space(3)))
; #define MFMA16(a, b, c) __builtin_amdgcn_mfma_f32_16x16x32_bf16((a), (b), (c), 0, 0, 0)
; __device__ __forceinline__ void ret_unit(LAS unsigned char* lds, int u, const bf16* PROJ, const int* pos, const float* dec_f, const float* dec_b, const bf16* ST,
;                                          const float* gn_w, const float* gn_b, bf16* MIX, int tid, const WsRef& wsr) {
;     ...
; #pragma unroll
;         for (int kk = 0; kk < 4; ++kk)
; #pragma unroll
;             for (int n = 0; n < 8; ++n) { const bf16x8 yf = *(const LAS bf16x8*)(Ks + (n * 16 + fr) * LDT + kk * 32 + fq * 8); const bf16x8 yb = *(const LAS bf16x8*)(VT + (n * 16 + fr) * LDT + kk * 32 + fq * 8);
;                 tf[n] = MFMA16(yf, qf[kk], tf[n]); tb[n] = MFMA16(yb, qf[kk], tb[n]); }
	v_mfma_f32_16x16x32_bf16 v[80:83], v[244:247], v[40:43], v[80:83]
	s_waitcnt lgkmcnt(0)
	v_mfma_f32_16x16x32_bf16 v[84:87], v[248:251], v[40:43], v[84:87]
	ds_read_b128 v[244:247], v209 offset:60992
	ds_read_b128 v[248:251], v216 offset:64
	s_waitcnt lgkmcnt(1)
	v_mfma_f32_16x16x32_bf16 v[244:247], v[244:247], v[40:43], v[20:23]
	s_waitcnt lgkmcnt(0)
	v_mfma_f32_16x16x32_bf16 v[248:251], v[248:251], v[40:43], v[24:27]
	s_nop 0
	ds_read_b128 v[20:23], v209 offset:65344
	s_nop 0
	ds_read_b128 v[24:27], v217 offset:64
	s_waitcnt lgkmcnt(1)
	v_mfma_f32_16x16x32_bf16 v[8:11], v[20:23], v[40:43], v[8:11]
	s_waitcnt lgkmcnt(0)
	v_mfma_f32_16x16x32_bf16 v[4:7], v[24:27], v[40:43], v[4:7]
	ds_read_b128 v[20:23], v209 offset:34944
	ds_read_b128 v[24:27], v210 offset:128
	s_waitcnt lgkmcnt(1)
	v_mfma_f32_16x16x32_bf16 v[40:43], v[20:23], v[28:31], v[12:15]
	s_waitcnt lgkmcnt(0)
	v_mfma_f32_16x16x32_bf16 v[130:133], v[24:27], v[28:31], v[16:19]
	s_nop 0
	ds_read_b128 v[12:15], v209 offset:39296
	s_nop 0
	ds_read_b128 v[16:19], v211 offset:128
	s_waitcnt lgkmcnt(1)
	v_mfma_f32_16x16x32_bf16 v[32:35], v[12:15], v[28:31], v[32:35]
	s_waitcnt lgkmcnt(0)
	v_mfma_f32_16x16x32_bf16 v[36:39], v[16:19], v[28:31], v[36:39]
	ds_read_b128 v[12:15], v209 offset:43648
	ds_read_b128 v[16:19], v212 offset:128
	s_waitcnt lgkmcnt(1)
	v_mfma_f32_16x16x32_bf16 v[44:47], v[12:15], v[28:31], v[44:47]
	s_waitcnt lgkmcnt(0)
	v_mfma_f32_16x16x32_bf16 v[88:91], v[16:19], v[28:31], v[88:91]
	ds_read_b128 v[12:15], v209 offset:48000
	ds_read_b128 v[16:19], v213 offset:128
	s_waitcnt lgkmcnt(1)
	v_mfma_f32_16x16x32_bf16 v[92:95], v[12:15], v[28:31], v[92:95]
	s_waitcnt lgkmcnt(0)
	v_mfma_f32_16x16x32_bf16 v[232:235], v[16:19], v[28:31], v[232:235]
	ds_read_b128 v[12:15], v209 offset:52352
	ds_read_b128 v[16:19], v214 offset:128
	s_waitcnt lgkmcnt(1)
	v_mfma_f32_16x16x32_bf16 v[236:239], v[12:15], v[28:31], v[236:239]
	s_waitcnt lgkmcnt(0)
	v_mfma_f32_16x16x32_bf16 v[240:243], v[16:19], v[28:31], v[240:243]
	ds_read_b128 v[12:15], v209 offset:56704
	ds_read_b128 v[16:19], v215 offset:128
	s_waitcnt lgkmcnt(1)
	v_mfma_f32_16x16x32_bf16 v[20:23], v[12:15], v[28:31], v[80:83]
	s_waitcnt lgkmcnt(0)
	v_mfma_f32_16x16x32_bf16 v[24:27], v[16:19], v[28:31], v[84:87]
	ds_read_b128 v[12:15], v209 offset:61056
	ds_read_b128 v[16:19], v216 offset:128
	ds_read_b128 v[80:83], v209 offset:65408
	ds_read_b128 v[84:87], v217 offset:128
	s_waitcnt lgkmcnt(3)
	v_mfma_f32_16x16x32_bf16 v[12:15], v[12:15], v[28:31], v[244:247]
	s_waitcnt lgkmcnt(2)
	v_mfma_f32_16x16x32_bf16 v[16:19], v[16:19], v[28:31], v[248:251]
	s_waitcnt lgkmcnt(1)
	v_mfma_f32_16x16x32_bf16 v[8:11], v[80:83], v[28:31], v[8:11]
	s_waitcnt lgkmcnt(0)
	v_mfma_f32_16x16x32_bf16 v[4:7], v[84:87], v[28:31], v[4:7]
	ds_read_b128 v[28:31], v209 offset:35008
	ds_read_b128 v[80:83], v210 offset:192
	s_waitcnt lgkmcnt(1)
	v_mfma_f32_16x16x32_bf16 v[28:31], v[28:31], v[0:3], v[40:43]
	s_waitcnt lgkmcnt(0)
	v_mfma_f32_16x16x32_bf16 v[40:43], v[80:83], v[0:3], v[130:133]
	ds_read_b128 v[80:83], v209 offset:39360
	ds_read_b128 v[84:87], v211 offset:192
	s_waitcnt lgkmcnt(1)
	v_mfma_f32_16x16x32_bf16 v[80:83], v[80:83], v[0:3], v[32:35]
	s_waitcnt lgkmcnt(0)
	v_mfma_f32_16x16x32_bf16 v[34:37], v[84:87], v[0:3], v[36:39]
	ds_read_b128 v[84:87], v209 offset:43712
	ds_read_b128 v[130:133], v212 offset:192
	s_waitcnt lgkmcnt(1)
	v_mfma_f32_16x16x32_bf16 v[44:47], v[84:87], v[0:3], v[44:47]
	s_waitcnt lgkmcnt(0)
	v_mfma_f32_16x16x32_bf16 v[84:87], v[130:133], v[0:3], v[88:91]
	s_nop 2
	ds_read_b128 v[88:91], v209 offset:48064
	ds_read_b128 v[130:133], v213 offset:192
	s_waitcnt lgkmcnt(1)
	v_mfma_f32_16x16x32_bf16 v[88:91], v[88:91], v[0:3], v[92:95]
	s_waitcnt lgkmcnt(0)
	v_mfma_f32_16x16x32_bf16 v[92:95], v[130:133], v[0:3], v[232:235]
	ds_read_b128 v[130:133], v209 offset:52416
	s_nop 1
	ds_read_b128 v[232:235], v214 offset:192
	s_waitcnt lgkmcnt(1)
	v_mfma_f32_16x16x32_bf16 v[130:133], v[130:133], v[0:3], v[236:239]
	s_waitcnt lgkmcnt(0)
	v_mfma_f32_16x16x32_bf16 v[232:235], v[232:235], v[0:3], v[240:243]
	s_nop 0
	ds_read_b128 v[236:239], v209 offset:56768
	s_nop 0
	ds_read_b128 v[240:243], v215 offset:192
	s_waitcnt lgkmcnt(1)
	v_mfma_f32_16x16x32_bf16 v[236:239], v[236:239], v[0:3], v[20:23]
	s_waitcnt lgkmcnt(0)
	v_mfma_f32_16x16x32_bf16 v[240:243], v[240:243], v[0:3], v[24:27]
	s_nop 0
	ds_read_b128 v[20:23], v209 offset:61120
	s_nop 0
	ds_read_b128 v[24:27], v216 offset:192
	s_waitcnt lgkmcnt(1)
	v_mfma_f32_16x16x32_bf16 v[12:15], v[20:23], v[0:3], v[12:15]
	s_waitcnt lgkmcnt(0)
	v_mfma_f32_16x16x32_bf16 v[244:247], v[24:27], v[0:3], v[16:19]
	s_nop 2
	ds_read_b128 v[16:19], v209 offset:65472
	ds_read_b128 v[20:23], v217 offset:192
	s_waitcnt lgkmcnt(1)
	v_mfma_f32_16x16x32_bf16 v[8:11], v[16:19], v[0:3], v[8:11]
	s_waitcnt lgkmcnt(0)
; __device__ __forceinline__ float fexp2(float x) { return __builtin_amdgcn_exp2f(x); }
; __device__ __forceinline__ void ret_unit(LAS unsigned char* lds, int u, const bf16* PROJ, const int* pos, const float* dec_f, const float* dec_b, const bf16* ST,
;                                          const float* gn_w, const float* gn_b, bf16* MIX, int tid, const WsRef& wsr) {
;     ...
;         const float xif = fexp2(lgf2 * (float)(q + 1)), xib = fexp2(lgb2 * (float)(128 - q));
; #pragma unroll
;         for (int n = 0; n < 8; ++n) o[n] = o[n] + tf[n] * xif + tb[n] * xib;
;     }
;     float sm = 0.f;
; #pragma unroll
;     for (int n = 0; n < 8; ++n) sm += (o[n][0] + o[n][1]) + (o[n][2] + o[n][3]);
;     sm += __shfl_xor(sm, 16); sm += __shfl_xor(sm, 32);
;     const float mu = sm * (1.f / 128.f);
;     float vq = 0.f;
; #pragma unroll
;     for (int n = 0; n < 8; ++n) { const f32x4 d = o[n] - mu; vq += (d[0] * d[0] + d[1] * d[1]) + (d[2] * d[2] + d[3] * d[3]); }
;     vq += __shfl_xor(vq, 16); vq += __shfl_xor(vq, 32);
	v_mfma_f32_16x16x32_bf16 v[248:251], v[20:23], v[0:3], v[4:7]
	v_mul_f32_e32 v0, v105, v218
	v_exp_f32_e32 v38, v0
	v_mul_f32_e32 v0, v230, v219
	v_exp_f32_e32 v230, v0
	v_pk_fma_f32 v[2:3], v[38:39], v[28:29], v[52:53] op_sel_hi:[0,1,1]
	v_pk_fma_f32 v[16:17], v[38:39], v[132:133], v[70:71] op_sel_hi:[0,1,1]
	v_pk_fma_f32 v[0:1], v[38:39], v[30:31], v[54:55] op_sel_hi:[0,1,1]
	v_pk_fma_f32 v[32:33], v[230:231], v[40:41], v[2:3] op_sel_hi:[0,1,1]
	v_pk_fma_f32 v[2:3], v[38:39], v[80:81], v[56:57] op_sel_hi:[0,1,1]
	v_pk_fma_f32 v[18:19], v[38:39], v[130:131], v[68:69] op_sel_hi:[0,1,1]
	v_pk_fma_f32 v[22:23], v[230:231], v[234:235], v[16:17] op_sel_hi:[0,1,1]
	v_pk_fma_f32 v[16:17], v[38:39], v[238:239], v[74:75] op_sel_hi:[0,1,1]
	v_pk_fma_f32 v[12:13], v[38:39], v[12:13], v[76:77] op_sel_hi:[0,1,1]
	v_pk_fma_f32 v[30:31], v[230:231], v[42:43], v[0:1] op_sel_hi:[0,1,1]
	v_pk_fma_f32 v[0:1], v[38:39], v[82:83], v[58:59] op_sel_hi:[0,1,1]
	v_pk_fma_f32 v[28:29], v[230:231], v[34:35], v[2:3] op_sel_hi:[0,1,1]
	v_pk_fma_f32 v[24:25], v[230:231], v[232:233], v[18:19] op_sel_hi:[0,1,1]
	v_pk_fma_f32 v[18:19], v[230:231], v[242:243], v[16:17] op_sel_hi:[0,1,1]
	v_pk_fma_f32 v[16:17], v[230:231], v[244:245], v[12:13] op_sel_hi:[0,1,1]
	v_pk_fma_f32 v[10:11], v[38:39], v[10:11], v[50:51] op_sel_hi:[0,1,1]
	v_pk_fma_f32 v[12:13], v[38:39], v[8:9], v[48:49] op_sel_hi:[0,1,1]
	v_pk_fma_f32 v[26:27], v[230:231], v[36:37], v[0:1] op_sel_hi:[0,1,1]
	v_pk_fma_f32 v[8:9], v[230:231], v[250:251], v[10:11] op_sel_hi:[0,1,1]
	v_pk_fma_f32 v[10:11], v[230:231], v[248:249], v[12:13] op_sel_hi:[0,1,1]
	v_mov_b32_e32 v12, v32
	v_mov_b32_e32 v13, v28
	v_mov_b32_e32 v34, v33
	v_mov_b32_e32 v35, v29
	v_pk_fma_f32 v[0:1], v[38:39], v[46:47], v[62:63] op_sel_hi:[0,1,1]
	v_pk_fma_f32 v[2:3], v[38:39], v[44:45], v[60:61] op_sel_hi:[0,1,1]
	v_pk_add_f32 v[12:13], v[12:13], v[34:35]
	v_mov_b32_e32 v34, v30
	v_mov_b32_e32 v35, v26
	v_mov_b32_e32 v36, v31
	v_mov_b32_e32 v37, v27
	v_pk_fma_f32 v[4:5], v[230:231], v[86:87], v[0:1] op_sel_hi:[0,1,1]
	v_pk_fma_f32 v[6:7], v[230:231], v[84:85], v[2:3] op_sel_hi:[0,1,1]
	v_pk_add_f32 v[34:35], v[34:35], v[36:37]
	v_mov_b32_e32 v36, v6
	v_pk_add_f32 v[12:13], v[12:13], v[34:35]
	v_pk_mov_b32 v[34:35], v[6:7], v[4:5] op_sel:[1,0]
	v_mov_b32_e32 v37, v5
	v_pk_fma_f32 v[0:1], v[38:39], v[90:91], v[66:67] op_sel_hi:[0,1,1]
	v_pk_fma_f32 v[2:3], v[38:39], v[88:89], v[64:65] op_sel_hi:[0,1,1]
	v_pk_add_f32 v[34:35], v[34:35], v[36:37]
	v_pk_fma_f32 v[0:1], v[230:231], v[94:95], v[0:1] op_sel_hi:[0,1,1]
	v_pk_fma_f32 v[2:3], v[230:231], v[92:93], v[2:3] op_sel_hi:[0,1,1]
	v_add_f32_e32 v12, 0, v12
	v_pk_add_f32 v[34:35], v[34:35], v[34:35] op_sel:[0,1] op_sel_hi:[1,0]
	v_pk_fma_f32 v[20:21], v[38:39], v[236:237], v[72:73] op_sel_hi:[0,1,1]
	v_pk_fma_f32 v[14:15], v[38:39], v[14:15], v[78:79] op_sel_hi:[0,1,1]
	v_add_f32_e32 v12, v12, v13
	v_add_f32_e32 v36, v2, v3
	v_add_f32_e32 v38, v0, v1
	v_mov_b32_e32 v13, v24
	v_mov_b32_e32 v35, v25
	v_mov_b32_e32 v37, v22
	v_mov_b32_e32 v39, v23
	v_pk_fma_f32 v[20:21], v[230:231], v[240:241], v[20:21] op_sel_hi:[0,1,1]
	v_pk_add_f32 v[12:13], v[12:13], v[34:35]
	v_pk_add_f32 v[34:35], v[36:37], v[38:39]
	v_mov_b32_e32 v36, v20
	v_pk_add_f32 v[12:13], v[12:13], v[34:35]
	v_pk_mov_b32 v[34:35], v[20:21], v[18:19] op_sel:[1,0]
	v_mov_b32_e32 v37, v19
	v_pk_add_f32 v[34:35], v[34:35], v[36:37]
	v_pk_fma_f32 v[14:15], v[230:231], v[246:247], v[14:15] op_sel_hi:[0,1,1]
	v_pk_add_f32 v[12:13], v[12:13], v[12:13] op_sel:[0,1] op_sel_hi:[1,0]
	v_pk_add_f32 v[34:35], v[34:35], v[34:35] op_sel:[0,1] op_sel_hi:[1,0]
	v_add_f32_e32 v36, v16, v17
	v_add_f32_e32 v38, v14, v15
	v_mov_b32_e32 v13, v10
	v_mov_b32_e32 v35, v11
	v_mov_b32_e32 v37, v8
	v_mov_b32_e32 v39, v9
	v_pk_add_f32 v[12:13], v[12:13], v[34:35]
	v_pk_add_f32 v[34:35], v[36:37], v[38:39]
	v_or_b32_e32 v48, s0, v126
	v_pk_add_f32 v[12:13], v[12:13], v[34:35]
	v_mov_b32_e32 v49, v97
	v_add_f32_e32 v12, v12, v13
	ds_bpermute_b32 v13, v220, v12
	s_waitcnt lgkmcnt(0)
	v_add_f32_e32 v12, v12, v13
	ds_bpermute_b32 v13, v221, v12
	s_waitcnt lgkmcnt(0)
	v_add_f32_e32 v40, v12, v13
	v_fmamk_f32 v33, v40, 0xbc000000, v33
	v_fmamk_f32 v29, v40, 0xbc000000, v29
	v_fmamk_f32 v31, v40, 0xbc000000, v31
	v_fmac_f32_e32 v32, 0xbc000000, v40
	v_fmamk_f32 v27, v40, 0xbc000000, v27
	v_fmac_f32_e32 v28, 0xbc000000, v40
	v_mov_b32_e32 v34, v33
	v_mov_b32_e32 v35, v29
	v_fmac_f32_e32 v30, 0xbc000000, v40
	v_fmac_f32_e32 v26, 0xbc000000, v40
	v_mov_b32_e32 v12, v32
	v_mov_b32_e32 v13, v28
	v_pk_mul_f32 v[34:35], v[34:35], v[34:35]
	v_mov_b32_e32 v36, v31
	v_mov_b32_e32 v37, v27
	v_pk_fma_f32 v[12:13], v[12:13], v[12:13], v[34:35]
	v_mov_b32_e32 v34, v30
	v_mov_b32_e32 v35, v26
	v_pk_mul_f32 v[36:37], v[36:37], v[36:37]
	v_fmamk_f32 v7, v40, 0xbc000000, v7
	v_pk_fma_f32 v[34:35], v[34:35], v[34:35], v[36:37]
	v_fmac_f32_e32 v6, 0xbc000000, v40
	v_pk_add_f32 v[12:13], v[12:13], v[34:35]
	v_fmamk_f32 v5, v40, 0xbc000000, v5
	v_fmac_f32_e32 v4, 0xbc000000, v40
	v_pk_add_f32 v[12:13], v[12:13], v[12:13] op_sel_hi:[0,1]
	v_pk_mul_f32 v[34:35], v[4:5], v[4:5]
	v_pk_mul_f32 v[36:37], v[6:7], v[6:7]
	v_fmac_f32_e32 v2, 0xbc000000, v40
	v_pk_mov_b32 v[38:39], v[36:37], v[34:35] op_sel:[1,0]
	v_mov_b32_e32 v37, v35
	v_fmamk_f32 v3, v40, 0xbc000000, v3
	v_fmac_f32_e32 v0, 0xbc000000, v40
	v_mul_f32_e32 v12, v2, v2
	v_pk_add_f32 v[34:35], v[38:39], v[36:37]
	v_fmamk_f32 v1, v40, 0xbc000000, v1
	v_pk_fma_f32 v[36:37], v[2:3], v[2:3], v[12:13] op_sel_hi:[1,1,0]
	v_mul_f32_e32 v12, v0, v0
	v_pk_add_f32 v[34:35], v[34:35], v[34:35] op_sel_hi:[0,1]
	v_pk_fma_f32 v[38:39], v[0:1], v[0:1], v[12:13] op_sel_hi:[1,1,0]
; __device__ __forceinline__ unsigned pk2(float lo, float hi) { return pg8::cvt_pk_bf16(lo, hi); }
; __device__ __forceinline__ float bflo(unsigned w) { return __uint_as_float(w << 16); }
; __device__ __forceinline__ float bfhi(unsigned w) { return __uint_as_float(w & 0xffff0000u); }
; __device__ __forceinline__ void ret_unit(LAS unsigned char* lds, int u, const bf16* PROJ, const int* pos, const float* dec_f, const float* dec_b, const bf16* ST,
;                                          const float* gn_w, const float* gn_b, bf16* MIX, int tid, const WsRef& wsr) {
;     ...
;     vq += __shfl_xor(vq, 16); vq += __shfl_xor(vq, 32);
;     const float rstd = rsqrtf(vq * (1.f / 128.f) + EPS);
;     const size_t row = row0 + q;
; #pragma unroll
;     for (int n = 0; n < 8; ++n) { const int col = h * 128 + n * 16 + 4 * fq;
;         const f32x4 gw = *(const f32x4*)(gn_w + col), gb = *(const f32x4*)(gn_b + col);
;         const u32x2 gg = *(const u32x2*)(PROJ + row * INC + 1536 + col);
;         const f32x4 g = (f32x4){bflo(gg.x), bfhi(gg.x), bflo(gg.y), bfhi(gg.y)};
;         f32x4 y = (o[n] - mu) * rstd * gw + gb;
; #pragma unroll
;         for (int r = 0; r < 4; ++r) y[r] = y[r] * g[r] * __builtin_amdgcn_rcpf(1.f + __expf(-g[r]));
;         u32x2 w; w.x = pk2(y[0], y[1]); w.y = pk2(y[2], y[3]); *(u32x2*)(MIX + row * D + col) = w; }
	v_fmamk_f32 v23, v40, 0xbc000000, v23
	v_fmac_f32_e32 v22, 0xbc000000, v40
	v_fmamk_f32 v25, v40, 0xbc000000, v25
	v_fmac_f32_e32 v24, 0xbc000000, v40
	v_mul_f32_e32 v36, v24, v24
	v_mul_f32_e32 v38, v25, v25
	v_mul_f32_e32 v34, v22, v22
	v_mul_f32_e32 v12, v23, v23
	v_pk_add_f32 v[36:37], v[36:37], v[38:39]
	v_pk_add_f32 v[12:13], v[34:35], v[12:13]
	v_fmamk_f32 v21, v40, 0xbc000000, v21
	v_pk_add_f32 v[12:13], v[36:37], v[12:13]
	v_fmac_f32_e32 v20, 0xbc000000, v40
	v_fmamk_f32 v19, v40, 0xbc000000, v19
	v_fmac_f32_e32 v18, 0xbc000000, v40
	v_pk_add_f32 v[12:13], v[12:13], v[12:13] op_sel_hi:[0,1]
	v_pk_mul_f32 v[34:35], v[18:19], v[18:19]
	v_pk_mul_f32 v[36:37], v[20:21], v[20:21]
	v_fmac_f32_e32 v16, 0xbc000000, v40
	v_pk_mov_b32 v[38:39], v[36:37], v[34:35] op_sel:[1,0]
	v_mov_b32_e32 v37, v35
	v_fmamk_f32 v17, v40, 0xbc000000, v17
	v_fmac_f32_e32 v14, 0xbc000000, v40
	v_mul_f32_e32 v12, v16, v16
	v_pk_add_f32 v[34:35], v[38:39], v[36:37]
	v_fmamk_f32 v15, v40, 0xbc000000, v15
	v_pk_fma_f32 v[36:37], v[16:17], v[16:17], v[12:13] op_sel_hi:[1,1,0]
	v_mul_f32_e32 v12, v14, v14
	v_pk_add_f32 v[34:35], v[34:35], v[34:35] op_sel_hi:[0,1]
	v_pk_fma_f32 v[38:39], v[14:15], v[14:15], v[12:13] op_sel_hi:[1,1,0]
	v_fmamk_f32 v9, v40, 0xbc000000, v9
	v_fmac_f32_e32 v8, 0xbc000000, v40
	v_fmamk_f32 v11, v40, 0xbc000000, v11
	v_fmac_f32_e32 v10, 0xbc000000, v40
	v_mul_f32_e32 v36, v10, v10
	v_mul_f32_e32 v38, v11, v11
	v_mul_f32_e32 v34, v8, v8
	v_mul_f32_e32 v12, v9, v9
	v_pk_add_f32 v[36:37], v[36:37], v[38:39]
	v_pk_add_f32 v[12:13], v[34:35], v[12:13]
	v_lshl_add_u64 v[34:35], s[4:5], 0, v[102:103]
	v_pk_add_f32 v[12:13], v[36:37], v[12:13]
	v_mov_b64_e32 v[36:37], s[6:7]
	v_add_f32_e32 v12, v12, v13
	ds_bpermute_b32 v13, v220, v12
	s_waitcnt lgkmcnt(0)
	v_add_f32_e32 v12, v12, v13
	ds_bpermute_b32 v13, v221, v12
	s_waitcnt lgkmcnt(0)
	v_add_f32_e32 v12, v12, v13
	v_fmamk_f32 v12, v12, 0x3c000000, v227
	v_cmp_gt_f32_e64 s[68:69], s1, v12
	v_mul_f32_e32 v13, 0x4b800000, v12
	v_mad_u64_u32 v[44:45], s[0:1], v34, s72, v[36:37]
	v_cndmask_b32_e64 v12, v12, v13, s[68:69]
	v_rsq_f32_e32 v12, v12
	v_mad_i32_i24 v45, v35, s72, v45
	v_lshlrev_b64 v[34:35], 11, v[34:35]
	v_lshl_add_u64 v[46:47], s[70:71], 0, v[34:35]
	v_mul_f32_e32 v13, 0x45800000, v12
	v_cndmask_b32_e64 v12, v12, v13, s[68:69]
	v_lshlrev_b32_e32 v13, 2, v48
	v_lshlrev_b32_e32 v48, 1, v48
	v_lshl_add_u64 v[34:35], v[44:45], 0, v[48:49]
	v_lshl_add_u64 v[46:47], v[46:47], 0, v[48:49]
	global_load_dwordx2 v[56:57], v[34:35], off offset:3072 nt
	global_load_dwordx2 v[58:59], v[34:35], off offset:3104 nt
	global_load_dwordx2 v[60:61], v[34:35], off offset:3136 nt
	global_load_dwordx2 v[62:63], v[34:35], off offset:3168 nt
	global_load_dwordx2 v[64:65], v[34:35], off offset:3200 nt
	global_load_dwordx2 v[66:67], v[34:35], off offset:3232 nt
	global_load_dwordx2 v[68:69], v[34:35], off offset:3264 nt
	global_load_dwordx2 v[70:71], v[34:35], off offset:3296 nt
	global_load_dwordx4 v[72:75], v13, s[22:23]
	global_load_dwordx4 v[76:79], v13, s[36:37]
	global_load_dwordx4 v[80:83], v13, s[22:23] offset:64
	global_load_dwordx4 v[84:87], v13, s[36:37] offset:64
	global_load_dwordx4 v[88:91], v13, s[22:23] offset:128
	global_load_dwordx4 v[92:95], v13, s[36:37] offset:128
	global_load_dwordx4 v[36:39], v13, s[22:23] offset:192
	global_load_dwordx4 v[40:43], v13, s[36:37] offset:192
	global_load_dwordx4 v[232:235], v13, s[22:23] offset:256
	global_load_dwordx4 v[236:239], v13, s[36:37] offset:256
	global_load_dwordx4 v[240:243], v13, s[22:23] offset:320
	global_load_dwordx4 v[248:251], v13, s[36:37] offset:320
	v_pk_mul_f32 v[32:33], v[32:33], v[12:13] op_sel_hi:[1,0]
	v_pk_mul_f32 v[30:31], v[30:31], v[12:13] op_sel_hi:[1,0]
	v_pk_mul_f32 v[28:29], v[28:29], v[12:13] op_sel_hi:[1,0]
	v_pk_mul_f32 v[26:27], v[26:27], v[12:13] op_sel_hi:[1,0]
	v_pk_mul_f32 v[6:7], v[6:7], v[12:13] op_sel_hi:[1,0]
	v_pk_mul_f32 v[4:5], v[4:5], v[12:13] op_sel_hi:[1,0]
	v_pk_mul_f32 v[2:3], v[2:3], v[12:13] op_sel_hi:[1,0]
	v_pk_mul_f32 v[0:1], v[0:1], v[12:13] op_sel_hi:[1,0]
	v_pk_mul_f32 v[24:25], v[24:25], v[12:13] op_sel_hi:[1,0]
	v_pk_mul_f32 v[22:23], v[22:23], v[12:13] op_sel_hi:[1,0]
	v_pk_mul_f32 v[20:21], v[20:21], v[12:13] op_sel_hi:[1,0]
	v_pk_mul_f32 v[18:19], v[18:19], v[12:13] op_sel_hi:[1,0]
	v_pk_mul_f32 v[16:17], v[16:17], v[12:13] op_sel_hi:[1,0]
	v_pk_mul_f32 v[14:15], v[14:15], v[12:13] op_sel_hi:[1,0]
	v_pk_mul_f32 v[10:11], v[10:11], v[12:13] op_sel_hi:[1,0]
	v_pk_mul_f32 v[8:9], v[8:9], v[12:13] op_sel_hi:[1,0]
	s_waitcnt vmcnt(10)
	v_lshlrev_b32_e32 v130, 16, v56
	v_and_b32_e32 v131, 0xffff0000, v56
	v_lshlrev_b32_e32 v132, 16, v57
	v_and_b32_e32 v133, 0xffff0000, v57
	v_pk_fma_f32 v[32:33], v[72:73], v[32:33], v[76:77]
	v_pk_fma_f32 v[30:31], v[74:75], v[30:31], v[78:79]
	global_load_dwordx4 v[72:75], v13, s[22:23] offset:384
	global_load_dwordx4 v[76:79], v13, s[36:37] offset:384
	v_mul_f32_e32 v56, 0xbfb8aa3b, v130
	v_mul_f32_e32 v57, 0xbfb8aa3b, v131
	v_exp_f32_e32 v56, v56
	v_exp_f32_e32 v57, v57
	v_pk_mul_f32 v[32:33], v[32:33], v[130:131]
	v_mul_f32_e32 v130, 0xbfb8aa3b, v132
	v_mul_f32_e32 v131, 0xbfb8aa3b, v133
	v_add_f32_e32 v56, 1.0, v56
	v_add_f32_e32 v57, 1.0, v57
	v_rcp_f32_e32 v56, v56
	v_rcp_f32_e32 v57, v57
	v_exp_f32_e32 v130, v130
	v_exp_f32_e32 v131, v131
	v_pk_mul_f32 v[30:31], v[30:31], v[132:133]
	v_pk_mul_f32 v[32:33], v[56:57], v[32:33]
	v_add_f32_e32 v130, 1.0, v130
	v_add_f32_e32 v131, 1.0, v131
	v_rcp_f32_e32 v130, v130
	v_rcp_f32_e32 v131, v131
	v_cvt_pk_bf16_f32 v56, v32, v33
	s_nop 0
	v_pk_mul_f32 v[30:31], v[130:131], v[30:31]
	s_nop 0
	v_cvt_pk_bf16_f32 v57, v30, v31
	global_store_dwordx2 v[46:47], v[56:57], off
	s_waitcnt vmcnt(11)
; __device__ __forceinline__ unsigned pk2(float lo, float hi) { return pg8::cvt_pk_bf16(lo, hi); }
; __device__ __forceinline__ float bflo(unsigned w) { return __uint_as_float(w << 16); }
; __device__ __forceinline__ float bfhi(unsigned w) { return __uint_as_float(w & 0xffff0000u); }
; __device__ __forceinline__ void ret_unit(LAS unsigned char* lds, int u, const bf16* PROJ, const int* pos, const float* dec_f, const float* dec_b, const bf16* ST,
;                                          const float* gn_w, const float* gn_b, bf16* MIX, int tid, const WsRef& wsr) {
;     ...
;     for (int n = 0; n < 8; ++n) { const int col = h * 128 + n * 16 + 4 * fq;
;         const f32x4 gw = *(const f32x4*)(gn_w + col), gb = *(const f32x4*)(gn_b + col);
;         const u32x2 gg = *(const u32x2*)(PROJ + row * INC + 1536 + col);
;         const f32x4 g = (f32x4){bflo(gg.x), bfhi(gg.x), bflo(gg.y), bfhi(gg.y)};
;         f32x4 y = (o[n] - mu) * rstd * gw + gb;
; #pragma unroll
;         for (int r = 0; r < 4; ++r) y[r] = y[r] * g[r] * __builtin_amdgcn_rcpf(1.f + __expf(-g[r]));
;         u32x2 w; w.x = pk2(y[0], y[1]); w.y = pk2(y[2], y[3]); *(u32x2*)(MIX + row * D + col) = w; }
	v_lshlrev_b32_e32 v130, 16, v58
	v_and_b32_e32 v131, 0xffff0000, v58
	v_lshlrev_b32_e32 v132, 16, v59
	v_and_b32_e32 v133, 0xffff0000, v59
	v_pk_fma_f32 v[28:29], v[80:81], v[28:29], v[84:85]
	v_pk_fma_f32 v[26:27], v[82:83], v[26:27], v[86:87]
	global_load_dwordx4 v[80:83], v13, s[22:23] offset:448
	global_load_dwordx4 v[84:87], v13, s[36:37] offset:448
	v_mul_f32_e32 v58, 0xbfb8aa3b, v130
	v_mul_f32_e32 v59, 0xbfb8aa3b, v131
	v_exp_f32_e32 v58, v58
	v_exp_f32_e32 v59, v59
	v_pk_mul_f32 v[28:29], v[28:29], v[130:131]
	v_mul_f32_e32 v130, 0xbfb8aa3b, v132
	v_mul_f32_e32 v131, 0xbfb8aa3b, v133
	v_add_f32_e32 v58, 1.0, v58
	v_add_f32_e32 v59, 1.0, v59
	v_rcp_f32_e32 v58, v58
	v_rcp_f32_e32 v59, v59
	v_exp_f32_e32 v130, v130
	v_exp_f32_e32 v131, v131
	v_pk_mul_f32 v[26:27], v[26:27], v[132:133]
	v_pk_mul_f32 v[28:29], v[58:59], v[28:29]
	v_add_f32_e32 v130, 1.0, v130
	v_add_f32_e32 v131, 1.0, v131
	v_rcp_f32_e32 v130, v130
	v_rcp_f32_e32 v131, v131
	v_cvt_pk_bf16_f32 v58, v28, v29
	s_nop 0
	v_pk_mul_f32 v[26:27], v[130:131], v[26:27]
	s_nop 0
	v_cvt_pk_bf16_f32 v59, v26, v27
	global_store_dwordx2 v[46:47], v[58:59], off offset:32
	s_waitcnt vmcnt(12)
	v_lshlrev_b32_e32 v130, 16, v60
	v_and_b32_e32 v131, 0xffff0000, v60
	v_lshlrev_b32_e32 v132, 16, v61
	v_and_b32_e32 v133, 0xffff0000, v61
	v_pk_fma_f32 v[6:7], v[88:89], v[6:7], v[92:93]
	v_pk_fma_f32 v[4:5], v[90:91], v[4:5], v[94:95]
	v_mul_f32_e32 v60, 0xbfb8aa3b, v130
	v_mul_f32_e32 v61, 0xbfb8aa3b, v131
	v_exp_f32_e32 v60, v60
	v_exp_f32_e32 v61, v61
	v_pk_mul_f32 v[6:7], v[6:7], v[130:131]
	v_mul_f32_e32 v130, 0xbfb8aa3b, v132
	v_mul_f32_e32 v131, 0xbfb8aa3b, v133
	v_add_f32_e32 v60, 1.0, v60
	v_add_f32_e32 v61, 1.0, v61
	v_rcp_f32_e32 v60, v60
	v_rcp_f32_e32 v61, v61
	v_exp_f32_e32 v130, v130
	v_exp_f32_e32 v131, v131
	v_pk_mul_f32 v[4:5], v[4:5], v[132:133]
	v_pk_mul_f32 v[6:7], v[60:61], v[6:7]
	v_add_f32_e32 v130, 1.0, v130
	v_add_f32_e32 v131, 1.0, v131
	v_rcp_f32_e32 v130, v130
	v_rcp_f32_e32 v131, v131
	v_cvt_pk_bf16_f32 v60, v6, v7
	s_nop 0
	v_pk_mul_f32 v[4:5], v[130:131], v[4:5]
	s_nop 0
	v_cvt_pk_bf16_f32 v61, v4, v5
	global_store_dwordx2 v[46:47], v[60:61], off offset:64
	s_waitcnt vmcnt(11)
	v_lshlrev_b32_e32 v130, 16, v62
	v_and_b32_e32 v131, 0xffff0000, v62
	v_lshlrev_b32_e32 v132, 16, v63
	v_and_b32_e32 v133, 0xffff0000, v63
	v_pk_fma_f32 v[2:3], v[36:37], v[2:3], v[40:41]
	v_pk_fma_f32 v[0:1], v[38:39], v[0:1], v[42:43]
	v_mul_f32_e32 v62, 0xbfb8aa3b, v130
	v_mul_f32_e32 v63, 0xbfb8aa3b, v131
	v_exp_f32_e32 v62, v62
	v_exp_f32_e32 v63, v63
	v_pk_mul_f32 v[2:3], v[2:3], v[130:131]
	v_mul_f32_e32 v130, 0xbfb8aa3b, v132
	v_mul_f32_e32 v131, 0xbfb8aa3b, v133
	v_add_f32_e32 v62, 1.0, v62
	v_add_f32_e32 v63, 1.0, v63
	v_rcp_f32_e32 v62, v62
	v_rcp_f32_e32 v63, v63
	v_exp_f32_e32 v130, v130
	v_exp_f32_e32 v131, v131
	v_pk_mul_f32 v[0:1], v[0:1], v[132:133]
	v_pk_mul_f32 v[2:3], v[62:63], v[2:3]
	v_add_f32_e32 v130, 1.0, v130
	v_add_f32_e32 v131, 1.0, v131
	v_rcp_f32_e32 v130, v130
	v_rcp_f32_e32 v131, v131
	v_cvt_pk_bf16_f32 v62, v2, v3
	s_nop 0
	v_pk_mul_f32 v[0:1], v[130:131], v[0:1]
	s_nop 0
	v_cvt_pk_bf16_f32 v63, v0, v1
	global_store_dwordx2 v[46:47], v[62:63], off offset:96
	s_waitcnt vmcnt(10)
	v_lshlrev_b32_e32 v130, 16, v64
	v_and_b32_e32 v131, 0xffff0000, v64
	v_lshlrev_b32_e32 v132, 16, v65
	v_and_b32_e32 v133, 0xffff0000, v65
	v_pk_fma_f32 v[24:25], v[232:233], v[24:25], v[236:237]
	v_pk_fma_f32 v[22:23], v[234:235], v[22:23], v[238:239]
	v_mul_f32_e32 v64, 0xbfb8aa3b, v130
	v_mul_f32_e32 v65, 0xbfb8aa3b, v131
	v_exp_f32_e32 v64, v64
	v_exp_f32_e32 v65, v65
	v_pk_mul_f32 v[24:25], v[24:25], v[130:131]
	v_mul_f32_e32 v130, 0xbfb8aa3b, v132
	v_mul_f32_e32 v131, 0xbfb8aa3b, v133
	v_add_f32_e32 v64, 1.0, v64
	v_add_f32_e32 v65, 1.0, v65
	v_rcp_f32_e32 v64, v64
	v_rcp_f32_e32 v65, v65
	v_exp_f32_e32 v130, v130
	v_exp_f32_e32 v131, v131
	v_pk_mul_f32 v[22:23], v[22:23], v[132:133]
	v_pk_mul_f32 v[24:25], v[64:65], v[24:25]
	v_add_f32_e32 v130, 1.0, v130
	v_add_f32_e32 v131, 1.0, v131
	v_rcp_f32_e32 v130, v130
	v_rcp_f32_e32 v131, v131
	v_cvt_pk_bf16_f32 v64, v24, v25
	s_nop 0
	v_pk_mul_f32 v[22:23], v[130:131], v[22:23]
	s_nop 0
	v_cvt_pk_bf16_f32 v65, v22, v23
	global_store_dwordx2 v[46:47], v[64:65], off offset:128
	s_waitcnt vmcnt(9)
; __device__ __forceinline__ unsigned pk2(float lo, float hi) { return pg8::cvt_pk_bf16(lo, hi); }
; __device__ __forceinline__ float bflo(unsigned w) { return __uint_as_float(w << 16); }
; __device__ __forceinline__ float bfhi(unsigned w) { return __uint_as_float(w & 0xffff0000u); }
; __device__ __forceinline__ void ret_unit(LAS unsigned char* lds, int u, const bf16* PROJ, const int* pos, const float* dec_f, const float* dec_b, const bf16* ST,
;                                          const float* gn_w, const float* gn_b, bf16* MIX, int tid, const WsRef& wsr) {
;     ...
;     for (int n = 0; n < 8; ++n) { const int col = h * 128 + n * 16 + 4 * fq;
;         const f32x4 gw = *(const f32x4*)(gn_w + col), gb = *(const f32x4*)(gn_b + col);
;         const u32x2 gg = *(const u32x2*)(PROJ + row * INC + 1536 + col);
;         const f32x4 g = (f32x4){bflo(gg.x), bfhi(gg.x), bflo(gg.y), bfhi(gg.y)};
;         f32x4 y = (o[n] - mu) * rstd * gw + gb;
; #pragma unroll
;         for (int r = 0; r < 4; ++r) y[r] = y[r] * g[r] * __builtin_amdgcn_rcpf(1.f + __expf(-g[r]));
;         u32x2 w; w.x = pk2(y[0], y[1]); w.y = pk2(y[2], y[3]); *(u32x2*)(MIX + row * D + col) = w; }
;     __syncthreads();
	v_lshlrev_b32_e32 v130, 16, v66
	v_and_b32_e32 v131, 0xffff0000, v66
	v_lshlrev_b32_e32 v132, 16, v67
	v_and_b32_e32 v133, 0xffff0000, v67
	v_pk_fma_f32 v[20:21], v[240:241], v[20:21], v[248:249]
	v_pk_fma_f32 v[18:19], v[242:243], v[18:19], v[250:251]
	v_mul_f32_e32 v66, 0xbfb8aa3b, v130
	v_mul_f32_e32 v67, 0xbfb8aa3b, v131
	v_exp_f32_e32 v66, v66
	v_exp_f32_e32 v67, v67
	v_pk_mul_f32 v[20:21], v[20:21], v[130:131]
	v_mul_f32_e32 v130, 0xbfb8aa3b, v132
	v_mul_f32_e32 v131, 0xbfb8aa3b, v133
	v_add_f32_e32 v66, 1.0, v66
	v_add_f32_e32 v67, 1.0, v67
	v_rcp_f32_e32 v66, v66
	v_rcp_f32_e32 v67, v67
	v_exp_f32_e32 v130, v130
	v_exp_f32_e32 v131, v131
	v_pk_mul_f32 v[18:19], v[18:19], v[132:133]
	v_pk_mul_f32 v[20:21], v[66:67], v[20:21]
	v_add_f32_e32 v130, 1.0, v130
	v_add_f32_e32 v131, 1.0, v131
	v_rcp_f32_e32 v130, v130
	v_rcp_f32_e32 v131, v131
	v_cvt_pk_bf16_f32 v66, v20, v21
	s_nop 0
	v_pk_mul_f32 v[18:19], v[130:131], v[18:19]
	s_nop 0
	v_cvt_pk_bf16_f32 v67, v18, v19
	global_store_dwordx2 v[46:47], v[66:67], off offset:160
	s_waitcnt vmcnt(8)
	v_lshlrev_b32_e32 v130, 16, v68
	v_and_b32_e32 v131, 0xffff0000, v68
	v_lshlrev_b32_e32 v132, 16, v69
	v_and_b32_e32 v133, 0xffff0000, v69
	v_pk_fma_f32 v[16:17], v[72:73], v[16:17], v[76:77]
	v_pk_fma_f32 v[14:15], v[74:75], v[14:15], v[78:79]
	v_mul_f32_e32 v68, 0xbfb8aa3b, v130
	v_mul_f32_e32 v69, 0xbfb8aa3b, v131
	v_exp_f32_e32 v68, v68
	v_exp_f32_e32 v69, v69
	v_pk_mul_f32 v[16:17], v[16:17], v[130:131]
	v_mul_f32_e32 v130, 0xbfb8aa3b, v132
	v_mul_f32_e32 v131, 0xbfb8aa3b, v133
	v_add_f32_e32 v68, 1.0, v68
	v_add_f32_e32 v69, 1.0, v69
	v_rcp_f32_e32 v68, v68
	v_rcp_f32_e32 v69, v69
	v_exp_f32_e32 v130, v130
	v_exp_f32_e32 v131, v131
	v_pk_mul_f32 v[14:15], v[14:15], v[132:133]
	v_pk_mul_f32 v[16:17], v[68:69], v[16:17]
	v_add_f32_e32 v130, 1.0, v130
	v_add_f32_e32 v131, 1.0, v131
	v_rcp_f32_e32 v130, v130
	v_rcp_f32_e32 v131, v131
	v_cvt_pk_bf16_f32 v68, v16, v17
	s_nop 0
	v_pk_mul_f32 v[14:15], v[130:131], v[14:15]
	s_nop 0
	v_cvt_pk_bf16_f32 v69, v14, v15
	global_store_dwordx2 v[46:47], v[68:69], off offset:192
	s_waitcnt vmcnt(6)
	v_lshlrev_b32_e32 v130, 16, v70
	v_and_b32_e32 v131, 0xffff0000, v70
	v_lshlrev_b32_e32 v132, 16, v71
	v_and_b32_e32 v133, 0xffff0000, v71
	v_pk_fma_f32 v[10:11], v[80:81], v[10:11], v[84:85]
	v_pk_fma_f32 v[8:9], v[82:83], v[8:9], v[86:87]
	v_mul_f32_e32 v70, 0xbfb8aa3b, v130
	v_mul_f32_e32 v71, 0xbfb8aa3b, v131
	v_exp_f32_e32 v70, v70
	v_exp_f32_e32 v71, v71
	v_pk_mul_f32 v[10:11], v[10:11], v[130:131]
	v_mul_f32_e32 v130, 0xbfb8aa3b, v132
	v_mul_f32_e32 v131, 0xbfb8aa3b, v133
	v_add_f32_e32 v70, 1.0, v70
	v_add_f32_e32 v71, 1.0, v71
	v_rcp_f32_e32 v70, v70
	v_rcp_f32_e32 v71, v71
	v_exp_f32_e32 v130, v130
	v_exp_f32_e32 v131, v131
	v_pk_mul_f32 v[8:9], v[8:9], v[132:133]
	v_pk_mul_f32 v[10:11], v[70:71], v[10:11]
	v_add_f32_e32 v130, 1.0, v130
	v_add_f32_e32 v131, 1.0, v131
	v_rcp_f32_e32 v130, v130
	v_rcp_f32_e32 v131, v131
	v_cvt_pk_bf16_f32 v70, v10, v11
	s_nop 0
	v_pk_mul_f32 v[8:9], v[130:131], v[8:9]
	s_nop 0
	v_cvt_pk_bf16_f32 v71, v8, v9
	global_store_dwordx2 v[46:47], v[70:71], off offset:224
	s_barrier
	s_cbranch_scc1 .LBB0_438
	v_readlane_b32 s82, v255, 40
	v_readlane_b32 s4, v255, 38
	v_readlane_b32 s80, v255, 42
	v_readlane_b32 s83, v255, 41
	v_readlane_b32 s5, v255, 39
	v_readlane_b32 s2, v255, 58
	v_readlane_b32 s81, v255, 43
